# GEMM epilogues: first-batch loads (row statistics / residual) issued before the leading half's align barrier
# speedup vs baseline: 1.0500x; 1.0033x over previous
.LBB0_111:
	s_add_u32 s2, s92, s24
	s_addc_u32 s20, s93, 0
	s_add_u32 s21, s2, 0x100
	s_addc_u32 s25, s20, 0
	s_and_b64 s[14:15], s[96:97], exec
	s_cselect_b32 s43, s16, s25
	s_cselect_b32 s42, s83, s21
	s_add_u32 s14, s90, s24
	s_addc_u32 s15, s91, 0
	s_add_u32 s21, s14, 0x100
	s_addc_u32 s24, s15, 0
	s_add_i32 s66, 0, 0x10000
	s_and_b64 s[14:15], s[96:97], exec
	s_cselect_b32 s39, s81, s24
	s_cselect_b32 s38, s8, s21
	s_add_i32 s67, 0, 0x14000
	s_add_u32 s26, s2, 0x10080
	s_addc_u32 s27, s20, 0
	s_add_i32 s35, s66, s61
	s_add_i32 m0, s76, 0xc000
	s_add_i32 s62, s76, 0xe000
	s_add_i32 s14, s35, 0x2000
	s_add_u32 s24, s38, 0x10000
	v_add_u32_e32 v126, s66, v242
	v_add_u32_e32 v158, s67, v242
	s_addc_u32 s25, s39, 0
	s_add_i32 s15, s67, s61
	ds_read_b128 v[114:117], v126
	ds_read_b128 v[118:121], v126 offset:1024
	ds_read_b128 v[122:125], v126 offset:2048
	ds_read_b128 v[126:129], v126 offset:3072
	ds_read_b128 v[138:141], v158
	ds_read_b128 v[142:145], v158 offset:1024
	ds_read_b128 v[146:149], v158 offset:2048
	ds_read_b128 v[158:161], v158 offset:3072
	s_add_i32 s2, s15, 0x2000
	s_add_i32 s30, 0, 0x18000
	s_add_i32 s21, 0, 0x1c000
	s_add_u32 vcc_lo, s42, 0x10000
	s_addc_u32 vcc_hi, s43, 0
	s_add_i32 s20, s30, s61
	s_add_i32 s58, s20, 0x2000
	s_add_u32 s96, s38, 0x10080
	s_addc_u32 s97, s39, 0
	s_add_i32 s67, s21, s61
	s_add_i32 s66, s67, 0x2000
	v_lshl_add_u64 v[194:195], s[26:27], 0, v[200:201]
	ds_read_b128 v[162:165], v244
	ds_read_b128 v[166:169], v244 offset:1024
	ds_read_b128 v[170:173], v244 offset:2048
	ds_read_b128 v[174:177], v244 offset:3072
	ds_read_b128 v[178:181], v244 offset:4096
	ds_read_b128 v[182:185], v244 offset:5120
	ds_read_b128 v[186:189], v244 offset:6144
	ds_read_b128 v[190:193], v244 offset:7168
	global_load_lds_dwordx4 v[194:195], off
	v_lshl_add_u64 v[194:195], s[26:27], 0, v[202:203]
	s_mov_b32 m0, s62
	s_nop 0
	global_load_lds_dwordx4 v[194:195], off
	s_waitcnt vmcnt(8)
	s_waitcnt lgkmcnt(0)
	s_barrier
	s_setprio 1
	s_waitcnt lgkmcnt(0)
	v_mfma_f32_16x16x32_bf16 v[154:157], v[114:117], v[162:165], v[154:157]
	v_mfma_f32_16x16x32_bf16 v[150:153], v[122:125], v[162:165], v[150:153]
	v_mfma_f32_16x16x32_bf16 v[110:113], v[114:117], v[170:173], v[110:113]
	v_mfma_f32_16x16x32_bf16 v[106:109], v[122:125], v[170:173], v[106:109]
	v_mfma_f32_16x16x32_bf16 v[92:95], v[114:117], v[178:181], v[92:95]
	v_mfma_f32_16x16x32_bf16 v[88:91], v[122:125], v[178:181], v[88:91]
	v_mfma_f32_16x16x32_bf16 v[76:79], v[114:117], v[186:189], v[76:79]
	v_mfma_f32_16x16x32_bf16 v[72:75], v[122:125], v[186:189], v[72:75]
	v_mfma_f32_16x16x32_bf16 v[154:157], v[118:121], v[166:169], v[154:157]
	v_mfma_f32_16x16x32_bf16 v[150:153], v[126:129], v[166:169], v[150:153]
	v_mfma_f32_16x16x32_bf16 v[110:113], v[118:121], v[174:177], v[110:113]
	v_mfma_f32_16x16x32_bf16 v[106:109], v[126:129], v[174:177], v[106:109]
	v_mfma_f32_16x16x32_bf16 v[92:95], v[118:121], v[182:185], v[92:95]
	v_mfma_f32_16x16x32_bf16 v[88:91], v[126:129], v[182:185], v[88:91]
	v_mfma_f32_16x16x32_bf16 v[76:79], v[118:121], v[190:193], v[76:79]
	v_mfma_f32_16x16x32_bf16 v[72:75], v[126:129], v[190:193], v[72:75]
	s_setprio 0
	s_setprio 1
	v_mfma_f32_16x16x32_bf16 v[134:137], v[138:141], v[162:165], v[134:137]
	v_mfma_f32_16x16x32_bf16 v[130:133], v[146:149], v[162:165], v[130:133]
	v_mfma_f32_16x16x32_bf16 v[102:105], v[138:141], v[170:173], v[102:105]
	v_mfma_f32_16x16x32_bf16 v[98:101], v[146:149], v[170:173], v[98:101]
	v_mfma_f32_16x16x32_bf16 v[84:87], v[138:141], v[178:181], v[84:87]
	v_mfma_f32_16x16x32_bf16 v[80:83], v[146:149], v[178:181], v[80:83]
	v_mfma_f32_16x16x32_bf16 v[68:71], v[138:141], v[186:189], v[68:71]
	v_mfma_f32_16x16x32_bf16 v[64:67], v[146:149], v[186:189], v[64:67]
	v_mfma_f32_16x16x32_bf16 v[134:137], v[142:145], v[166:169], v[134:137]
	v_mfma_f32_16x16x32_bf16 v[130:133], v[158:161], v[166:169], v[130:133]
	v_mfma_f32_16x16x32_bf16 v[102:105], v[142:145], v[174:177], v[102:105]
	v_mfma_f32_16x16x32_bf16 v[98:101], v[158:161], v[174:177], v[98:101]
	v_mfma_f32_16x16x32_bf16 v[84:87], v[142:145], v[182:185], v[84:87]
	v_mfma_f32_16x16x32_bf16 v[80:83], v[158:161], v[182:185], v[80:83]
	v_mfma_f32_16x16x32_bf16 v[68:71], v[142:145], v[190:193], v[68:71]
	v_mfma_f32_16x16x32_bf16 v[64:67], v[158:161], v[190:193], v[64:67]
	s_setprio 0
	s_barrier
	s_mov_b32 m0, s35
	v_lshl_add_u64 v[194:195], s[38:39], 0, v[96:97]
	ds_read_b128 v[162:165], v244 offset:16384
	ds_read_b128 v[166:169], v244 offset:17408
	ds_read_b128 v[170:173], v244 offset:18432
	ds_read_b128 v[174:177], v244 offset:19456
	ds_read_b128 v[178:181], v244 offset:20480
	ds_read_b128 v[182:185], v244 offset:21504
	ds_read_b128 v[186:189], v244 offset:22528
	ds_read_b128 v[190:193], v244 offset:23552
	global_load_lds_dwordx4 v[194:195], off
	v_lshl_add_u64 v[196:197], s[38:39], 0, v[204:205]
	s_mov_b32 m0, s14
	v_lshl_add_u64 v[206:207], s[24:25], 0, v[96:97]
	global_load_lds_dwordx4 v[196:197], off
	s_mov_b32 m0, s15
	v_lshl_add_u64 v[208:209], s[42:43], 0, v[202:203]
	global_load_lds_dwordx4 v[206:207], off
	v_lshl_add_u64 v[206:207], s[24:25], 0, v[204:205]
	s_mov_b32 m0, s2
	s_nop 0
	global_load_lds_dwordx4 v[206:207], off
	v_lshl_add_u64 v[206:207], s[42:43], 0, v[200:201]
	s_mov_b32 m0, s76
	s_nop 0
	global_load_lds_dwordx4 v[206:207], off
	s_mov_b32 m0, s63
	s_nop 0
	global_load_lds_dwordx4 v[208:209], off
	s_waitcnt vmcnt(8)
	s_waitcnt lgkmcnt(0)
	s_barrier
	s_setprio 1
	s_waitcnt lgkmcnt(0)
	v_mfma_f32_16x16x32_bf16 v[60:63], v[114:117], v[162:165], v[60:63]
	v_mfma_f32_16x16x32_bf16 v[56:59], v[122:125], v[162:165], v[56:59]
	v_mfma_f32_16x16x32_bf16 v[44:47], v[114:117], v[170:173], v[44:47]
	v_mfma_f32_16x16x32_bf16 v[40:43], v[122:125], v[170:173], v[40:43]
	v_mfma_f32_16x16x32_bf16 v[28:31], v[114:117], v[178:181], v[28:31]
	v_mfma_f32_16x16x32_bf16 v[24:27], v[122:125], v[178:181], v[24:27]
	v_mfma_f32_16x16x32_bf16 v[12:15], v[114:117], v[186:189], v[12:15]
	v_mfma_f32_16x16x32_bf16 v[8:11], v[122:125], v[186:189], v[8:11]
	v_mfma_f32_16x16x32_bf16 v[60:63], v[118:121], v[166:169], v[60:63]
	v_mfma_f32_16x16x32_bf16 v[56:59], v[126:129], v[166:169], v[56:59]
	v_mfma_f32_16x16x32_bf16 v[44:47], v[118:121], v[174:177], v[44:47]
	v_mfma_f32_16x16x32_bf16 v[40:43], v[126:129], v[174:177], v[40:43]
	v_mfma_f32_16x16x32_bf16 v[28:31], v[118:121], v[182:185], v[28:31]
	v_mfma_f32_16x16x32_bf16 v[24:27], v[126:129], v[182:185], v[24:27]
	v_mfma_f32_16x16x32_bf16 v[12:15], v[118:121], v[190:193], v[12:15]
	v_mfma_f32_16x16x32_bf16 v[8:11], v[126:129], v[190:193], v[8:11]
	s_setprio 0
	s_setprio 1
	v_mfma_f32_16x16x32_bf16 v[52:55], v[138:141], v[162:165], v[52:55]
	v_mfma_f32_16x16x32_bf16 v[48:51], v[146:149], v[162:165], v[48:51]
	v_mfma_f32_16x16x32_bf16 v[36:39], v[138:141], v[170:173], v[36:39]
	v_mfma_f32_16x16x32_bf16 v[32:35], v[146:149], v[170:173], v[32:35]
	v_mfma_f32_16x16x32_bf16 v[20:23], v[138:141], v[178:181], v[20:23]
	v_mfma_f32_16x16x32_bf16 v[16:19], v[146:149], v[178:181], v[16:19]
	v_mfma_f32_16x16x32_bf16 v[4:7], v[138:141], v[186:189], v[4:7]
	v_mfma_f32_16x16x32_bf16 v[0:3], v[146:149], v[186:189], v[0:3]
	v_mfma_f32_16x16x32_bf16 v[52:55], v[142:145], v[166:169], v[52:55]
	v_mfma_f32_16x16x32_bf16 v[48:51], v[158:161], v[166:169], v[48:51]
	v_mfma_f32_16x16x32_bf16 v[36:39], v[142:145], v[174:177], v[36:39]
	v_mfma_f32_16x16x32_bf16 v[32:35], v[158:161], v[174:177], v[32:35]
	v_mfma_f32_16x16x32_bf16 v[20:23], v[142:145], v[182:185], v[20:23]
	v_mfma_f32_16x16x32_bf16 v[16:19], v[158:161], v[182:185], v[16:19]
	v_mfma_f32_16x16x32_bf16 v[4:7], v[142:145], v[190:193], v[4:7]
	v_mfma_f32_16x16x32_bf16 v[0:3], v[158:161], v[190:193], v[0:3]
	s_setprio 0
	s_barrier
	v_add_u32_e32 v126, s30, v242
	v_add_u32_e32 v158, s21, v242
	ds_read_b128 v[114:117], v126
	ds_read_b128 v[118:121], v126 offset:1024
	ds_read_b128 v[122:125], v126 offset:2048
	ds_read_b128 v[126:129], v126 offset:3072
	ds_read_b128 v[138:141], v158
	ds_read_b128 v[142:145], v158 offset:1024
	ds_read_b128 v[146:149], v158 offset:2048
	ds_read_b128 v[158:161], v158 offset:3072
	s_mov_b32 m0, s75
	v_lshl_add_u64 v[210:211], vcc, 0, v[200:201]
	ds_read_b128 v[162:165], v244 offset:32768
	ds_read_b128 v[166:169], v244 offset:33792
	ds_read_b128 v[170:173], v244 offset:34816
	ds_read_b128 v[174:177], v244 offset:35840
	ds_read_b128 v[178:181], v244 offset:36864
	ds_read_b128 v[182:185], v244 offset:37888
	ds_read_b128 v[186:189], v244 offset:38912
	ds_read_b128 v[190:193], v244 offset:39936
	global_load_lds_dwordx4 v[210:211], off
	v_lshl_add_u64 v[210:211], vcc, 0, v[202:203]
	s_mov_b32 m0, s89
	s_nop 0
	global_load_lds_dwordx4 v[210:211], off
	s_waitcnt vmcnt(8)
	s_waitcnt lgkmcnt(0)
	s_barrier
	s_setprio 1
	s_waitcnt lgkmcnt(0)
	v_mfma_f32_16x16x32_bf16 v[154:157], v[114:117], v[162:165], v[154:157]
	v_mfma_f32_16x16x32_bf16 v[150:153], v[122:125], v[162:165], v[150:153]
	v_mfma_f32_16x16x32_bf16 v[110:113], v[114:117], v[170:173], v[110:113]
	v_mfma_f32_16x16x32_bf16 v[106:109], v[122:125], v[170:173], v[106:109]
	v_mfma_f32_16x16x32_bf16 v[92:95], v[114:117], v[178:181], v[92:95]
	v_mfma_f32_16x16x32_bf16 v[88:91], v[122:125], v[178:181], v[88:91]
	v_mfma_f32_16x16x32_bf16 v[76:79], v[114:117], v[186:189], v[76:79]
	v_mfma_f32_16x16x32_bf16 v[72:75], v[122:125], v[186:189], v[72:75]
	v_mfma_f32_16x16x32_bf16 v[154:157], v[118:121], v[166:169], v[154:157]
	v_mfma_f32_16x16x32_bf16 v[150:153], v[126:129], v[166:169], v[150:153]
	v_mfma_f32_16x16x32_bf16 v[110:113], v[118:121], v[174:177], v[110:113]
	v_mfma_f32_16x16x32_bf16 v[106:109], v[126:129], v[174:177], v[106:109]
	v_mfma_f32_16x16x32_bf16 v[92:95], v[118:121], v[182:185], v[92:95]
	v_mfma_f32_16x16x32_bf16 v[88:91], v[126:129], v[182:185], v[88:91]
	v_mfma_f32_16x16x32_bf16 v[76:79], v[118:121], v[190:193], v[76:79]
	v_mfma_f32_16x16x32_bf16 v[72:75], v[126:129], v[190:193], v[72:75]
	s_setprio 0
	s_setprio 1
	v_mfma_f32_16x16x32_bf16 v[134:137], v[138:141], v[162:165], v[134:137]
	v_mfma_f32_16x16x32_bf16 v[130:133], v[146:149], v[162:165], v[130:133]
	v_mfma_f32_16x16x32_bf16 v[102:105], v[138:141], v[170:173], v[102:105]
	v_mfma_f32_16x16x32_bf16 v[98:101], v[146:149], v[170:173], v[98:101]
	v_mfma_f32_16x16x32_bf16 v[84:87], v[138:141], v[178:181], v[84:87]
	v_mfma_f32_16x16x32_bf16 v[80:83], v[146:149], v[178:181], v[80:83]
	v_mfma_f32_16x16x32_bf16 v[68:71], v[138:141], v[186:189], v[68:71]
	v_mfma_f32_16x16x32_bf16 v[64:67], v[146:149], v[186:189], v[64:67]
	v_mfma_f32_16x16x32_bf16 v[134:137], v[142:145], v[166:169], v[134:137]
	v_mfma_f32_16x16x32_bf16 v[130:133], v[158:161], v[166:169], v[130:133]
	v_mfma_f32_16x16x32_bf16 v[102:105], v[142:145], v[174:177], v[102:105]
	v_mfma_f32_16x16x32_bf16 v[98:101], v[158:161], v[174:177], v[98:101]
	v_mfma_f32_16x16x32_bf16 v[84:87], v[142:145], v[182:185], v[84:87]
	v_mfma_f32_16x16x32_bf16 v[80:83], v[158:161], v[182:185], v[80:83]
	v_mfma_f32_16x16x32_bf16 v[68:71], v[142:145], v[190:193], v[68:71]
	v_mfma_f32_16x16x32_bf16 v[64:67], v[158:161], v[190:193], v[64:67]
	s_setprio 0
	s_barrier
	s_mov_b32 m0, s20
	v_lshl_add_u64 v[194:195], v[194:195], 0, s[22:23]
	ds_read_b128 v[162:165], v244 offset:49152
	ds_read_b128 v[166:169], v244 offset:50176
	ds_read_b128 v[170:173], v244 offset:51200
	ds_read_b128 v[174:177], v244 offset:52224
	ds_read_b128 v[178:181], v244 offset:53248
	ds_read_b128 v[182:185], v244 offset:54272
	ds_read_b128 v[186:189], v244 offset:55296
	ds_read_b128 v[190:193], v244 offset:56320
	global_load_lds_dwordx4 v[194:195], off
	v_lshl_add_u64 v[194:195], v[196:197], 0, s[22:23]
	s_mov_b32 m0, s58
	s_nop 0
	global_load_lds_dwordx4 v[194:195], off
	v_lshl_add_u64 v[194:195], s[96:97], 0, v[96:97]
	s_mov_b32 m0, s67
	s_nop 0
	global_load_lds_dwordx4 v[194:195], off
	v_lshl_add_u64 v[194:195], s[96:97], 0, v[204:205]
	s_mov_b32 m0, s66
	s_nop 0
	global_load_lds_dwordx4 v[194:195], off
	v_lshl_add_u64 v[194:195], v[206:207], 0, s[22:23]
	s_mov_b32 m0, s19
	s_nop 0
	global_load_lds_dwordx4 v[194:195], off
	v_lshl_add_u64 v[194:195], v[208:209], 0, s[22:23]
	s_mov_b32 m0, s68
	s_nop 0
	global_load_lds_dwordx4 v[194:195], off
	s_waitcnt vmcnt(8)
	s_waitcnt lgkmcnt(0)
	s_barrier
	s_setprio 1
	s_waitcnt lgkmcnt(0)
	v_mfma_f32_16x16x32_bf16 v[60:63], v[114:117], v[162:165], v[60:63]
	v_mfma_f32_16x16x32_bf16 v[56:59], v[122:125], v[162:165], v[56:59]
	v_mfma_f32_16x16x32_bf16 v[44:47], v[114:117], v[170:173], v[44:47]
	v_mfma_f32_16x16x32_bf16 v[40:43], v[122:125], v[170:173], v[40:43]
	v_mfma_f32_16x16x32_bf16 v[28:31], v[114:117], v[178:181], v[28:31]
	v_mfma_f32_16x16x32_bf16 v[24:27], v[122:125], v[178:181], v[24:27]
	v_mfma_f32_16x16x32_bf16 v[12:15], v[114:117], v[186:189], v[12:15]
	v_mfma_f32_16x16x32_bf16 v[8:11], v[122:125], v[186:189], v[8:11]
	v_mfma_f32_16x16x32_bf16 v[60:63], v[118:121], v[166:169], v[60:63]
	v_mfma_f32_16x16x32_bf16 v[56:59], v[126:129], v[166:169], v[56:59]
	v_mfma_f32_16x16x32_bf16 v[44:47], v[118:121], v[174:177], v[44:47]
	v_mfma_f32_16x16x32_bf16 v[40:43], v[126:129], v[174:177], v[40:43]
	v_mfma_f32_16x16x32_bf16 v[28:31], v[118:121], v[182:185], v[28:31]
	v_mfma_f32_16x16x32_bf16 v[24:27], v[126:129], v[182:185], v[24:27]
	v_mfma_f32_16x16x32_bf16 v[12:15], v[118:121], v[190:193], v[12:15]
	v_mfma_f32_16x16x32_bf16 v[8:11], v[126:129], v[190:193], v[8:11]
	s_setprio 0
	s_setprio 1
	v_mfma_f32_16x16x32_bf16 v[52:55], v[138:141], v[162:165], v[52:55]
	v_mfma_f32_16x16x32_bf16 v[48:51], v[146:149], v[162:165], v[48:51]
	v_mfma_f32_16x16x32_bf16 v[36:39], v[138:141], v[170:173], v[36:39]
	v_mfma_f32_16x16x32_bf16 v[32:35], v[146:149], v[170:173], v[32:35]
	v_mfma_f32_16x16x32_bf16 v[20:23], v[138:141], v[178:181], v[20:23]
	v_mfma_f32_16x16x32_bf16 v[16:19], v[146:149], v[178:181], v[16:19]
	v_mfma_f32_16x16x32_bf16 v[4:7], v[138:141], v[186:189], v[4:7]
	v_mfma_f32_16x16x32_bf16 v[0:3], v[146:149], v[186:189], v[0:3]
	v_mfma_f32_16x16x32_bf16 v[52:55], v[142:145], v[166:169], v[52:55]
	v_mfma_f32_16x16x32_bf16 v[48:51], v[158:161], v[166:169], v[48:51]
	v_mfma_f32_16x16x32_bf16 v[36:39], v[142:145], v[174:177], v[36:39]
	v_mfma_f32_16x16x32_bf16 v[32:35], v[158:161], v[174:177], v[32:35]
	v_mfma_f32_16x16x32_bf16 v[20:23], v[142:145], v[182:185], v[20:23]
	v_mfma_f32_16x16x32_bf16 v[16:19], v[158:161], v[182:185], v[16:19]
	v_mfma_f32_16x16x32_bf16 v[4:7], v[142:145], v[190:193], v[4:7]
	v_mfma_f32_16x16x32_bf16 v[0:3], v[158:161], v[190:193], v[0:3]
	s_setprio 0
	s_barrier
	s_movk_i32 s24, 0x100
	s_andn2_b64 vcc, exec, s[94:95]
	s_mov_b64 s[96:97], -1
	s_mov_b64 s[94:95], 0
	s_cbranch_vccz .LBB0_111
	v_mov_b64_e32 v[250:251], 0x200
	v_lshl_or_b32 v206, s74, 8, v243
	v_lshl_add_u32 v236, s88, 8, v199
	v_ashrrev_i32_e32 v207, 31, v206
	v_lshlrev_b64 v[238:239], 1, v[206:207]
	v_ashrrev_i32_e32 v237, 31, v236
	v_lshl_add_u64 v[118:119], s[52:53], 0, v[238:239]
	v_lshlrev_b64 v[240:241], 11, v[236:237]
	v_lshl_add_u64 v[114:115], v[118:119], 0, v[240:241]
	global_load_dwordx4 v[190:193], v[114:115], off
	global_load_dwordx4 v[186:189], v[114:115], off offset:256
	v_or_b32_e32 v232, 16, v236
	v_ashrrev_i32_e32 v233, 31, v232
	v_or_b32_e32 v228, 32, v236
	v_lshlrev_b64 v[234:235], 11, v[232:233]
	v_ashrrev_i32_e32 v229, 31, v228
	v_or_b32_e32 v224, 48, v236
	v_lshl_add_u64 v[114:115], v[118:119], 0, v[234:235]
	v_lshlrev_b64 v[230:231], 11, v[228:229]
	v_ashrrev_i32_e32 v225, 31, v224
	v_add_u32_e32 v220, 0x80, v236
	global_load_dwordx4 v[182:185], v[114:115], off
	global_load_dwordx4 v[178:181], v[114:115], off offset:256
	v_lshl_add_u64 v[114:115], v[118:119], 0, v[230:231]
	v_lshlrev_b64 v[226:227], 11, v[224:225]
	v_ashrrev_i32_e32 v221, 31, v220
	v_add_u32_e32 v216, 0x90, v236
	global_load_dwordx4 v[174:177], v[114:115], off
	global_load_dwordx4 v[170:173], v[114:115], off offset:256
	v_lshl_add_u64 v[114:115], v[118:119], 0, v[226:227]
	v_lshlrev_b64 v[222:223], 11, v[220:221]
	v_ashrrev_i32_e32 v217, 31, v216
	v_add_u32_e32 v212, 0xa0, v236
	v_add_u32_e32 v208, 0xb0, v236
	global_load_dwordx4 v[166:169], v[114:115], off
	global_load_dwordx4 v[162:165], v[114:115], off offset:256
	v_lshl_add_u64 v[114:115], v[118:119], 0, v[222:223]
	v_lshlrev_b64 v[218:219], 11, v[216:217]
	v_ashrrev_i32_e32 v213, 31, v212
	v_ashrrev_i32_e32 v209, 31, v208
	global_load_dwordx4 v[158:161], v[114:115], off
	global_load_dwordx4 v[146:149], v[114:115], off offset:256
	v_lshl_add_u64 v[114:115], v[118:119], 0, v[218:219]
	v_lshlrev_b64 v[214:215], 11, v[212:213]
	v_lshlrev_b64 v[210:211], 11, v[208:209]
	global_load_dwordx4 v[142:145], v[114:115], off
	global_load_dwordx4 v[138:141], v[114:115], off offset:256
	v_lshl_add_u64 v[114:115], v[118:119], 0, v[214:215]
	v_lshl_add_u64 v[118:119], v[118:119], 0, v[210:211]
	global_load_dwordx4 v[122:125], v[114:115], off
	global_load_dwordx4 v[114:117], v[114:115], off offset:256
	global_load_dwordx4 v[126:129], v[118:119], off
	global_load_dwordx4 v[118:121], v[118:119], off offset:256
	s_and_b64 vcc, exec, s[78:79]
	s_cbranch_vccz .LBB0_114
	s_barrier
.LBB0_114:
	s_nop 0
	s_nop 0
	s_nop 0
	s_waitcnt vmcnt(0)
	v_lshlrev_b32_e32 v194, 16, v190
	v_and_b32_e32 v195, 0xffff0000, v190
	v_lshlrev_b32_e32 v190, 16, v191
	v_and_b32_e32 v191, 0xffff0000, v191
	v_lshlrev_b32_e32 v196, 16, v192
	v_and_b32_e32 v197, 0xffff0000, v192
	v_lshlrev_b32_e32 v192, 16, v193
	v_and_b32_e32 v193, 0xffff0000, v193
	v_pk_add_f32 v[154:155], v[154:155], v[194:195]
	v_lshl_add_u64 v[194:195], s[52:53], 0, v[240:241]
	v_pk_add_f32 v[156:157], v[156:157], v[190:191]
	v_pk_add_f32 v[190:191], v[152:153], v[192:193]
	v_pk_add_f32 v[192:193], v[150:151], v[196:197]
	v_cvt_pk_bf16_f32 v150, v154, v155
	v_cvt_pk_bf16_f32 v151, v156, v157
	v_lshl_add_u64 v[194:195], v[194:195], 0, v[238:239]
	v_cvt_pk_bf16_f32 v152, v192, v193
	v_cvt_pk_bf16_f32 v153, v190, v191
	global_store_dwordx4 v[194:195], v[150:153], off
	s_nop 1
	v_mul_f32_e32 v150, v155, v155
	v_mul_f32_e32 v151, v157, v157
	v_fmac_f32_e32 v150, v154, v154
	v_fmac_f32_e32 v151, v156, v156
	v_add_f32_e32 v150, v150, v151
	v_mul_f32_e32 v151, v193, v193
	v_mul_f32_e32 v152, v191, v191
	v_fmac_f32_e32 v151, v192, v192
	v_fmac_f32_e32 v152, v190, v190
	v_add_f32_e32 v151, v151, v152
	v_add_f32_e32 v190, v150, v151
	v_lshlrev_b32_e32 v150, 16, v186
	v_and_b32_e32 v151, 0xffff0000, v186
	v_lshlrev_b32_e32 v152, 16, v187
	v_and_b32_e32 v153, 0xffff0000, v187
	v_lshlrev_b32_e32 v154, 16, v188
	v_and_b32_e32 v155, 0xffff0000, v188
	v_lshlrev_b32_e32 v156, 16, v189
	v_and_b32_e32 v157, 0xffff0000, v189
	v_pk_add_f32 v[136:137], v[136:137], v[152:153]
	v_pk_add_f32 v[134:135], v[134:135], v[150:151]
	v_pk_add_f32 v[152:153], v[130:131], v[154:155]
	v_cvt_pk_bf16_f32 v130, v134, v135
	v_cvt_pk_bf16_f32 v131, v136, v137
	v_pk_add_f32 v[150:151], v[132:133], v[156:157]
	v_cvt_pk_bf16_f32 v132, v152, v153
	s_nop 0
	v_cvt_pk_bf16_f32 v133, v150, v151
	global_store_dwordx4 v[194:195], v[130:133], off offset:256
	s_nop 1
	v_mul_f32_e32 v130, v135, v135
	v_mul_f32_e32 v131, v137, v137
	v_fmac_f32_e32 v130, v134, v134
	v_fmac_f32_e32 v131, v136, v136
	v_add_f32_e32 v130, v130, v131
	v_mul_f32_e32 v131, v153, v153
	v_mul_f32_e32 v132, v151, v151
	v_fmac_f32_e32 v131, v152, v152
	v_fmac_f32_e32 v132, v150, v150
	v_add_f32_e32 v131, v131, v132
	v_add_f32_e32 v130, v130, v131
	v_and_b32_e32 v132, 64, v248
	v_add_f32_e32 v131, v190, v130
	v_xor_b32_e32 v130, 16, v248
	v_add_u32_e32 v133, 64, v132
	v_cmp_lt_i32_e32 vcc, v130, v133
	s_nop 1
	v_cndmask_b32_e32 v130, v248, v130, vcc
	v_lshlrev_b32_e32 v130, 2, v130
	ds_bpermute_b32 v132, v130, v131
	s_waitcnt lgkmcnt(0)
	v_add_f32_e32 v132, v131, v132
	v_xor_b32_e32 v131, 32, v248
	v_cmp_lt_i32_e32 vcc, v131, v133
	s_nop 1
	v_cndmask_b32_e32 v131, v248, v131, vcc
	v_lshlrev_b32_e32 v131, 2, v131
	ds_bpermute_b32 v133, v131, v132
	s_and_saveexec_b64 s[24:25], s[0:1]
	s_movk_i32 s96, 0x2000
	s_mov_b32 s97, 0x10000
	s_cbranch_execz .LBB0_116
	s_waitcnt lgkmcnt(0)
	v_add_f32_e32 v134, v132, v133
	s_lshl_b32 s14, s74, 2
	v_lshlrev_b64 v[132:133], 6, v[236:237]
	s_ashr_i32 s15, s14, 31
	v_lshl_add_u64 v[132:133], s[56:57], 0, v[132:133]
	v_lshl_add_u64 v[132:133], s[14:15], 2, v[132:133]
	s_lshl_b32 s16, s18, 2
	v_lshl_add_u64 v[132:133], v[132:133], 0, s[16:17]
	global_store_dword v[132:133], v134, off

.LBB0_179:
	s_add_u32 s2, s88, 0xfffc0080
	s_addc_u32 s14, s89, -1
	s_add_i32 s15, 0, 0x10000
	s_cmp_eq_u32 s62, 12
	s_cselect_b32 s27, s5, s14
	s_cselect_b32 s26, s6, s2
	s_cselect_b32 s25, s7, s19
	s_cselect_b32 s24, s8, s18
	s_add_i32 s2, 0, 0x14000
	v_add_u32_e32 v138, s15, v206
	v_add_u32_e32 v176, s2, v206
	ds_read_b128 v[122:125], v138
	ds_read_b128 v[126:129], v138 offset:1024
	ds_read_b128 v[134:137], v138 offset:2048
	ds_read_b128 v[138:141], v138 offset:3072
	ds_read_b128 v[146:149], v176
	ds_read_b128 v[168:171], v176 offset:1024
	ds_read_b128 v[172:175], v176 offset:2048
	ds_read_b128 v[176:179], v176 offset:3072
	v_lshl_add_u64 v[180:181], s[88:89], 0, v[166:167]
	s_add_i32 m0, s39, 0xc000
	ds_read_b128 v[208:211], v151
	ds_read_b128 v[212:215], v151 offset:1024
	ds_read_b128 v[216:219], v151 offset:2048
	ds_read_b128 v[220:223], v151 offset:3072
	ds_read_b128 v[224:227], v151 offset:4096
	ds_read_b128 v[228:231], v151 offset:5120
	ds_read_b128 v[232:235], v151 offset:6144
	ds_read_b128 v[236:239], v151 offset:7168
	global_load_lds_dwordx4 v[180:181], off
	v_lshl_add_u64 v[180:181], s[88:89], 0, v[164:165]
	s_add_i32 m0, s39, 0xe000
	s_nop 0
	global_load_lds_dwordx4 v[180:181], off
	s_waitcnt vmcnt(8)
	s_waitcnt lgkmcnt(0)
	s_barrier
	s_setprio 1
	s_waitcnt lgkmcnt(0)
	v_mfma_f32_16x16x32_bf16 v[142:145], v[122:125], v[208:211], v[142:145]
	v_mfma_f32_16x16x32_bf16 v[130:133], v[134:137], v[208:211], v[130:133]
	v_mfma_f32_16x16x32_bf16 v[110:113], v[122:125], v[216:219], v[110:113]
	v_mfma_f32_16x16x32_bf16 v[106:109], v[134:137], v[216:219], v[106:109]
	v_mfma_f32_16x16x32_bf16 v[92:95], v[122:125], v[224:227], v[92:95]
	v_mfma_f32_16x16x32_bf16 v[88:91], v[134:137], v[224:227], v[88:91]
	v_mfma_f32_16x16x32_bf16 v[76:79], v[122:125], v[232:235], v[76:79]
	v_mfma_f32_16x16x32_bf16 v[72:75], v[134:137], v[232:235], v[72:75]
	v_mfma_f32_16x16x32_bf16 v[142:145], v[126:129], v[212:215], v[142:145]
	v_mfma_f32_16x16x32_bf16 v[130:133], v[138:141], v[212:215], v[130:133]
	v_mfma_f32_16x16x32_bf16 v[110:113], v[126:129], v[220:223], v[110:113]
	v_mfma_f32_16x16x32_bf16 v[106:109], v[138:141], v[220:223], v[106:109]
	v_mfma_f32_16x16x32_bf16 v[92:95], v[126:129], v[228:231], v[92:95]
	v_mfma_f32_16x16x32_bf16 v[88:91], v[138:141], v[228:231], v[88:91]
	v_mfma_f32_16x16x32_bf16 v[76:79], v[126:129], v[236:239], v[76:79]
	v_mfma_f32_16x16x32_bf16 v[72:75], v[138:141], v[236:239], v[72:75]
	s_setprio 0
	s_setprio 1
	v_mfma_f32_16x16x32_bf16 v[118:121], v[146:149], v[208:211], v[118:121]
	v_mfma_f32_16x16x32_bf16 v[114:117], v[172:175], v[208:211], v[114:117]
	v_mfma_f32_16x16x32_bf16 v[102:105], v[146:149], v[216:219], v[102:105]
	v_mfma_f32_16x16x32_bf16 v[98:101], v[172:175], v[216:219], v[98:101]
	v_mfma_f32_16x16x32_bf16 v[84:87], v[146:149], v[224:227], v[84:87]
	v_mfma_f32_16x16x32_bf16 v[80:83], v[172:175], v[224:227], v[80:83]
	v_mfma_f32_16x16x32_bf16 v[68:71], v[146:149], v[232:235], v[68:71]
	v_mfma_f32_16x16x32_bf16 v[64:67], v[172:175], v[232:235], v[64:67]
	v_mfma_f32_16x16x32_bf16 v[118:121], v[168:171], v[212:215], v[118:121]
	v_mfma_f32_16x16x32_bf16 v[114:117], v[176:179], v[212:215], v[114:117]
	v_mfma_f32_16x16x32_bf16 v[102:105], v[168:171], v[220:223], v[102:105]
	v_mfma_f32_16x16x32_bf16 v[98:101], v[176:179], v[220:223], v[98:101]
	v_mfma_f32_16x16x32_bf16 v[84:87], v[168:171], v[228:231], v[84:87]
	v_mfma_f32_16x16x32_bf16 v[80:83], v[176:179], v[228:231], v[80:83]
	v_mfma_f32_16x16x32_bf16 v[68:71], v[168:171], v[236:239], v[68:71]
	v_mfma_f32_16x16x32_bf16 v[64:67], v[176:179], v[236:239], v[64:67]
	s_setprio 0
	s_barrier
	s_add_i32 s14, s15, s38
	v_lshl_add_u64 v[180:181], s[24:25], 0, v[154:155]
	s_mov_b32 m0, s14
	ds_read_b128 v[208:211], v151 offset:16384
	ds_read_b128 v[212:215], v151 offset:17408
	ds_read_b128 v[216:219], v151 offset:18432
	ds_read_b128 v[220:223], v151 offset:19456
	ds_read_b128 v[224:227], v151 offset:20480
	ds_read_b128 v[228:231], v151 offset:21504
	ds_read_b128 v[232:235], v151 offset:22528
	ds_read_b128 v[236:239], v151 offset:23552
	global_load_lds_dwordx4 v[180:181], off
	s_add_i32 m0, s14, 0x2000
	s_add_u32 s14, s24, 0x40000
	v_lshl_add_u64 v[184:185], s[24:25], 0, v[158:159]
	s_addc_u32 s15, s25, 0
	s_add_i32 s2, s2, s38
	global_load_lds_dwordx4 v[184:185], off
	v_lshl_add_u64 v[194:195], s[14:15], 0, v[154:155]
	s_mov_b32 m0, s2
	v_lshl_add_u64 v[196:197], s[26:27], 0, v[156:157]
	global_load_lds_dwordx4 v[194:195], off
	v_lshl_add_u64 v[194:195], s[14:15], 0, v[158:159]
	s_add_i32 m0, s2, 0x2000
	s_nop 0
	global_load_lds_dwordx4 v[194:195], off
	v_lshl_add_u64 v[194:195], s[26:27], 0, v[96:97]
	s_mov_b32 m0, s39
	s_nop 0
	global_load_lds_dwordx4 v[194:195], off
	s_mov_b32 m0, s42
	s_nop 0
	global_load_lds_dwordx4 v[196:197], off
	s_waitcnt vmcnt(8)
	s_waitcnt lgkmcnt(0)
	s_barrier
	s_setprio 1
	s_waitcnt lgkmcnt(0)
	v_mfma_f32_16x16x32_bf16 v[60:63], v[122:125], v[208:211], v[60:63]
	v_mfma_f32_16x16x32_bf16 v[56:59], v[134:137], v[208:211], v[56:59]
	v_mfma_f32_16x16x32_bf16 v[44:47], v[122:125], v[216:219], v[44:47]
	v_mfma_f32_16x16x32_bf16 v[40:43], v[134:137], v[216:219], v[40:43]
	v_mfma_f32_16x16x32_bf16 v[28:31], v[122:125], v[224:227], v[28:31]
	v_mfma_f32_16x16x32_bf16 v[24:27], v[134:137], v[224:227], v[24:27]
	v_mfma_f32_16x16x32_bf16 v[12:15], v[122:125], v[232:235], v[12:15]
	v_mfma_f32_16x16x32_bf16 v[8:11], v[134:137], v[232:235], v[8:11]
	v_mfma_f32_16x16x32_bf16 v[60:63], v[126:129], v[212:215], v[60:63]
	v_mfma_f32_16x16x32_bf16 v[56:59], v[138:141], v[212:215], v[56:59]
	v_mfma_f32_16x16x32_bf16 v[44:47], v[126:129], v[220:223], v[44:47]
	v_mfma_f32_16x16x32_bf16 v[40:43], v[138:141], v[220:223], v[40:43]
	v_mfma_f32_16x16x32_bf16 v[28:31], v[126:129], v[228:231], v[28:31]
	v_mfma_f32_16x16x32_bf16 v[24:27], v[138:141], v[228:231], v[24:27]
	v_mfma_f32_16x16x32_bf16 v[12:15], v[126:129], v[236:239], v[12:15]
	v_mfma_f32_16x16x32_bf16 v[8:11], v[138:141], v[236:239], v[8:11]
	s_setprio 0
	s_setprio 1
	v_mfma_f32_16x16x32_bf16 v[52:55], v[146:149], v[208:211], v[52:55]
	v_mfma_f32_16x16x32_bf16 v[48:51], v[172:175], v[208:211], v[48:51]
	v_mfma_f32_16x16x32_bf16 v[36:39], v[146:149], v[216:219], v[36:39]
	v_mfma_f32_16x16x32_bf16 v[32:35], v[172:175], v[216:219], v[32:35]
	v_mfma_f32_16x16x32_bf16 v[20:23], v[146:149], v[224:227], v[20:23]
	v_mfma_f32_16x16x32_bf16 v[16:19], v[172:175], v[224:227], v[16:19]
	v_mfma_f32_16x16x32_bf16 v[4:7], v[146:149], v[232:235], v[4:7]
	v_mfma_f32_16x16x32_bf16 v[0:3], v[172:175], v[232:235], v[0:3]
	v_mfma_f32_16x16x32_bf16 v[52:55], v[168:171], v[212:215], v[52:55]
	v_mfma_f32_16x16x32_bf16 v[48:51], v[176:179], v[212:215], v[48:51]
	v_mfma_f32_16x16x32_bf16 v[36:39], v[168:171], v[220:223], v[36:39]
	v_mfma_f32_16x16x32_bf16 v[32:35], v[176:179], v[220:223], v[32:35]
	v_mfma_f32_16x16x32_bf16 v[20:23], v[168:171], v[228:231], v[20:23]
	v_mfma_f32_16x16x32_bf16 v[16:19], v[176:179], v[228:231], v[16:19]
	v_mfma_f32_16x16x32_bf16 v[4:7], v[168:171], v[236:239], v[4:7]
	v_mfma_f32_16x16x32_bf16 v[0:3], v[176:179], v[236:239], v[0:3]
	s_setprio 0
	s_barrier
	s_add_i32 s2, 0, 0x18000
	s_add_i32 s20, 0, 0x1c000
	v_add_u32_e32 v138, s2, v206
	v_add_u32_e32 v176, s20, v206
	ds_read_b128 v[122:125], v138
	ds_read_b128 v[126:129], v138 offset:1024
	ds_read_b128 v[134:137], v138 offset:2048
	ds_read_b128 v[138:141], v138 offset:3072
	ds_read_b128 v[146:149], v176
	ds_read_b128 v[168:171], v176 offset:1024
	ds_read_b128 v[172:175], v176 offset:2048
	ds_read_b128 v[176:179], v176 offset:3072
	s_add_u32 s14, s26, 0x40000
	s_addc_u32 s15, s27, 0
	s_mov_b32 m0, s43
	v_lshl_add_u64 v[200:201], s[14:15], 0, v[96:97]
	ds_read_b128 v[208:211], v151 offset:32768
	ds_read_b128 v[212:215], v151 offset:33792
	ds_read_b128 v[216:219], v151 offset:34816
	ds_read_b128 v[220:223], v151 offset:35840
	ds_read_b128 v[224:227], v151 offset:36864
	ds_read_b128 v[228:231], v151 offset:37888
	ds_read_b128 v[232:235], v151 offset:38912
	ds_read_b128 v[236:239], v151 offset:39936
	global_load_lds_dwordx4 v[200:201], off
	v_lshl_add_u64 v[200:201], s[14:15], 0, v[156:157]
	s_mov_b32 m0, s45
	s_nop 0
	global_load_lds_dwordx4 v[200:201], off
	s_waitcnt vmcnt(8)
	s_waitcnt lgkmcnt(0)
	s_barrier
	s_setprio 1
	s_waitcnt lgkmcnt(0)
	v_mfma_f32_16x16x32_bf16 v[142:145], v[122:125], v[208:211], v[142:145]
	v_mfma_f32_16x16x32_bf16 v[130:133], v[134:137], v[208:211], v[130:133]
	v_mfma_f32_16x16x32_bf16 v[110:113], v[122:125], v[216:219], v[110:113]
	v_mfma_f32_16x16x32_bf16 v[106:109], v[134:137], v[216:219], v[106:109]
	v_mfma_f32_16x16x32_bf16 v[92:95], v[122:125], v[224:227], v[92:95]
	v_mfma_f32_16x16x32_bf16 v[88:91], v[134:137], v[224:227], v[88:91]
	v_mfma_f32_16x16x32_bf16 v[76:79], v[122:125], v[232:235], v[76:79]
	v_mfma_f32_16x16x32_bf16 v[72:75], v[134:137], v[232:235], v[72:75]
	v_mfma_f32_16x16x32_bf16 v[142:145], v[126:129], v[212:215], v[142:145]
	v_mfma_f32_16x16x32_bf16 v[130:133], v[138:141], v[212:215], v[130:133]
	v_mfma_f32_16x16x32_bf16 v[110:113], v[126:129], v[220:223], v[110:113]
	v_mfma_f32_16x16x32_bf16 v[106:109], v[138:141], v[220:223], v[106:109]
	v_mfma_f32_16x16x32_bf16 v[92:95], v[126:129], v[228:231], v[92:95]
	v_mfma_f32_16x16x32_bf16 v[88:91], v[138:141], v[228:231], v[88:91]
	v_mfma_f32_16x16x32_bf16 v[76:79], v[126:129], v[236:239], v[76:79]
	v_mfma_f32_16x16x32_bf16 v[72:75], v[138:141], v[236:239], v[72:75]
	s_setprio 0
	s_setprio 1
	v_mfma_f32_16x16x32_bf16 v[118:121], v[146:149], v[208:211], v[118:121]
	v_mfma_f32_16x16x32_bf16 v[114:117], v[172:175], v[208:211], v[114:117]
	v_mfma_f32_16x16x32_bf16 v[102:105], v[146:149], v[216:219], v[102:105]
	v_mfma_f32_16x16x32_bf16 v[98:101], v[172:175], v[216:219], v[98:101]
	v_mfma_f32_16x16x32_bf16 v[84:87], v[146:149], v[224:227], v[84:87]
	v_mfma_f32_16x16x32_bf16 v[80:83], v[172:175], v[224:227], v[80:83]
	v_mfma_f32_16x16x32_bf16 v[68:71], v[146:149], v[232:235], v[68:71]
	v_mfma_f32_16x16x32_bf16 v[64:67], v[172:175], v[232:235], v[64:67]
	v_mfma_f32_16x16x32_bf16 v[118:121], v[168:171], v[212:215], v[118:121]
	v_mfma_f32_16x16x32_bf16 v[114:117], v[176:179], v[212:215], v[114:117]
	v_mfma_f32_16x16x32_bf16 v[102:105], v[168:171], v[220:223], v[102:105]
	v_mfma_f32_16x16x32_bf16 v[98:101], v[176:179], v[220:223], v[98:101]
	v_mfma_f32_16x16x32_bf16 v[84:87], v[168:171], v[228:231], v[84:87]
	v_mfma_f32_16x16x32_bf16 v[80:83], v[176:179], v[228:231], v[80:83]
	v_mfma_f32_16x16x32_bf16 v[68:71], v[168:171], v[236:239], v[68:71]
	v_mfma_f32_16x16x32_bf16 v[64:67], v[176:179], v[236:239], v[64:67]
	s_setprio 0
	s_barrier
	s_add_i32 s2, s2, s38
	v_lshl_add_u64 v[180:181], v[180:181], 0, s[22:23]
	s_mov_b32 m0, s2
	ds_read_b128 v[208:211], v151 offset:49152
	ds_read_b128 v[212:215], v151 offset:50176
	ds_read_b128 v[216:219], v151 offset:51200
	ds_read_b128 v[220:223], v151 offset:52224
	ds_read_b128 v[224:227], v151 offset:53248
	ds_read_b128 v[228:231], v151 offset:54272
	ds_read_b128 v[232:235], v151 offset:55296
	ds_read_b128 v[236:239], v151 offset:56320
	global_load_lds_dwordx4 v[180:181], off
	s_add_i32 m0, s2, 0x2000
	s_add_u32 s14, s24, 0x40080
	v_lshl_add_u64 v[180:181], v[184:185], 0, s[22:23]
	s_addc_u32 s15, s25, 0
	s_add_i32 s2, s20, s38
	global_load_lds_dwordx4 v[180:181], off
	v_lshl_add_u64 v[180:181], s[14:15], 0, v[154:155]
	s_mov_b32 m0, s2
	s_nop 0
	global_load_lds_dwordx4 v[180:181], off
	v_lshl_add_u64 v[180:181], s[14:15], 0, v[158:159]
	s_add_i32 m0, s2, 0x2000
	s_nop 0
	global_load_lds_dwordx4 v[180:181], off
	v_lshl_add_u64 v[180:181], v[194:195], 0, s[22:23]
	s_mov_b32 m0, s47
	s_nop 0
	global_load_lds_dwordx4 v[180:181], off
	v_lshl_add_u64 v[180:181], v[196:197], 0, s[22:23]
	s_mov_b32 m0, s59
	s_nop 0
	global_load_lds_dwordx4 v[180:181], off
	s_waitcnt vmcnt(8)
	s_waitcnt lgkmcnt(0)
	s_barrier
	s_setprio 1
	s_waitcnt lgkmcnt(0)
	v_mfma_f32_16x16x32_bf16 v[60:63], v[122:125], v[208:211], v[60:63]
	v_mfma_f32_16x16x32_bf16 v[56:59], v[134:137], v[208:211], v[56:59]
	v_mfma_f32_16x16x32_bf16 v[44:47], v[122:125], v[216:219], v[44:47]
	v_mfma_f32_16x16x32_bf16 v[40:43], v[134:137], v[216:219], v[40:43]
	v_mfma_f32_16x16x32_bf16 v[28:31], v[122:125], v[224:227], v[28:31]
	v_mfma_f32_16x16x32_bf16 v[24:27], v[134:137], v[224:227], v[24:27]
	v_mfma_f32_16x16x32_bf16 v[12:15], v[122:125], v[232:235], v[12:15]
	v_mfma_f32_16x16x32_bf16 v[8:11], v[134:137], v[232:235], v[8:11]
	v_mfma_f32_16x16x32_bf16 v[60:63], v[126:129], v[212:215], v[60:63]
	v_mfma_f32_16x16x32_bf16 v[56:59], v[138:141], v[212:215], v[56:59]
	v_mfma_f32_16x16x32_bf16 v[44:47], v[126:129], v[220:223], v[44:47]
	v_mfma_f32_16x16x32_bf16 v[40:43], v[138:141], v[220:223], v[40:43]
	v_mfma_f32_16x16x32_bf16 v[28:31], v[126:129], v[228:231], v[28:31]
	v_mfma_f32_16x16x32_bf16 v[24:27], v[138:141], v[228:231], v[24:27]
	v_mfma_f32_16x16x32_bf16 v[12:15], v[126:129], v[236:239], v[12:15]
	v_mfma_f32_16x16x32_bf16 v[8:11], v[138:141], v[236:239], v[8:11]
	s_setprio 0
	s_setprio 1
	v_mfma_f32_16x16x32_bf16 v[52:55], v[146:149], v[208:211], v[52:55]
	v_mfma_f32_16x16x32_bf16 v[48:51], v[172:175], v[208:211], v[48:51]
	v_mfma_f32_16x16x32_bf16 v[36:39], v[146:149], v[216:219], v[36:39]
	v_mfma_f32_16x16x32_bf16 v[32:35], v[172:175], v[216:219], v[32:35]
	v_mfma_f32_16x16x32_bf16 v[20:23], v[146:149], v[224:227], v[20:23]
	v_mfma_f32_16x16x32_bf16 v[16:19], v[172:175], v[224:227], v[16:19]
	v_mfma_f32_16x16x32_bf16 v[4:7], v[146:149], v[232:235], v[4:7]
	v_mfma_f32_16x16x32_bf16 v[0:3], v[172:175], v[232:235], v[0:3]
	v_mfma_f32_16x16x32_bf16 v[52:55], v[168:171], v[212:215], v[52:55]
	v_mfma_f32_16x16x32_bf16 v[48:51], v[176:179], v[212:215], v[48:51]
	v_mfma_f32_16x16x32_bf16 v[36:39], v[168:171], v[220:223], v[36:39]
	v_mfma_f32_16x16x32_bf16 v[32:35], v[176:179], v[220:223], v[32:35]
	v_mfma_f32_16x16x32_bf16 v[20:23], v[168:171], v[228:231], v[20:23]
	v_mfma_f32_16x16x32_bf16 v[16:19], v[176:179], v[228:231], v[16:19]
	v_mfma_f32_16x16x32_bf16 v[4:7], v[168:171], v[236:239], v[4:7]
	v_mfma_f32_16x16x32_bf16 v[0:3], v[176:179], v[236:239], v[0:3]
	s_setprio 0
	s_barrier
	s_add_i32 s62, s62, 2
	s_add_u32 s18, s18, 0x100
	s_addc_u32 s19, s19, 0
	s_add_u32 s88, s88, 0x100
	s_addc_u32 s89, s89, 0
	s_cmp_gt_u32 s62, 13
	s_cbranch_scc0 .LBB0_179
	v_lshl_add_u32 v184, s4, 8, v205
	v_ashrrev_i32_e32 v185, 31, v184
	v_lshlrev_b64 v[122:123], 6, v[184:185]
	v_lshl_add_u64 v[122:123], v[160:161], 0, v[122:123]
	global_load_dwordx4 v[210:213], v[122:123], off
	v_or_b32_e32 v180, 16, v184
	v_ashrrev_i32_e32 v181, 31, v180
	v_lshlrev_b64 v[122:123], 6, v[180:181]
	v_or_b32_e32 v178, 32, v184
	v_lshl_add_u64 v[122:123], v[160:161], 0, v[122:123]
	v_ashrrev_i32_e32 v179, 31, v178
	global_load_dwordx4 v[214:217], v[122:123], off
	v_lshlrev_b64 v[122:123], 6, v[178:179]
	v_lshl_add_u64 v[122:123], v[160:161], 0, v[122:123]
	global_load_dwordx4 v[218:221], v[122:123], off
	v_or_b32_e32 v176, 48, v184
	v_ashrrev_i32_e32 v177, 31, v176
	v_lshlrev_b64 v[122:123], 6, v[176:177]
	v_add_u32_e32 v174, 0x80, v184
	v_lshl_add_u64 v[122:123], v[160:161], 0, v[122:123]
	v_ashrrev_i32_e32 v175, 31, v174
	global_load_dwordx4 v[146:149], v[122:123], off
	v_lshlrev_b64 v[122:123], 6, v[174:175]
	v_lshl_add_u64 v[122:123], v[160:161], 0, v[122:123]
	global_load_dwordx4 v[138:141], v[122:123], off
	v_add_u32_e32 v172, 0x90, v184
	v_ashrrev_i32_e32 v173, 31, v172
	v_lshlrev_b64 v[122:123], 6, v[172:173]
	v_add_u32_e32 v170, 0xa0, v184
	v_lshl_add_u64 v[122:123], v[160:161], 0, v[122:123]
	v_ashrrev_i32_e32 v171, 31, v170
	global_load_dwordx4 v[134:137], v[122:123], off
	v_lshlrev_b64 v[122:123], 6, v[170:171]
	v_lshl_add_u64 v[122:123], v[160:161], 0, v[122:123]
	global_load_dwordx4 v[126:129], v[122:123], off
	v_add_u32_e32 v168, 0xb0, v184
	v_ashrrev_i32_e32 v169, 31, v168
	v_lshlrev_b64 v[122:123], 6, v[168:169]
	v_lshl_add_u64 v[122:123], v[160:161], 0, v[122:123]
	global_load_dwordx4 v[122:125], v[122:123], off
	s_and_b64 vcc, exec, s[78:79]
	s_cbranch_vccz .LBB0_182
	s_barrier
.LBB0_182:
	v_and_b32_e32 v186, 64, v248
	v_xor_b32_e32 v182, 16, v248
	v_add_u32_e32 v186, 64, v186
	v_cmp_lt_i32_e32 vcc, v182, v186
	s_nop 1
	v_cndmask_b32_e32 v182, v248, v182, vcc
	v_lshlrev_b32_e32 v207, 2, v182
	v_xor_b32_e32 v182, 32, v248
	v_cmp_lt_i32_e32 vcc, v182, v186
	s_nop 1
	v_cndmask_b32_e32 v182, v248, v182, vcc
	v_lshlrev_b32_e32 v208, 2, v182
	s_mov_b32 s2, 0x358637bd
	v_lshlrev_b64 v[184:185], 9, v[184:185]
	s_waitcnt vmcnt(0)
	v_mov_b32_e32 v194, v211
	v_mov_b32_e32 v195, v212
	v_mov_b32_e32 v211, v213
	v_pk_add_f32 v[194:195], v[194:195], v[210:211]
	v_mov_b32_e32 v196, v219
	v_add_f32_e32 v182, v194, v195
	ds_bpermute_b32 v186, v207, v182
	v_mov_b32_e32 v194, v215
	v_mov_b32_e32 v195, v216
	v_mov_b32_e32 v215, v217
	v_mov_b32_e32 v197, v220
	v_mov_b32_e32 v219, v221
	v_pk_add_f32 v[194:195], v[194:195], v[214:215]
	v_pk_add_f32 v[196:197], v[196:197], v[218:219]
	s_waitcnt lgkmcnt(0)
	v_add_f32_e32 v182, v182, v186
	v_mov_b32_e32 v200, v196
	v_mov_b32_e32 v201, v194
	v_mov_b32_e32 v194, v197
	ds_bpermute_b32 v186, v208, v182
	v_pk_add_f32 v[194:195], v[200:201], v[194:195]
	ds_bpermute_b32 v197, v207, v195
	ds_bpermute_b32 v196, v207, v194
	v_mov_b64_e32 v[200:201], s[2:3]
	s_waitcnt lgkmcnt(2)
	v_add_f32_e32 v182, v182, v186
	v_fmamk_f32 v182, v182, 0x3a800000, v247
	v_cmp_gt_f32_e32 vcc, s29, v182
	s_waitcnt lgkmcnt(0)
	v_pk_add_f32 v[194:195], v[194:195], v[196:197]
	v_mul_f32_e32 v186, 0x4b800000, v182
	ds_bpermute_b32 v197, v208, v195
	ds_bpermute_b32 v196, v208, v194
	v_cndmask_b32_e32 v182, v182, v186, vcc
	v_rsq_f32_e32 v182, v182
	s_waitcnt lgkmcnt(0)
	v_pk_add_f32 v[194:195], v[194:195], v[196:197]
	v_mul_f32_e32 v186, 0x45800000, v182
	v_pk_fma_f32 v[194:195], v[194:195], s[28:29], v[200:201] op_sel_hi:[1,0,0]
	v_cndmask_b32_e32 v192, v182, v186, vcc
	v_mul_f32_e32 v182, 0x4b800000, v195
	v_cmp_gt_f32_e64 s[4:5], s29, v195
	v_cmp_gt_f32_e32 vcc, s29, v194
	v_pk_mul_f32 v[142:143], v[142:143], v[192:193] op_sel_hi:[1,0]
	v_cndmask_b32_e64 v182, v195, v182, s[4:5]
	v_rsq_f32_e32 v182, v182
	v_mov_b32_e32 v195, v148
	v_mov_b32_e32 v148, v139
	v_mov_b32_e32 v139, v141
	v_mul_f32_e32 v186, 0x45800000, v182
	v_cndmask_b32_e64 v190, v182, v186, s[4:5]
	v_mul_f32_e32 v182, 0x4b800000, v194
	v_cndmask_b32_e32 v182, v194, v182, vcc
	v_mov_b32_e32 v194, v147
	v_mov_b32_e32 v147, v149
	v_mov_b32_e32 v149, v140
	v_pk_add_f32 v[146:147], v[194:195], v[146:147]
	v_pk_add_f32 v[138:139], v[148:149], v[138:139]
	v_mov_b32_e32 v141, v146
	v_mov_b32_e32 v140, v138
	v_mov_b32_e32 v146, v139
	v_pk_add_f32 v[138:139], v[140:141], v[146:147]
	ds_bpermute_b32 v141, v207, v139
	ds_bpermute_b32 v140, v207, v138
	v_rsq_f32_e32 v182, v182
	v_pk_mul_f32 v[144:145], v[144:145], v[192:193] op_sel_hi:[1,0]
	v_pk_mul_f32 v[210:211], v[142:143], v[142:143]
	v_pk_mul_f32 v[196:197], v[144:145], v[144:145]
	s_waitcnt lgkmcnt(0)
	v_pk_add_f32 v[138:139], v[138:139], v[140:141]
	ds_bpermute_b32 v141, v208, v139
	ds_bpermute_b32 v140, v208, v138
	v_mul_f32_e32 v186, 0x45800000, v182
	v_cndmask_b32_e32 v186, v182, v186, vcc
	v_pk_mov_b32 v[212:213], v[210:211], v[196:197] op_sel:[1,0]
	v_mov_b32_e32 v211, v197
	s_waitcnt lgkmcnt(0)
	v_pk_add_f32 v[138:139], v[138:139], v[140:141]
	v_pk_mul_f32 v[130:131], v[130:131], v[192:193] op_sel_hi:[1,0]
	v_pk_fma_f32 v[138:139], v[138:139], s[28:29], v[200:201] op_sel_hi:[1,0,0]
	v_pk_mul_f32 v[132:133], v[132:133], v[192:193] op_sel_hi:[1,0]
	v_mul_f32_e32 v140, 0x4b800000, v139
	v_cmp_gt_f32_e64 s[4:5], s29, v139
	v_cmp_gt_f32_e32 vcc, s29, v138
	v_pk_add_f32 v[196:197], v[212:213], v[210:211]
	v_cndmask_b32_e64 v139, v139, v140, s[4:5]
	v_rsq_f32_e32 v139, v139
	v_pk_mul_f32 v[210:211], v[132:133], v[132:133]
	v_pk_mul_f32 v[212:213], v[130:131], v[130:131]
	v_pk_mul_f32 v[120:121], v[120:121], v[192:193] op_sel_hi:[1,0]
	v_mul_f32_e32 v140, 0x45800000, v139
	v_cndmask_b32_e64 v188, v139, v140, s[4:5]
	v_mul_f32_e32 v139, 0x4b800000, v138
	v_cndmask_b32_e32 v138, v138, v139, vcc
	v_rsq_f32_e32 v138, v138
	v_pk_mov_b32 v[214:215], v[212:213], v[210:211] op_sel:[1,0]
	v_mov_b32_e32 v213, v211
	v_pk_add_f32 v[210:211], v[214:215], v[212:213]
	v_mul_f32_e32 v139, 0x45800000, v138
	v_cndmask_b32_e32 v182, v138, v139, vcc
	v_mov_b32_e32 v138, v135
	v_mov_b32_e32 v139, v136
	v_mov_b32_e32 v135, v137
	v_mov_b32_e32 v136, v127
	v_mov_b32_e32 v137, v128
	v_mov_b32_e32 v127, v129
	v_pk_add_f32 v[134:135], v[138:139], v[134:135]
	v_pk_add_f32 v[126:127], v[136:137], v[126:127]
	v_mov_b32_e32 v129, v134
	v_mov_b32_e32 v128, v126
	v_mov_b32_e32 v134, v127
	v_pk_add_f32 v[126:127], v[128:129], v[134:135]
	ds_bpermute_b32 v129, v207, v127
	ds_bpermute_b32 v128, v207, v126
	v_pk_mul_f32 v[212:213], v[118:119], v[192:193] op_sel_hi:[1,0]
	v_pk_add_f32 v[196:197], v[196:197], v[196:197] op_sel_hi:[0,1]
	v_mul_f32_e32 v118, v212, v212
	v_pk_fma_f32 v[118:119], v[212:213], v[212:213], v[118:119] op_sel_hi:[1,1,0]
	s_waitcnt lgkmcnt(0)
	v_pk_add_f32 v[126:127], v[126:127], v[128:129]
	ds_bpermute_b32 v129, v208, v127
	ds_bpermute_b32 v128, v208, v126
	v_mul_f32_e32 v118, v120, v120
	v_pk_add_f32 v[210:211], v[210:211], v[210:211] op_sel_hi:[0,1]
	v_pk_fma_f32 v[214:215], v[120:121], v[120:121], v[118:119] op_sel_hi:[1,1,0]
	v_pk_mul_f32 v[216:217], v[116:117], v[192:193] op_sel_hi:[1,0]
	s_waitcnt lgkmcnt(0)
	v_pk_add_f32 v[126:127], v[126:127], v[128:129]
	v_pk_mul_f32 v[218:219], v[114:115], v[192:193] op_sel_hi:[1,0]
	v_pk_fma_f32 v[126:127], v[126:127], s[28:29], v[200:201] op_sel_hi:[1,0,0]
	v_mul_f32_e32 v118, v218, v218
	v_mul_f32_e32 v128, 0x4b800000, v127
	v_cmp_gt_f32_e64 s[4:5], s29, v127
	v_cmp_gt_f32_e32 vcc, s29, v126
	v_mul_f32_e32 v214, v219, v219
	v_cndmask_b32_e64 v127, v127, v128, s[4:5]
	v_rsq_f32_e32 v127, v127
	v_mul_f32_e32 v196, v216, v216
	v_mul_f32_e32 v210, v217, v217
	v_pk_add_f32 v[114:115], v[118:119], v[214:215]
	v_mul_f32_e32 v128, 0x45800000, v127
	v_cndmask_b32_e64 v148, v127, v128, s[4:5]
	v_mul_f32_e32 v127, 0x4b800000, v126
	v_cndmask_b32_e32 v126, v126, v127, vcc
	v_rsq_f32_e32 v126, v126
	v_pk_add_f32 v[116:117], v[196:197], v[210:211]
	v_readlane_b32 s4, v255, 6
	v_pk_add_f32 v[114:115], v[114:115], v[116:117]
	v_mul_f32_e32 v127, 0x45800000, v126
	v_cndmask_b32_e32 v146, v126, v127, vcc
	v_mov_b32_e32 v126, v123
	v_mov_b32_e32 v127, v124
	v_mov_b32_e32 v123, v125
	v_pk_add_f32 v[194:195], v[126:127], v[122:123]
	v_mov_b32_e32 v122, v97
	v_mov_b32_e32 v116, v114
	v_ashrrev_i32_e32 v123, 31, v122
	v_lshl_add_u64 v[134:135], v[122:123], 2, v[162:163]
	flat_load_dwordx4 v[122:125], v[134:135]
	flat_load_dwordx4 v[126:129], v[134:135] offset:16
	flat_load_dwordx4 v[138:141], v[134:135] offset:128
	s_nop 0
	flat_load_dwordx4 v[134:137], v[134:135] offset:144
	v_mov_b32_e32 v117, v194
	v_mov_b32_e32 v194, v115
	v_pk_add_f32 v[114:115], v[116:117], v[194:195]
	ds_bpermute_b32 v117, v207, v115
	ds_bpermute_b32 v116, v207, v114
	v_readlane_b32 s5, v255, 7
	s_mov_b32 s5, s28
	s_mov_b32 s2, s4
	v_pk_mul_f32 v[110:111], v[110:111], v[190:191] op_sel_hi:[1,0]
	s_waitcnt lgkmcnt(0)
	v_pk_add_f32 v[114:115], v[114:115], v[116:117]
	ds_bpermute_b32 v117, v208, v115
	ds_bpermute_b32 v116, v208, v114
	v_pk_mul_f32 v[112:113], v[112:113], v[190:191] op_sel_hi:[1,0]
	v_pk_mul_f32 v[106:107], v[106:107], v[190:191] op_sel_hi:[1,0]
	v_pk_mul_f32 v[108:109], v[108:109], v[190:191] op_sel_hi:[1,0]
	v_pk_mul_f32 v[102:103], v[102:103], v[190:191] op_sel_hi:[1,0]
	s_waitcnt lgkmcnt(0)
	v_pk_add_f32 v[114:115], v[114:115], v[116:117]
	v_pk_mul_f32 v[104:105], v[104:105], v[190:191] op_sel_hi:[1,0]
	v_pk_fma_f32 v[116:117], v[114:115], s[4:5], v[200:201] op_sel_hi:[1,1,0]
	v_pk_mul_f32 v[92:93], v[92:93], v[186:187] op_sel_hi:[1,0]
	v_mul_f32_e32 v114, 0x4b800000, v117
	v_cmp_gt_f32_e64 s[4:5], s29, v117
	v_cmp_gt_f32_e32 vcc, s29, v116
	v_pk_mul_f32 v[94:95], v[94:95], v[186:187] op_sel_hi:[1,0]
	v_cndmask_b32_e64 v114, v117, v114, s[4:5]
	v_rsq_f32_e32 v114, v114
	v_pk_mul_f32 v[88:89], v[88:89], v[186:187] op_sel_hi:[1,0]
	v_pk_mul_f32 v[90:91], v[90:91], v[186:187] op_sel_hi:[1,0]
	v_pk_mul_f32 v[84:85], v[84:85], v[186:187] op_sel_hi:[1,0]
	v_mul_f32_e32 v115, 0x45800000, v114
	v_cndmask_b32_e64 v114, v114, v115, s[4:5]
	v_mul_f32_e32 v115, 0x4b800000, v116
	v_cndmask_b32_e32 v115, v116, v115, vcc
	v_rsq_f32_e32 v115, v115
	v_pk_mul_f32 v[86:87], v[86:87], v[186:187] op_sel_hi:[1,0]
	v_pk_mul_f32 v[76:77], v[76:77], v[188:189] op_sel_hi:[1,0]
	v_pk_mul_f32 v[78:79], v[78:79], v[188:189] op_sel_hi:[1,0]
	v_mul_f32_e32 v116, 0x45800000, v115
	v_cndmask_b32_e32 v115, v115, v116, vcc
	v_mul_f32_e32 v192, 0x3e38aa3b, v115
	v_pk_mul_f32 v[72:73], v[72:73], v[188:189] op_sel_hi:[1,0]
	v_pk_mul_f32 v[74:75], v[74:75], v[188:189] op_sel_hi:[1,0]
	v_pk_mul_f32 v[68:69], v[68:69], v[188:189] op_sel_hi:[1,0]
	v_pk_mul_f32 v[70:71], v[70:71], v[188:189] op_sel_hi:[1,0]
	v_pk_mul_f32 v[60:61], v[60:61], v[182:183] op_sel_hi:[1,0]
	v_pk_mul_f32 v[62:63], v[62:63], v[182:183] op_sel_hi:[1,0]
	v_pk_mul_f32 v[56:57], v[56:57], v[182:183] op_sel_hi:[1,0]
	v_pk_mul_f32 v[58:59], v[58:59], v[182:183] op_sel_hi:[1,0]
	v_pk_mul_f32 v[52:53], v[52:53], v[182:183] op_sel_hi:[1,0]
	v_pk_mul_f32 v[54:55], v[54:55], v[182:183] op_sel_hi:[1,0]
	v_pk_mul_f32 v[44:45], v[44:45], v[148:149] op_sel_hi:[1,0]
	v_pk_mul_f32 v[46:47], v[46:47], v[148:149] op_sel_hi:[1,0]
	v_pk_mul_f32 v[40:41], v[40:41], v[148:149] op_sel_hi:[1,0]
	v_pk_mul_f32 v[42:43], v[42:43], v[148:149] op_sel_hi:[1,0]
	v_pk_mul_f32 v[36:37], v[36:37], v[148:149] op_sel_hi:[1,0]
	v_pk_mul_f32 v[38:39], v[38:39], v[148:149] op_sel_hi:[1,0]
	v_pk_mul_f32 v[28:29], v[28:29], v[146:147] op_sel_hi:[1,0]
	v_pk_mul_f32 v[30:31], v[30:31], v[146:147] op_sel_hi:[1,0]
	v_pk_mul_f32 v[24:25], v[24:25], v[146:147] op_sel_hi:[1,0]
	v_pk_mul_f32 v[26:27], v[26:27], v[146:147] op_sel_hi:[1,0]
	v_pk_mul_f32 v[20:21], v[20:21], v[146:147] op_sel_hi:[1,0]
	v_pk_mul_f32 v[22:23], v[22:23], v[146:147] op_sel_hi:[1,0]
	v_pk_mul_f32 v[12:13], v[12:13], v[114:115] op_sel_hi:[1,0]
	v_pk_mul_f32 v[14:15], v[14:15], v[114:115] op_sel_hi:[1,0]
	v_pk_mul_f32 v[8:9], v[8:9], v[114:115] op_sel_hi:[1,0]
	v_pk_mul_f32 v[10:11], v[10:11], v[114:115] op_sel_hi:[1,0]
	v_pk_mul_f32 v[4:5], v[4:5], v[114:115] op_sel_hi:[1,0]
	v_pk_mul_f32 v[6:7], v[6:7], v[114:115] op_sel_hi:[1,0]
	v_writelane_b32 v255, s2, 6
	s_mov_b64 s[4:5], -1
	s_waitcnt vmcnt(0)
	v_pk_mul_f32 v[116:117], v[142:143], v[122:123]
	v_pk_mul_f32 v[118:119], v[144:145], v[124:125]
	v_pk_mul_f32 v[130:131], v[130:131], v[126:127]
	v_pk_mul_f32 v[118:119], v[118:119], v[192:193] op_sel_hi:[1,0]
	v_pk_mul_f32 v[116:117], v[116:117], v[192:193] op_sel_hi:[1,0]
	v_pk_mul_f32 v[132:133], v[132:133], v[128:129]
	v_pk_mul_f32 v[130:131], v[130:131], v[192:193] op_sel_hi:[1,0]
	v_pk_mul_f32 v[132:133], v[132:133], v[192:193] op_sel_hi:[1,0]
	v_cvt_pk_bf16_f32 v116, v116, v117
	v_cvt_pk_bf16_f32 v117, v118, v119
	v_cvt_pk_bf16_f32 v118, v130, v131
	v_lshl_add_u64 v[130:131], v[152:153], 0, v[184:185]
	v_cvt_pk_bf16_f32 v119, v132, v133
	global_store_dwordx4 v[130:131], v[116:119], off
	v_pk_mul_f32 v[132:133], v[216:217], v[136:137]
	v_pk_mul_f32 v[142:143], v[98:99], v[190:191] op_sel_hi:[1,0]
	v_pk_mul_f32 v[116:117], v[212:213], v[138:139]
	v_pk_mul_f32 v[118:119], v[120:121], v[140:141]
	v_pk_mul_f32 v[116:117], v[116:117], v[192:193] op_sel_hi:[1,0]
	v_pk_mul_f32 v[118:119], v[118:119], v[192:193] op_sel_hi:[1,0]
	v_pk_mul_f32 v[120:121], v[218:219], v[134:135]
	v_pk_mul_f32 v[132:133], v[132:133], v[192:193] op_sel_hi:[1,0]
	v_pk_mul_f32 v[120:121], v[120:121], v[192:193] op_sel_hi:[1,0]
	v_cvt_pk_bf16_f32 v116, v116, v117
	v_cvt_pk_bf16_f32 v117, v118, v119
	v_writelane_b32 v255, s3, 7
	v_cvt_pk_bf16_f32 v118, v120, v121
	v_cvt_pk_bf16_f32 v119, v132, v133
	global_store_dwordx4 v[130:131], v[116:119], off offset:64
	v_pk_mul_f32 v[132:133], v[100:101], v[190:191] op_sel_hi:[1,0]
	s_nop 0
	v_pk_mul_f32 v[116:117], v[112:113], v[112:113]
	v_pk_mul_f32 v[118:119], v[110:111], v[110:111]
	s_nop 0
	v_pk_mov_b32 v[120:121], v[118:119], v[116:117] op_sel:[1,0]
	v_mov_b32_e32 v119, v117
	v_pk_add_f32 v[116:117], v[120:121], v[118:119]
	v_pk_mul_f32 v[118:119], v[108:109], v[108:109]
	v_pk_add_f32 v[116:117], v[116:117], v[116:117] op_sel_hi:[0,1]
	v_pk_mul_f32 v[120:121], v[106:107], v[106:107]
	v_mul_f32_e32 v116, v102, v102
	v_pk_mov_b32 v[130:131], v[120:121], v[118:119] op_sel:[1,0]
	v_mov_b32_e32 v121, v119
	v_pk_add_f32 v[118:119], v[130:131], v[120:121]
	v_pk_fma_f32 v[120:121], v[102:103], v[102:103], v[116:117] op_sel_hi:[1,1,0]
	v_mul_f32_e32 v116, v104, v104
	v_pk_add_f32 v[118:119], v[118:119], v[118:119] op_sel_hi:[0,1]
	v_pk_fma_f32 v[130:131], v[104:105], v[104:105], v[116:117] op_sel_hi:[1,1,0]
	v_mul_f32_e32 v120, v142, v142
	v_mul_f32_e32 v130, v143, v143
	v_mul_f32_e32 v116, v132, v132
	v_mul_f32_e32 v118, v133, v133
	v_pk_add_f32 v[98:99], v[120:121], v[130:131]
	v_pk_add_f32 v[100:101], v[116:117], v[118:119]
	v_pk_mul_f32 v[106:107], v[106:107], v[126:127]
	v_pk_add_f32 v[98:99], v[98:99], v[100:101]
	v_pk_mul_f32 v[100:101], v[112:113], v[124:125]
	v_add_f32_e32 v98, v98, v99
	ds_bpermute_b32 v99, v207, v98
	v_lshlrev_b64 v[118:119], 9, v[180:181]
	v_pk_mul_f32 v[108:109], v[108:109], v[128:129]
	s_waitcnt lgkmcnt(0)
	v_add_f32_e32 v98, v98, v99
	ds_bpermute_b32 v99, v208, v98
	s_waitcnt lgkmcnt(0)
	v_add_f32_e32 v98, v98, v99
	v_fmamk_f32 v98, v98, 0x3c800000, v247
	v_cmp_gt_f32_e32 vcc, s29, v98
	v_mul_f32_e32 v99, 0x4b800000, v98
	s_nop 0
	v_cndmask_b32_e32 v98, v98, v99, vcc
	v_rsq_f32_e32 v98, v98
	s_nop 0
	v_mul_f32_e32 v99, 0x45800000, v98
	v_cndmask_b32_e32 v98, v98, v99, vcc
	v_mul_f32_e32 v116, 0x3e38aa3b, v98
	v_pk_mul_f32 v[98:99], v[110:111], v[122:123]
	v_pk_mul_f32 v[100:101], v[100:101], v[116:117] op_sel_hi:[1,0]
	v_pk_mul_f32 v[98:99], v[98:99], v[116:117] op_sel_hi:[1,0]
	v_pk_mul_f32 v[106:107], v[106:107], v[116:117] op_sel_hi:[1,0]
	v_pk_mul_f32 v[108:109], v[108:109], v[116:117] op_sel_hi:[1,0]
	v_cvt_pk_bf16_f32 v98, v98, v99
	v_cvt_pk_bf16_f32 v99, v100, v101
	v_cvt_pk_bf16_f32 v100, v106, v107
	v_lshl_add_u64 v[106:107], v[152:153], 0, v[118:119]
	v_cvt_pk_bf16_f32 v101, v108, v109
	global_store_dwordx4 v[106:107], v[98:101], off
	v_pk_mul_f32 v[108:109], v[80:81], v[186:187] op_sel_hi:[1,0]
	s_nop 0
	v_pk_mul_f32 v[98:99], v[102:103], v[138:139]
	v_pk_mul_f32 v[100:101], v[104:105], v[140:141]
	v_pk_mul_f32 v[98:99], v[98:99], v[116:117] op_sel_hi:[1,0]
	v_pk_mul_f32 v[100:101], v[100:101], v[116:117] op_sel_hi:[1,0]
	v_pk_mul_f32 v[102:103], v[142:143], v[134:135]
	v_pk_mul_f32 v[104:105], v[132:133], v[136:137]
	v_pk_mul_f32 v[102:103], v[102:103], v[116:117] op_sel_hi:[1,0]
	v_pk_mul_f32 v[104:105], v[104:105], v[116:117] op_sel_hi:[1,0]
	v_cvt_pk_bf16_f32 v98, v98, v99
	v_cvt_pk_bf16_f32 v99, v100, v101
	v_cvt_pk_bf16_f32 v100, v102, v103
	s_nop 0
	v_cvt_pk_bf16_f32 v101, v104, v105
	global_store_dwordx4 v[106:107], v[98:101], off offset:64
	v_pk_mul_f32 v[106:107], v[82:83], v[186:187] op_sel_hi:[1,0]
	s_nop 0
	v_pk_mul_f32 v[98:99], v[94:95], v[94:95]
	v_pk_mul_f32 v[100:101], v[92:93], v[92:93]
	s_nop 0
	v_pk_mov_b32 v[102:103], v[100:101], v[98:99] op_sel:[1,0]
	v_mov_b32_e32 v101, v99
	v_pk_add_f32 v[98:99], v[102:103], v[100:101]
	v_pk_mul_f32 v[100:101], v[90:91], v[90:91]
	v_pk_add_f32 v[98:99], v[98:99], v[98:99] op_sel_hi:[0,1]
	v_pk_mul_f32 v[102:103], v[88:89], v[88:89]
	v_mul_f32_e32 v98, v84, v84
	v_pk_mov_b32 v[104:105], v[102:103], v[100:101] op_sel:[1,0]
	v_mov_b32_e32 v103, v101
	v_pk_add_f32 v[100:101], v[104:105], v[102:103]
	v_pk_fma_f32 v[102:103], v[84:85], v[84:85], v[98:99] op_sel_hi:[1,1,0]
	v_mul_f32_e32 v98, v86, v86
	v_pk_add_f32 v[100:101], v[100:101], v[100:101] op_sel_hi:[0,1]
	v_pk_fma_f32 v[104:105], v[86:87], v[86:87], v[98:99] op_sel_hi:[1,1,0]
	v_mul_f32_e32 v102, v108, v108
	v_mul_f32_e32 v104, v109, v109
	v_mul_f32_e32 v98, v106, v106
	v_mul_f32_e32 v100, v107, v107
	v_pk_add_f32 v[80:81], v[102:103], v[104:105]
	v_pk_add_f32 v[82:83], v[98:99], v[100:101]
	v_pk_mul_f32 v[88:89], v[88:89], v[126:127]
	v_pk_add_f32 v[80:81], v[80:81], v[82:83]
	v_pk_mul_f32 v[82:83], v[124:125], v[94:95]
	v_add_f32_e32 v80, v80, v81
	ds_bpermute_b32 v81, v207, v80
	v_lshlrev_b64 v[100:101], 9, v[178:179]
	v_pk_mul_f32 v[90:91], v[90:91], v[128:129]
	s_waitcnt lgkmcnt(0)
	v_add_f32_e32 v80, v80, v81
	ds_bpermute_b32 v81, v208, v80
	s_waitcnt lgkmcnt(0)
	v_add_f32_e32 v80, v80, v81
	v_fmamk_f32 v80, v80, 0x3c800000, v247
	v_cmp_gt_f32_e32 vcc, s29, v80
	v_mul_f32_e32 v81, 0x4b800000, v80
	s_nop 0
	v_cndmask_b32_e32 v80, v80, v81, vcc
	v_rsq_f32_e32 v80, v80
	s_nop 0
	v_mul_f32_e32 v81, 0x45800000, v80
	v_cndmask_b32_e32 v80, v80, v81, vcc
	v_mul_f32_e32 v98, 0x3e38aa3b, v80
	v_pk_mul_f32 v[80:81], v[122:123], v[92:93]
	v_pk_mul_f32 v[82:83], v[82:83], v[98:99] op_sel_hi:[1,0]
	v_pk_mul_f32 v[80:81], v[80:81], v[98:99] op_sel_hi:[1,0]
	v_pk_mul_f32 v[88:89], v[88:89], v[98:99] op_sel_hi:[1,0]
	v_pk_mul_f32 v[90:91], v[90:91], v[98:99] op_sel_hi:[1,0]
	v_cvt_pk_bf16_f32 v80, v80, v81
	v_cvt_pk_bf16_f32 v81, v82, v83
	v_cvt_pk_bf16_f32 v82, v88, v89
	v_lshl_add_u64 v[88:89], v[152:153], 0, v[100:101]
	v_cvt_pk_bf16_f32 v83, v90, v91
	global_store_dwordx4 v[88:89], v[80:83], off
	v_pk_mul_f32 v[90:91], v[64:65], v[188:189] op_sel_hi:[1,0]
	s_nop 0
	v_pk_mul_f32 v[80:81], v[84:85], v[138:139]
	v_pk_mul_f32 v[82:83], v[86:87], v[140:141]
	v_pk_mul_f32 v[80:81], v[80:81], v[98:99] op_sel_hi:[1,0]
	v_pk_mul_f32 v[82:83], v[82:83], v[98:99] op_sel_hi:[1,0]
	v_pk_mul_f32 v[84:85], v[108:109], v[134:135]
	v_pk_mul_f32 v[86:87], v[106:107], v[136:137]
	v_pk_mul_f32 v[84:85], v[84:85], v[98:99] op_sel_hi:[1,0]
	v_pk_mul_f32 v[86:87], v[86:87], v[98:99] op_sel_hi:[1,0]
	v_cvt_pk_bf16_f32 v80, v80, v81
	v_cvt_pk_bf16_f32 v81, v82, v83
	v_cvt_pk_bf16_f32 v82, v84, v85
	s_nop 0
	v_cvt_pk_bf16_f32 v83, v86, v87
	global_store_dwordx4 v[88:89], v[80:83], off offset:64
	v_pk_mul_f32 v[88:89], v[66:67], v[188:189] op_sel_hi:[1,0]
	s_nop 0
	v_pk_mul_f32 v[80:81], v[78:79], v[78:79]
	v_pk_mul_f32 v[82:83], v[76:77], v[76:77]
	s_nop 0
	v_pk_mov_b32 v[84:85], v[82:83], v[80:81] op_sel:[1,0]
	v_mov_b32_e32 v83, v81
	v_pk_add_f32 v[80:81], v[84:85], v[82:83]
	v_pk_mul_f32 v[82:83], v[74:75], v[74:75]
	v_pk_add_f32 v[80:81], v[80:81], v[80:81] op_sel_hi:[0,1]
	v_pk_mul_f32 v[84:85], v[72:73], v[72:73]
	v_mul_f32_e32 v80, v68, v68
	v_pk_mov_b32 v[86:87], v[84:85], v[82:83] op_sel:[1,0]
	v_mov_b32_e32 v85, v83
	v_pk_add_f32 v[82:83], v[86:87], v[84:85]
	v_pk_fma_f32 v[84:85], v[68:69], v[68:69], v[80:81] op_sel_hi:[1,1,0]
	v_mul_f32_e32 v80, v70, v70
	v_pk_add_f32 v[82:83], v[82:83], v[82:83] op_sel_hi:[0,1]
	v_pk_fma_f32 v[86:87], v[70:71], v[70:71], v[80:81] op_sel_hi:[1,1,0]
	v_mul_f32_e32 v84, v90, v90
	v_mul_f32_e32 v86, v91, v91
	v_mul_f32_e32 v80, v88, v88
	v_mul_f32_e32 v82, v89, v89
	v_pk_add_f32 v[64:65], v[84:85], v[86:87]
	v_pk_add_f32 v[66:67], v[80:81], v[82:83]
	v_pk_mul_f32 v[72:73], v[126:127], v[72:73]
	v_pk_add_f32 v[64:65], v[64:65], v[66:67]
	v_pk_mul_f32 v[66:67], v[124:125], v[78:79]
	v_add_f32_e32 v64, v64, v65
	ds_bpermute_b32 v65, v207, v64
	v_lshlrev_b64 v[82:83], 9, v[176:177]
	v_pk_mul_f32 v[74:75], v[128:129], v[74:75]
	s_waitcnt lgkmcnt(0)
	v_add_f32_e32 v64, v64, v65
	ds_bpermute_b32 v65, v208, v64
	s_waitcnt lgkmcnt(0)
	v_add_f32_e32 v64, v64, v65
	v_fmamk_f32 v64, v64, 0x3c800000, v247
	v_cmp_gt_f32_e32 vcc, s29, v64
	v_mul_f32_e32 v65, 0x4b800000, v64
	s_nop 0
	v_cndmask_b32_e32 v64, v64, v65, vcc
	v_rsq_f32_e32 v64, v64
	s_nop 0
	v_mul_f32_e32 v65, 0x45800000, v64
	v_cndmask_b32_e32 v64, v64, v65, vcc
	v_mul_f32_e32 v80, 0x3e38aa3b, v64
	v_pk_mul_f32 v[64:65], v[122:123], v[76:77]
	v_pk_mul_f32 v[66:67], v[66:67], v[80:81] op_sel_hi:[1,0]
	v_pk_mul_f32 v[64:65], v[64:65], v[80:81] op_sel_hi:[1,0]
	v_pk_mul_f32 v[72:73], v[72:73], v[80:81] op_sel_hi:[1,0]
	v_pk_mul_f32 v[74:75], v[74:75], v[80:81] op_sel_hi:[1,0]
	v_cvt_pk_bf16_f32 v64, v64, v65
	v_cvt_pk_bf16_f32 v65, v66, v67
	v_cvt_pk_bf16_f32 v66, v72, v73
	v_lshl_add_u64 v[72:73], v[152:153], 0, v[82:83]
	v_cvt_pk_bf16_f32 v67, v74, v75
	global_store_dwordx4 v[72:73], v[64:67], off
	v_pk_mul_f32 v[74:75], v[48:49], v[182:183] op_sel_hi:[1,0]
	s_nop 0
	v_pk_mul_f32 v[64:65], v[138:139], v[68:69]
	v_pk_mul_f32 v[66:67], v[140:141], v[70:71]
	v_pk_mul_f32 v[64:65], v[64:65], v[80:81] op_sel_hi:[1,0]
	v_pk_mul_f32 v[66:67], v[66:67], v[80:81] op_sel_hi:[1,0]
	v_pk_mul_f32 v[68:69], v[90:91], v[134:135]
	v_pk_mul_f32 v[70:71], v[88:89], v[136:137]
	v_pk_mul_f32 v[68:69], v[68:69], v[80:81] op_sel_hi:[1,0]
	v_pk_mul_f32 v[70:71], v[70:71], v[80:81] op_sel_hi:[1,0]
	v_cvt_pk_bf16_f32 v64, v64, v65
	v_cvt_pk_bf16_f32 v65, v66, v67
	v_cvt_pk_bf16_f32 v66, v68, v69
	s_nop 0
	v_cvt_pk_bf16_f32 v67, v70, v71
	global_store_dwordx4 v[72:73], v[64:67], off offset:64
	v_pk_mul_f32 v[72:73], v[50:51], v[182:183] op_sel_hi:[1,0]
	s_nop 0
	v_pk_mul_f32 v[64:65], v[62:63], v[62:63]
	v_pk_mul_f32 v[66:67], v[60:61], v[60:61]
	s_nop 0
	v_pk_mov_b32 v[68:69], v[66:67], v[64:65] op_sel:[1,0]
	v_mov_b32_e32 v67, v65
	v_pk_add_f32 v[64:65], v[68:69], v[66:67]
	v_pk_mul_f32 v[66:67], v[58:59], v[58:59]
	v_pk_add_f32 v[64:65], v[64:65], v[64:65] op_sel_hi:[0,1]
	v_pk_mul_f32 v[68:69], v[56:57], v[56:57]
	v_mul_f32_e32 v64, v52, v52
	v_pk_mov_b32 v[70:71], v[68:69], v[66:67] op_sel:[1,0]
	v_mov_b32_e32 v69, v67
	v_pk_add_f32 v[66:67], v[70:71], v[68:69]
	v_pk_fma_f32 v[68:69], v[52:53], v[52:53], v[64:65] op_sel_hi:[1,1,0]
	v_mul_f32_e32 v64, v54, v54
	v_pk_add_f32 v[66:67], v[66:67], v[66:67] op_sel_hi:[0,1]
	v_pk_fma_f32 v[70:71], v[54:55], v[54:55], v[64:65] op_sel_hi:[1,1,0]
	v_mul_f32_e32 v68, v74, v74
	v_mul_f32_e32 v70, v75, v75
	v_mul_f32_e32 v64, v72, v72
	v_mul_f32_e32 v66, v73, v73
	v_pk_add_f32 v[48:49], v[68:69], v[70:71]
	v_pk_add_f32 v[50:51], v[64:65], v[66:67]
	v_pk_mul_f32 v[56:57], v[126:127], v[56:57]
	v_pk_add_f32 v[48:49], v[48:49], v[50:51]
	v_pk_mul_f32 v[50:51], v[124:125], v[62:63]
	v_add_f32_e32 v48, v48, v49
	ds_bpermute_b32 v49, v207, v48
	v_lshlrev_b64 v[66:67], 9, v[174:175]
	v_pk_mul_f32 v[58:59], v[128:129], v[58:59]
	s_waitcnt lgkmcnt(0)
	v_add_f32_e32 v48, v48, v49
	ds_bpermute_b32 v49, v208, v48
	s_waitcnt lgkmcnt(0)
	v_add_f32_e32 v48, v48, v49
	v_fmamk_f32 v48, v48, 0x3c800000, v247
	v_cmp_gt_f32_e32 vcc, s29, v48
	v_mul_f32_e32 v49, 0x4b800000, v48
	s_nop 0
	v_cndmask_b32_e32 v48, v48, v49, vcc
	v_rsq_f32_e32 v48, v48
	s_nop 0
	v_mul_f32_e32 v49, 0x45800000, v48
	v_cndmask_b32_e32 v48, v48, v49, vcc
	v_mul_f32_e32 v64, 0x3e38aa3b, v48
	v_pk_mul_f32 v[48:49], v[122:123], v[60:61]
	v_pk_mul_f32 v[50:51], v[50:51], v[64:65] op_sel_hi:[1,0]
	v_pk_mul_f32 v[48:49], v[48:49], v[64:65] op_sel_hi:[1,0]
	v_pk_mul_f32 v[56:57], v[56:57], v[64:65] op_sel_hi:[1,0]
	v_pk_mul_f32 v[58:59], v[58:59], v[64:65] op_sel_hi:[1,0]
	v_cvt_pk_bf16_f32 v48, v48, v49
	v_cvt_pk_bf16_f32 v49, v50, v51
	v_cvt_pk_bf16_f32 v50, v56, v57
	v_lshl_add_u64 v[56:57], v[152:153], 0, v[66:67]
	v_cvt_pk_bf16_f32 v51, v58, v59
	global_store_dwordx4 v[56:57], v[48:51], off
	v_pk_mul_f32 v[58:59], v[32:33], v[148:149] op_sel_hi:[1,0]
	s_nop 0
	v_pk_mul_f32 v[48:49], v[138:139], v[52:53]
	v_pk_mul_f32 v[50:51], v[140:141], v[54:55]
	v_pk_mul_f32 v[48:49], v[48:49], v[64:65] op_sel_hi:[1,0]
	v_pk_mul_f32 v[50:51], v[50:51], v[64:65] op_sel_hi:[1,0]
	v_pk_mul_f32 v[52:53], v[134:135], v[74:75]
	v_pk_mul_f32 v[54:55], v[136:137], v[72:73]
	v_pk_mul_f32 v[52:53], v[52:53], v[64:65] op_sel_hi:[1,0]
	v_pk_mul_f32 v[54:55], v[54:55], v[64:65] op_sel_hi:[1,0]
	v_cvt_pk_bf16_f32 v48, v48, v49
	v_cvt_pk_bf16_f32 v49, v50, v51
	v_cvt_pk_bf16_f32 v50, v52, v53
	s_nop 0
	v_cvt_pk_bf16_f32 v51, v54, v55
	global_store_dwordx4 v[56:57], v[48:51], off offset:64
	v_pk_mul_f32 v[56:57], v[34:35], v[148:149] op_sel_hi:[1,0]
	s_nop 0
	v_pk_mul_f32 v[48:49], v[46:47], v[46:47]
	v_pk_mul_f32 v[50:51], v[44:45], v[44:45]
	s_nop 0
	v_pk_mov_b32 v[52:53], v[50:51], v[48:49] op_sel:[1,0]
	v_mov_b32_e32 v51, v49
	v_pk_add_f32 v[48:49], v[52:53], v[50:51]
	v_pk_mul_f32 v[50:51], v[42:43], v[42:43]
	v_pk_add_f32 v[48:49], v[48:49], v[48:49] op_sel_hi:[0,1]
	v_pk_mul_f32 v[52:53], v[40:41], v[40:41]
	v_mul_f32_e32 v48, v36, v36
	v_pk_mov_b32 v[54:55], v[52:53], v[50:51] op_sel:[1,0]
	v_mov_b32_e32 v53, v51
	v_pk_add_f32 v[50:51], v[54:55], v[52:53]
	v_pk_fma_f32 v[52:53], v[36:37], v[36:37], v[48:49] op_sel_hi:[1,1,0]
	v_mul_f32_e32 v48, v38, v38
	v_pk_add_f32 v[50:51], v[50:51], v[50:51] op_sel_hi:[0,1]
	v_pk_fma_f32 v[54:55], v[38:39], v[38:39], v[48:49] op_sel_hi:[1,1,0]
	v_mul_f32_e32 v52, v58, v58
	v_mul_f32_e32 v54, v59, v59
	v_mul_f32_e32 v48, v56, v56
	v_mul_f32_e32 v50, v57, v57
	v_pk_add_f32 v[32:33], v[52:53], v[54:55]
	v_pk_add_f32 v[34:35], v[48:49], v[50:51]
	v_pk_mul_f32 v[40:41], v[126:127], v[40:41]
	v_pk_add_f32 v[32:33], v[32:33], v[34:35]
	v_pk_mul_f32 v[34:35], v[124:125], v[46:47]
	v_add_f32_e32 v32, v32, v33
	ds_bpermute_b32 v33, v207, v32
	v_lshlrev_b64 v[50:51], 9, v[172:173]
	v_pk_mul_f32 v[42:43], v[128:129], v[42:43]
	s_waitcnt lgkmcnt(0)
	v_add_f32_e32 v32, v32, v33
	ds_bpermute_b32 v33, v208, v32
	s_waitcnt lgkmcnt(0)
	v_add_f32_e32 v32, v32, v33
	v_fmamk_f32 v32, v32, 0x3c800000, v247
	v_cmp_gt_f32_e32 vcc, s29, v32
	v_mul_f32_e32 v33, 0x4b800000, v32
	s_nop 0
	v_cndmask_b32_e32 v32, v32, v33, vcc
	v_rsq_f32_e32 v32, v32
	s_nop 0
	v_mul_f32_e32 v33, 0x45800000, v32
	v_cndmask_b32_e32 v32, v32, v33, vcc
	v_mul_f32_e32 v48, 0x3e38aa3b, v32
	v_pk_mul_f32 v[32:33], v[122:123], v[44:45]
	v_pk_mul_f32 v[34:35], v[34:35], v[48:49] op_sel_hi:[1,0]
	v_pk_mul_f32 v[32:33], v[32:33], v[48:49] op_sel_hi:[1,0]
	v_pk_mul_f32 v[40:41], v[40:41], v[48:49] op_sel_hi:[1,0]
	v_pk_mul_f32 v[42:43], v[42:43], v[48:49] op_sel_hi:[1,0]
	v_cvt_pk_bf16_f32 v32, v32, v33
	v_cvt_pk_bf16_f32 v33, v34, v35
	v_cvt_pk_bf16_f32 v34, v40, v41
	v_lshl_add_u64 v[40:41], v[152:153], 0, v[50:51]
	v_cvt_pk_bf16_f32 v35, v42, v43
	global_store_dwordx4 v[40:41], v[32:35], off
	v_pk_mul_f32 v[42:43], v[16:17], v[146:147] op_sel_hi:[1,0]
	s_nop 0
	v_pk_mul_f32 v[32:33], v[138:139], v[36:37]
	v_pk_mul_f32 v[34:35], v[140:141], v[38:39]
	v_pk_mul_f32 v[32:33], v[32:33], v[48:49] op_sel_hi:[1,0]
	v_pk_mul_f32 v[34:35], v[34:35], v[48:49] op_sel_hi:[1,0]
	v_pk_mul_f32 v[36:37], v[134:135], v[58:59]
	v_pk_mul_f32 v[38:39], v[136:137], v[56:57]
	v_pk_mul_f32 v[36:37], v[36:37], v[48:49] op_sel_hi:[1,0]
	v_pk_mul_f32 v[38:39], v[38:39], v[48:49] op_sel_hi:[1,0]
	v_cvt_pk_bf16_f32 v32, v32, v33
	v_cvt_pk_bf16_f32 v33, v34, v35
	v_cvt_pk_bf16_f32 v34, v36, v37
	s_nop 0
	v_cvt_pk_bf16_f32 v35, v38, v39
	global_store_dwordx4 v[40:41], v[32:35], off offset:64
	v_pk_mul_f32 v[40:41], v[18:19], v[146:147] op_sel_hi:[1,0]
	s_nop 0
	v_pk_mul_f32 v[32:33], v[30:31], v[30:31]
	v_pk_mul_f32 v[34:35], v[28:29], v[28:29]
	s_nop 0
	v_pk_mov_b32 v[36:37], v[34:35], v[32:33] op_sel:[1,0]
	v_mov_b32_e32 v35, v33
	v_pk_add_f32 v[32:33], v[36:37], v[34:35]
	v_pk_mul_f32 v[34:35], v[26:27], v[26:27]
	v_pk_add_f32 v[32:33], v[32:33], v[32:33] op_sel_hi:[0,1]
	v_pk_mul_f32 v[36:37], v[24:25], v[24:25]
	v_mul_f32_e32 v32, v20, v20
	v_pk_mov_b32 v[38:39], v[36:37], v[34:35] op_sel:[1,0]
	v_mov_b32_e32 v37, v35
	v_pk_add_f32 v[34:35], v[38:39], v[36:37]
	v_pk_fma_f32 v[36:37], v[20:21], v[20:21], v[32:33] op_sel_hi:[1,1,0]
	v_mul_f32_e32 v32, v22, v22
	v_pk_add_f32 v[34:35], v[34:35], v[34:35] op_sel_hi:[0,1]
	v_pk_fma_f32 v[38:39], v[22:23], v[22:23], v[32:33] op_sel_hi:[1,1,0]
	v_mul_f32_e32 v36, v42, v42
	v_mul_f32_e32 v38, v43, v43
	v_mul_f32_e32 v32, v40, v40
	v_mul_f32_e32 v34, v41, v41
	v_pk_add_f32 v[16:17], v[36:37], v[38:39]
	v_pk_add_f32 v[18:19], v[32:33], v[34:35]
	v_pk_mul_f32 v[24:25], v[126:127], v[24:25]
	v_pk_add_f32 v[16:17], v[16:17], v[18:19]
	v_pk_mul_f32 v[18:19], v[124:125], v[30:31]
	v_add_f32_e32 v16, v16, v17
	ds_bpermute_b32 v17, v207, v16
	v_lshlrev_b64 v[34:35], 9, v[170:171]
	v_pk_mul_f32 v[26:27], v[128:129], v[26:27]
	s_waitcnt lgkmcnt(0)
	v_add_f32_e32 v16, v16, v17
	ds_bpermute_b32 v17, v208, v16
	s_waitcnt lgkmcnt(0)
	v_add_f32_e32 v16, v16, v17
	v_fmamk_f32 v16, v16, 0x3c800000, v247
	v_cmp_gt_f32_e32 vcc, s29, v16
	v_mul_f32_e32 v17, 0x4b800000, v16
	s_nop 0
	v_cndmask_b32_e32 v16, v16, v17, vcc
	v_rsq_f32_e32 v16, v16
	s_nop 0
	v_mul_f32_e32 v17, 0x45800000, v16
	v_cndmask_b32_e32 v16, v16, v17, vcc
	v_mul_f32_e32 v32, 0x3e38aa3b, v16
	v_pk_mul_f32 v[16:17], v[122:123], v[28:29]
	v_pk_mul_f32 v[18:19], v[18:19], v[32:33] op_sel_hi:[1,0]
	v_pk_mul_f32 v[16:17], v[16:17], v[32:33] op_sel_hi:[1,0]
	v_pk_mul_f32 v[24:25], v[24:25], v[32:33] op_sel_hi:[1,0]
	v_pk_mul_f32 v[26:27], v[26:27], v[32:33] op_sel_hi:[1,0]
	v_cvt_pk_bf16_f32 v16, v16, v17
	v_cvt_pk_bf16_f32 v17, v18, v19
	v_cvt_pk_bf16_f32 v18, v24, v25
	v_lshl_add_u64 v[24:25], v[152:153], 0, v[34:35]
	v_cvt_pk_bf16_f32 v19, v26, v27
	global_store_dwordx4 v[24:25], v[16:19], off
	v_pk_mul_f32 v[26:27], v[0:1], v[114:115] op_sel_hi:[1,0]
	s_nop 0
	v_pk_mul_f32 v[16:17], v[138:139], v[20:21]
	v_pk_mul_f32 v[18:19], v[140:141], v[22:23]
	v_pk_mul_f32 v[16:17], v[16:17], v[32:33] op_sel_hi:[1,0]
	v_pk_mul_f32 v[18:19], v[18:19], v[32:33] op_sel_hi:[1,0]
	v_pk_mul_f32 v[20:21], v[134:135], v[42:43]
	v_pk_mul_f32 v[22:23], v[136:137], v[40:41]
	v_pk_mul_f32 v[20:21], v[20:21], v[32:33] op_sel_hi:[1,0]
	v_pk_mul_f32 v[22:23], v[22:23], v[32:33] op_sel_hi:[1,0]
	v_cvt_pk_bf16_f32 v16, v16, v17
	v_cvt_pk_bf16_f32 v17, v18, v19
	v_cvt_pk_bf16_f32 v18, v20, v21
	s_nop 0
	v_cvt_pk_bf16_f32 v19, v22, v23
	global_store_dwordx4 v[24:25], v[16:19], off offset:64
	v_pk_mul_f32 v[24:25], v[2:3], v[114:115] op_sel_hi:[1,0]
	s_nop 0
	v_pk_mul_f32 v[16:17], v[14:15], v[14:15]
	v_pk_mul_f32 v[18:19], v[12:13], v[12:13]
	s_nop 0
	v_pk_mov_b32 v[20:21], v[18:19], v[16:17] op_sel:[1,0]
	v_mov_b32_e32 v19, v17
	v_pk_add_f32 v[16:17], v[20:21], v[18:19]
	v_pk_mul_f32 v[18:19], v[10:11], v[10:11]
	v_pk_add_f32 v[16:17], v[16:17], v[16:17] op_sel_hi:[0,1]
	v_pk_mul_f32 v[20:21], v[8:9], v[8:9]
	v_mul_f32_e32 v16, v4, v4
	v_pk_mov_b32 v[22:23], v[20:21], v[18:19] op_sel:[1,0]
	v_mov_b32_e32 v21, v19
	v_pk_add_f32 v[18:19], v[22:23], v[20:21]
	v_pk_fma_f32 v[20:21], v[4:5], v[4:5], v[16:17] op_sel_hi:[1,1,0]
	v_mul_f32_e32 v16, v6, v6
	v_pk_add_f32 v[18:19], v[18:19], v[18:19] op_sel_hi:[0,1]
	v_pk_fma_f32 v[22:23], v[6:7], v[6:7], v[16:17] op_sel_hi:[1,1,0]
	v_mul_f32_e32 v20, v26, v26
	v_mul_f32_e32 v22, v27, v27
	v_mul_f32_e32 v16, v24, v24
	v_mul_f32_e32 v18, v25, v25
	v_pk_add_f32 v[0:1], v[20:21], v[22:23]
	v_pk_add_f32 v[2:3], v[16:17], v[18:19]
	v_pk_mul_f32 v[8:9], v[126:127], v[8:9]
	v_pk_add_f32 v[0:1], v[0:1], v[2:3]
	v_pk_mul_f32 v[2:3], v[124:125], v[14:15]
	v_add_f32_e32 v0, v0, v1
	ds_bpermute_b32 v1, v207, v0
	v_lshlrev_b64 v[18:19], 9, v[168:169]
	v_pk_mul_f32 v[10:11], v[128:129], v[10:11]
	s_waitcnt lgkmcnt(0)
	v_add_f32_e32 v0, v0, v1
	ds_bpermute_b32 v1, v208, v0
	s_waitcnt lgkmcnt(0)
	v_add_f32_e32 v0, v0, v1
	v_fmamk_f32 v0, v0, 0x3c800000, v247
	v_cmp_gt_f32_e32 vcc, s29, v0
	v_mul_f32_e32 v1, 0x4b800000, v0
	s_nop 0
	v_cndmask_b32_e32 v0, v0, v1, vcc
	v_rsq_f32_e32 v0, v0
	s_nop 0
	v_mul_f32_e32 v1, 0x45800000, v0
	v_cndmask_b32_e32 v0, v0, v1, vcc
	v_mul_f32_e32 v16, 0x3e38aa3b, v0
	v_pk_mul_f32 v[0:1], v[122:123], v[12:13]
	v_pk_mul_f32 v[2:3], v[2:3], v[16:17] op_sel_hi:[1,0]
	v_pk_mul_f32 v[0:1], v[0:1], v[16:17] op_sel_hi:[1,0]
	v_pk_mul_f32 v[8:9], v[8:9], v[16:17] op_sel_hi:[1,0]
	v_pk_mul_f32 v[10:11], v[10:11], v[16:17] op_sel_hi:[1,0]
	v_cvt_pk_bf16_f32 v0, v0, v1
	v_cvt_pk_bf16_f32 v1, v2, v3
	v_cvt_pk_bf16_f32 v2, v8, v9
	v_lshl_add_u64 v[8:9], v[152:153], 0, v[18:19]
	v_cvt_pk_bf16_f32 v3, v10, v11
	global_store_dwordx4 v[8:9], v[0:3], off
	s_andn2_b64 vcc, exec, s[0:1]
	s_nop 0
	v_pk_mul_f32 v[0:1], v[138:139], v[4:5]
	v_pk_mul_f32 v[2:3], v[140:141], v[6:7]
	v_pk_mul_f32 v[0:1], v[0:1], v[16:17] op_sel_hi:[1,0]
	v_pk_mul_f32 v[2:3], v[2:3], v[16:17] op_sel_hi:[1,0]
	v_pk_mul_f32 v[4:5], v[134:135], v[26:27]
	v_pk_mul_f32 v[6:7], v[136:137], v[24:25]
	v_pk_mul_f32 v[4:5], v[4:5], v[16:17] op_sel_hi:[1,0]
	v_pk_mul_f32 v[6:7], v[6:7], v[16:17] op_sel_hi:[1,0]
	v_cvt_pk_bf16_f32 v0, v0, v1
	v_cvt_pk_bf16_f32 v1, v2, v3
	v_cvt_pk_bf16_f32 v2, v4, v5
	s_nop 0
	v_cvt_pk_bf16_f32 v3, v6, v7
	global_store_dwordx4 v[8:9], v[0:3], off offset:64
	s_cbranch_vccnz .LBB0_171
	s_andn2_b64 vcc, exec, s[76:77]
	s_cbranch_vccnz .LBB0_170
	s_barrier
	s_branch .LBB0_170

.LBB0_204:
	s_add_u32 s2, s82, 0xfffc0080
	s_addc_u32 s14, s83, -1
	s_add_i32 s15, 0, 0x10000
	s_cmp_eq_u32 s63, 12
	s_cselect_b32 s27, s1, s14
	s_cselect_b32 s26, s7, s2
	s_cselect_b32 s25, s8, s62
	s_cselect_b32 s24, s18, s19
	s_add_i32 s2, 0, 0x14000
	v_add_u32_e32 v142, s15, v179
	v_add_u32_e32 v172, s2, v179
	ds_read_b128 v[126:129], v142
	ds_read_b128 v[130:133], v142 offset:1024
	ds_read_b128 v[134:137], v142 offset:2048
	ds_read_b128 v[142:145], v142 offset:3072
	ds_read_b128 v[146:149], v172
	ds_read_b128 v[150:153], v172 offset:1024
	ds_read_b128 v[174:177], v172 offset:2048
	ds_read_b128 v[182:185], v172 offset:3072
	v_lshl_add_u64 v[194:195], s[82:83], 0, v[170:171]
	s_add_i32 m0, s47, 0xc000
	ds_read_b128 v[186:189], v181
	ds_read_b128 v[190:193], v181 offset:1024
	ds_read_b128 v[200:203], v181 offset:2048
	ds_read_b128 v[204:207], v181 offset:3072
	ds_read_b128 v[208:211], v181 offset:4096
	ds_read_b128 v[212:215], v181 offset:5120
	ds_read_b128 v[216:219], v181 offset:6144
	ds_read_b128 v[220:223], v181 offset:7168
	global_load_lds_dwordx4 v[194:195], off
	v_lshl_add_u64 v[194:195], s[82:83], 0, v[168:169]
	s_add_i32 m0, s47, 0xe000
	s_nop 0
	global_load_lds_dwordx4 v[194:195], off
	s_waitcnt vmcnt(8)
	s_waitcnt lgkmcnt(0)
	s_barrier
	s_setprio 1
	s_waitcnt lgkmcnt(0)
	v_mfma_f32_16x16x32_bf16 v[138:141], v[126:129], v[186:189], v[138:141]
	v_mfma_f32_16x16x32_bf16 v[122:125], v[134:137], v[186:189], v[122:125]
	v_mfma_f32_16x16x32_bf16 v[110:113], v[126:129], v[200:203], v[110:113]
	v_mfma_f32_16x16x32_bf16 v[106:109], v[134:137], v[200:203], v[106:109]
	v_mfma_f32_16x16x32_bf16 v[92:95], v[126:129], v[208:211], v[92:95]
	v_mfma_f32_16x16x32_bf16 v[88:91], v[134:137], v[208:211], v[88:91]
	v_mfma_f32_16x16x32_bf16 v[76:79], v[126:129], v[216:219], v[76:79]
	v_mfma_f32_16x16x32_bf16 v[72:75], v[134:137], v[216:219], v[72:75]
	v_mfma_f32_16x16x32_bf16 v[138:141], v[130:133], v[190:193], v[138:141]
	v_mfma_f32_16x16x32_bf16 v[122:125], v[142:145], v[190:193], v[122:125]
	v_mfma_f32_16x16x32_bf16 v[110:113], v[130:133], v[204:207], v[110:113]
	v_mfma_f32_16x16x32_bf16 v[106:109], v[142:145], v[204:207], v[106:109]
	v_mfma_f32_16x16x32_bf16 v[92:95], v[130:133], v[212:215], v[92:95]
	v_mfma_f32_16x16x32_bf16 v[88:91], v[142:145], v[212:215], v[88:91]
	v_mfma_f32_16x16x32_bf16 v[76:79], v[130:133], v[220:223], v[76:79]
	v_mfma_f32_16x16x32_bf16 v[72:75], v[142:145], v[220:223], v[72:75]
	s_setprio 0
	s_setprio 1
	v_mfma_f32_16x16x32_bf16 v[118:121], v[146:149], v[186:189], v[118:121]
	v_mfma_f32_16x16x32_bf16 v[114:117], v[174:177], v[186:189], v[114:117]
	v_mfma_f32_16x16x32_bf16 v[102:105], v[146:149], v[200:203], v[102:105]
	v_mfma_f32_16x16x32_bf16 v[98:101], v[174:177], v[200:203], v[98:101]
	v_mfma_f32_16x16x32_bf16 v[84:87], v[146:149], v[208:211], v[84:87]
	v_mfma_f32_16x16x32_bf16 v[80:83], v[174:177], v[208:211], v[80:83]
	v_mfma_f32_16x16x32_bf16 v[68:71], v[146:149], v[216:219], v[68:71]
	v_mfma_f32_16x16x32_bf16 v[64:67], v[174:177], v[216:219], v[64:67]
	v_mfma_f32_16x16x32_bf16 v[118:121], v[150:153], v[190:193], v[118:121]
	v_mfma_f32_16x16x32_bf16 v[114:117], v[182:185], v[190:193], v[114:117]
	v_mfma_f32_16x16x32_bf16 v[102:105], v[150:153], v[204:207], v[102:105]
	v_mfma_f32_16x16x32_bf16 v[98:101], v[182:185], v[204:207], v[98:101]
	v_mfma_f32_16x16x32_bf16 v[84:87], v[150:153], v[212:215], v[84:87]
	v_mfma_f32_16x16x32_bf16 v[80:83], v[182:185], v[212:215], v[80:83]
	v_mfma_f32_16x16x32_bf16 v[68:71], v[150:153], v[220:223], v[68:71]
	v_mfma_f32_16x16x32_bf16 v[64:67], v[182:185], v[220:223], v[64:67]
	s_setprio 0
	s_barrier
	s_add_i32 s14, s15, s42
	v_lshl_add_u64 v[194:195], s[24:25], 0, v[154:155]
	s_mov_b32 m0, s14
	ds_read_b128 v[186:189], v181 offset:16384
	ds_read_b128 v[190:193], v181 offset:17408
	ds_read_b128 v[200:203], v181 offset:18432
	ds_read_b128 v[204:207], v181 offset:19456
	ds_read_b128 v[208:211], v181 offset:20480
	ds_read_b128 v[212:215], v181 offset:21504
	ds_read_b128 v[216:219], v181 offset:22528
	ds_read_b128 v[220:223], v181 offset:23552
	global_load_lds_dwordx4 v[194:195], off
	s_add_i32 m0, s14, 0x2000
	s_add_u32 s14, s24, 0x40000
	v_lshl_add_u64 v[196:197], s[24:25], 0, v[158:159]
	s_addc_u32 s15, s25, 0
	s_add_i32 s2, s2, s42
	global_load_lds_dwordx4 v[196:197], off
	v_lshl_add_u64 v[224:225], s[14:15], 0, v[154:155]
	s_mov_b32 m0, s2
	v_lshl_add_u64 v[226:227], s[26:27], 0, v[156:157]
	global_load_lds_dwordx4 v[224:225], off
	v_lshl_add_u64 v[224:225], s[14:15], 0, v[158:159]
	s_add_i32 m0, s2, 0x2000
	s_nop 0
	global_load_lds_dwordx4 v[224:225], off
	v_lshl_add_u64 v[224:225], s[26:27], 0, v[96:97]
	s_mov_b32 m0, s47
	s_nop 0
	global_load_lds_dwordx4 v[224:225], off
	s_mov_b32 m0, s59
	s_nop 0
	global_load_lds_dwordx4 v[226:227], off
	s_waitcnt vmcnt(8)
	s_waitcnt lgkmcnt(0)
	s_barrier
	s_setprio 1
	s_waitcnt lgkmcnt(0)
	v_mfma_f32_16x16x32_bf16 v[60:63], v[126:129], v[186:189], v[60:63]
	v_mfma_f32_16x16x32_bf16 v[56:59], v[134:137], v[186:189], v[56:59]
	v_mfma_f32_16x16x32_bf16 v[44:47], v[126:129], v[200:203], v[44:47]
	v_mfma_f32_16x16x32_bf16 v[40:43], v[134:137], v[200:203], v[40:43]
	v_mfma_f32_16x16x32_bf16 v[28:31], v[126:129], v[208:211], v[28:31]
	v_mfma_f32_16x16x32_bf16 v[24:27], v[134:137], v[208:211], v[24:27]
	v_mfma_f32_16x16x32_bf16 v[12:15], v[126:129], v[216:219], v[12:15]
	v_mfma_f32_16x16x32_bf16 v[8:11], v[134:137], v[216:219], v[8:11]
	v_mfma_f32_16x16x32_bf16 v[60:63], v[130:133], v[190:193], v[60:63]
	v_mfma_f32_16x16x32_bf16 v[56:59], v[142:145], v[190:193], v[56:59]
	v_mfma_f32_16x16x32_bf16 v[44:47], v[130:133], v[204:207], v[44:47]
	v_mfma_f32_16x16x32_bf16 v[40:43], v[142:145], v[204:207], v[40:43]
	v_mfma_f32_16x16x32_bf16 v[28:31], v[130:133], v[212:215], v[28:31]
	v_mfma_f32_16x16x32_bf16 v[24:27], v[142:145], v[212:215], v[24:27]
	v_mfma_f32_16x16x32_bf16 v[12:15], v[130:133], v[220:223], v[12:15]
	v_mfma_f32_16x16x32_bf16 v[8:11], v[142:145], v[220:223], v[8:11]
	s_setprio 0
	s_setprio 1
	v_mfma_f32_16x16x32_bf16 v[52:55], v[146:149], v[186:189], v[52:55]
	v_mfma_f32_16x16x32_bf16 v[48:51], v[174:177], v[186:189], v[48:51]
	v_mfma_f32_16x16x32_bf16 v[36:39], v[146:149], v[200:203], v[36:39]
	v_mfma_f32_16x16x32_bf16 v[32:35], v[174:177], v[200:203], v[32:35]
	v_mfma_f32_16x16x32_bf16 v[20:23], v[146:149], v[208:211], v[20:23]
	v_mfma_f32_16x16x32_bf16 v[16:19], v[174:177], v[208:211], v[16:19]
	v_mfma_f32_16x16x32_bf16 v[4:7], v[146:149], v[216:219], v[4:7]
	v_mfma_f32_16x16x32_bf16 v[0:3], v[174:177], v[216:219], v[0:3]
	v_mfma_f32_16x16x32_bf16 v[52:55], v[150:153], v[190:193], v[52:55]
	v_mfma_f32_16x16x32_bf16 v[48:51], v[182:185], v[190:193], v[48:51]
	v_mfma_f32_16x16x32_bf16 v[36:39], v[150:153], v[204:207], v[36:39]
	v_mfma_f32_16x16x32_bf16 v[32:35], v[182:185], v[204:207], v[32:35]
	v_mfma_f32_16x16x32_bf16 v[20:23], v[150:153], v[212:215], v[20:23]
	v_mfma_f32_16x16x32_bf16 v[16:19], v[182:185], v[212:215], v[16:19]
	v_mfma_f32_16x16x32_bf16 v[4:7], v[150:153], v[220:223], v[4:7]
	v_mfma_f32_16x16x32_bf16 v[0:3], v[182:185], v[220:223], v[0:3]
	s_setprio 0
	s_barrier
	s_add_i32 s2, 0, 0x18000
	s_add_i32 s20, 0, 0x1c000
	v_add_u32_e32 v142, s2, v179
	v_add_u32_e32 v172, s20, v179
	ds_read_b128 v[126:129], v142
	ds_read_b128 v[130:133], v142 offset:1024
	ds_read_b128 v[134:137], v142 offset:2048
	ds_read_b128 v[142:145], v142 offset:3072
	ds_read_b128 v[146:149], v172
	ds_read_b128 v[150:153], v172 offset:1024
	ds_read_b128 v[174:177], v172 offset:2048
	ds_read_b128 v[182:185], v172 offset:3072
	s_add_u32 s14, s26, 0x40000
	s_addc_u32 s15, s27, 0
	s_mov_b32 m0, s60
	v_lshl_add_u64 v[228:229], s[14:15], 0, v[96:97]
	ds_read_b128 v[186:189], v181 offset:32768
	ds_read_b128 v[190:193], v181 offset:33792
	ds_read_b128 v[200:203], v181 offset:34816
	ds_read_b128 v[204:207], v181 offset:35840
	ds_read_b128 v[208:211], v181 offset:36864
	ds_read_b128 v[212:215], v181 offset:37888
	ds_read_b128 v[216:219], v181 offset:38912
	ds_read_b128 v[220:223], v181 offset:39936
	global_load_lds_dwordx4 v[228:229], off
	v_lshl_add_u64 v[228:229], s[14:15], 0, v[156:157]
	s_mov_b32 m0, s61
	s_nop 0
	global_load_lds_dwordx4 v[228:229], off
	s_waitcnt vmcnt(8)
	s_waitcnt lgkmcnt(0)
	s_barrier
	s_setprio 1
	s_waitcnt lgkmcnt(0)
	v_mfma_f32_16x16x32_bf16 v[138:141], v[126:129], v[186:189], v[138:141]
	v_mfma_f32_16x16x32_bf16 v[122:125], v[134:137], v[186:189], v[122:125]
	v_mfma_f32_16x16x32_bf16 v[110:113], v[126:129], v[200:203], v[110:113]
	v_mfma_f32_16x16x32_bf16 v[106:109], v[134:137], v[200:203], v[106:109]
	v_mfma_f32_16x16x32_bf16 v[92:95], v[126:129], v[208:211], v[92:95]
	v_mfma_f32_16x16x32_bf16 v[88:91], v[134:137], v[208:211], v[88:91]
	v_mfma_f32_16x16x32_bf16 v[76:79], v[126:129], v[216:219], v[76:79]
	v_mfma_f32_16x16x32_bf16 v[72:75], v[134:137], v[216:219], v[72:75]
	v_mfma_f32_16x16x32_bf16 v[138:141], v[130:133], v[190:193], v[138:141]
	v_mfma_f32_16x16x32_bf16 v[122:125], v[142:145], v[190:193], v[122:125]
	v_mfma_f32_16x16x32_bf16 v[110:113], v[130:133], v[204:207], v[110:113]
	v_mfma_f32_16x16x32_bf16 v[106:109], v[142:145], v[204:207], v[106:109]
	v_mfma_f32_16x16x32_bf16 v[92:95], v[130:133], v[212:215], v[92:95]
	v_mfma_f32_16x16x32_bf16 v[88:91], v[142:145], v[212:215], v[88:91]
	v_mfma_f32_16x16x32_bf16 v[76:79], v[130:133], v[220:223], v[76:79]
	v_mfma_f32_16x16x32_bf16 v[72:75], v[142:145], v[220:223], v[72:75]
	s_setprio 0
	s_setprio 1
	v_mfma_f32_16x16x32_bf16 v[118:121], v[146:149], v[186:189], v[118:121]
	v_mfma_f32_16x16x32_bf16 v[114:117], v[174:177], v[186:189], v[114:117]
	v_mfma_f32_16x16x32_bf16 v[102:105], v[146:149], v[200:203], v[102:105]
	v_mfma_f32_16x16x32_bf16 v[98:101], v[174:177], v[200:203], v[98:101]
	v_mfma_f32_16x16x32_bf16 v[84:87], v[146:149], v[208:211], v[84:87]
	v_mfma_f32_16x16x32_bf16 v[80:83], v[174:177], v[208:211], v[80:83]
	v_mfma_f32_16x16x32_bf16 v[68:71], v[146:149], v[216:219], v[68:71]
	v_mfma_f32_16x16x32_bf16 v[64:67], v[174:177], v[216:219], v[64:67]
	v_mfma_f32_16x16x32_bf16 v[118:121], v[150:153], v[190:193], v[118:121]
	v_mfma_f32_16x16x32_bf16 v[114:117], v[182:185], v[190:193], v[114:117]
	v_mfma_f32_16x16x32_bf16 v[102:105], v[150:153], v[204:207], v[102:105]
	v_mfma_f32_16x16x32_bf16 v[98:101], v[182:185], v[204:207], v[98:101]
	v_mfma_f32_16x16x32_bf16 v[84:87], v[150:153], v[212:215], v[84:87]
	v_mfma_f32_16x16x32_bf16 v[80:83], v[182:185], v[212:215], v[80:83]
	v_mfma_f32_16x16x32_bf16 v[68:71], v[150:153], v[220:223], v[68:71]
	v_mfma_f32_16x16x32_bf16 v[64:67], v[182:185], v[220:223], v[64:67]
	s_setprio 0
	s_barrier
	s_add_i32 s2, s2, s42
	v_lshl_add_u64 v[194:195], v[194:195], 0, s[22:23]
	s_mov_b32 m0, s2
	ds_read_b128 v[186:189], v181 offset:49152
	ds_read_b128 v[190:193], v181 offset:50176
	ds_read_b128 v[200:203], v181 offset:51200
	ds_read_b128 v[204:207], v181 offset:52224
	ds_read_b128 v[208:211], v181 offset:53248
	ds_read_b128 v[212:215], v181 offset:54272
	ds_read_b128 v[216:219], v181 offset:55296
	ds_read_b128 v[220:223], v181 offset:56320
	global_load_lds_dwordx4 v[194:195], off
	s_add_i32 m0, s2, 0x2000
	s_add_u32 s14, s24, 0x40080
	v_lshl_add_u64 v[194:195], v[196:197], 0, s[22:23]
	s_addc_u32 s15, s25, 0
	s_add_i32 s2, s20, s42
	global_load_lds_dwordx4 v[194:195], off
	v_lshl_add_u64 v[194:195], s[14:15], 0, v[154:155]
	s_mov_b32 m0, s2
	s_nop 0
	global_load_lds_dwordx4 v[194:195], off
	v_lshl_add_u64 v[194:195], s[14:15], 0, v[158:159]
	s_add_i32 m0, s2, 0x2000
	s_nop 0
	global_load_lds_dwordx4 v[194:195], off
	v_lshl_add_u64 v[194:195], v[224:225], 0, s[22:23]
	s_mov_b32 m0, s86
	s_nop 0
	global_load_lds_dwordx4 v[194:195], off
	v_lshl_add_u64 v[194:195], v[226:227], 0, s[22:23]
	s_mov_b32 m0, s87
	s_nop 0
	global_load_lds_dwordx4 v[194:195], off
	s_waitcnt vmcnt(8)
	s_waitcnt lgkmcnt(0)
	s_barrier
	s_setprio 1
	s_waitcnt lgkmcnt(0)
	v_mfma_f32_16x16x32_bf16 v[60:63], v[126:129], v[186:189], v[60:63]
	v_mfma_f32_16x16x32_bf16 v[56:59], v[134:137], v[186:189], v[56:59]
	v_mfma_f32_16x16x32_bf16 v[44:47], v[126:129], v[200:203], v[44:47]
	v_mfma_f32_16x16x32_bf16 v[40:43], v[134:137], v[200:203], v[40:43]
	v_mfma_f32_16x16x32_bf16 v[28:31], v[126:129], v[208:211], v[28:31]
	v_mfma_f32_16x16x32_bf16 v[24:27], v[134:137], v[208:211], v[24:27]
	v_mfma_f32_16x16x32_bf16 v[12:15], v[126:129], v[216:219], v[12:15]
	v_mfma_f32_16x16x32_bf16 v[8:11], v[134:137], v[216:219], v[8:11]
	v_mfma_f32_16x16x32_bf16 v[60:63], v[130:133], v[190:193], v[60:63]
	v_mfma_f32_16x16x32_bf16 v[56:59], v[142:145], v[190:193], v[56:59]
	v_mfma_f32_16x16x32_bf16 v[44:47], v[130:133], v[204:207], v[44:47]
	v_mfma_f32_16x16x32_bf16 v[40:43], v[142:145], v[204:207], v[40:43]
	v_mfma_f32_16x16x32_bf16 v[28:31], v[130:133], v[212:215], v[28:31]
	v_mfma_f32_16x16x32_bf16 v[24:27], v[142:145], v[212:215], v[24:27]
	v_mfma_f32_16x16x32_bf16 v[12:15], v[130:133], v[220:223], v[12:15]
	v_mfma_f32_16x16x32_bf16 v[8:11], v[142:145], v[220:223], v[8:11]
	s_setprio 0
	s_setprio 1
	v_mfma_f32_16x16x32_bf16 v[52:55], v[146:149], v[186:189], v[52:55]
	v_mfma_f32_16x16x32_bf16 v[48:51], v[174:177], v[186:189], v[48:51]
	v_mfma_f32_16x16x32_bf16 v[36:39], v[146:149], v[200:203], v[36:39]
	v_mfma_f32_16x16x32_bf16 v[32:35], v[174:177], v[200:203], v[32:35]
	v_mfma_f32_16x16x32_bf16 v[20:23], v[146:149], v[208:211], v[20:23]
	v_mfma_f32_16x16x32_bf16 v[16:19], v[174:177], v[208:211], v[16:19]
	v_mfma_f32_16x16x32_bf16 v[4:7], v[146:149], v[216:219], v[4:7]
	v_mfma_f32_16x16x32_bf16 v[0:3], v[174:177], v[216:219], v[0:3]
	v_mfma_f32_16x16x32_bf16 v[52:55], v[150:153], v[190:193], v[52:55]
	v_mfma_f32_16x16x32_bf16 v[48:51], v[182:185], v[190:193], v[48:51]
	v_mfma_f32_16x16x32_bf16 v[36:39], v[150:153], v[204:207], v[36:39]
	v_mfma_f32_16x16x32_bf16 v[32:35], v[182:185], v[204:207], v[32:35]
	v_mfma_f32_16x16x32_bf16 v[20:23], v[150:153], v[212:215], v[20:23]
	v_mfma_f32_16x16x32_bf16 v[16:19], v[182:185], v[212:215], v[16:19]
	v_mfma_f32_16x16x32_bf16 v[4:7], v[150:153], v[220:223], v[4:7]
	v_mfma_f32_16x16x32_bf16 v[0:3], v[182:185], v[220:223], v[0:3]
	s_setprio 0
	s_barrier
	s_add_i32 s63, s63, 2
	s_add_u32 s19, s19, 0x100
	s_addc_u32 s62, s62, 0
	s_add_u32 s82, s82, 0x100
	s_addc_u32 s83, s83, 0
	s_cmp_gt_u32 s63, 13
	s_cbranch_scc0 .LBB0_204
	v_lshl_add_u32 v174, s0, 8, v173
	v_ashrrev_i32_e32 v175, 31, v174
	v_lshlrev_b64 v[126:127], 6, v[174:175]
	v_or_b32_e32 v176, 16, v174
	v_lshl_add_u64 v[126:127], v[166:167], 0, v[126:127]
	v_ashrrev_i32_e32 v177, 31, v176
	global_load_dwordx4 v[190:193], v[126:127], off
	v_lshlrev_b64 v[126:127], 6, v[176:177]
	v_lshl_add_u64 v[126:127], v[166:167], 0, v[126:127]
	global_load_dwordx4 v[210:213], v[126:127], off
	v_or_b32_e32 v182, 32, v174
	v_ashrrev_i32_e32 v183, 31, v182
	v_lshlrev_b64 v[126:127], 6, v[182:183]
	v_or_b32_e32 v188, 48, v174
	v_lshl_add_u64 v[126:127], v[166:167], 0, v[126:127]
	v_ashrrev_i32_e32 v189, 31, v188
	global_load_dwordx4 v[150:153], v[126:127], off
	v_lshlrev_b64 v[126:127], 6, v[188:189]
	v_lshl_add_u64 v[126:127], v[166:167], 0, v[126:127]
	global_load_dwordx4 v[146:149], v[126:127], off
	v_add_u32_e32 v202, 0x80, v174
	v_ashrrev_i32_e32 v203, 31, v202
	v_lshlrev_b64 v[126:127], 6, v[202:203]
	v_add_u32_e32 v204, 0x90, v174
	v_lshl_add_u64 v[126:127], v[166:167], 0, v[126:127]
	v_ashrrev_i32_e32 v205, 31, v204
	global_load_dwordx4 v[142:145], v[126:127], off
	v_lshlrev_b64 v[126:127], 6, v[204:205]
	v_lshl_add_u64 v[126:127], v[166:167], 0, v[126:127]
	global_load_dwordx4 v[134:137], v[126:127], off
	v_add_u32_e32 v206, 0xa0, v174
	v_ashrrev_i32_e32 v207, 31, v206
	v_lshlrev_b64 v[126:127], 6, v[206:207]
	v_add_u32_e32 v208, 0xb0, v174
	v_lshl_add_u64 v[126:127], v[166:167], 0, v[126:127]
	v_ashrrev_i32_e32 v209, 31, v208
	global_load_dwordx4 v[130:133], v[126:127], off
	v_lshlrev_b64 v[126:127], 6, v[208:209]
	v_lshl_add_u64 v[126:127], v[166:167], 0, v[126:127]
	global_load_dwordx4 v[126:129], v[126:127], off
	s_and_b64 vcc, exec, s[74:75]
	s_cbranch_vccz .LBB0_207
	s_barrier
.LBB0_207:
	v_and_b32_e32 v178, 64, v248
	v_xor_b32_e32 v172, 16, v248
	v_add_u32_e32 v178, 64, v178
	v_cmp_lt_i32_e32 vcc, v172, v178
	s_nop 1
	v_cndmask_b32_e32 v172, v248, v172, vcc
	v_lshlrev_b32_e32 v185, 2, v172
	v_xor_b32_e32 v172, 32, v248
	v_cmp_lt_i32_e32 vcc, v172, v178
	s_nop 1
	s_mov_b32 s0, 0x358637bd
	s_ashr_i32 s82, s6, 1
	v_cndmask_b32_e32 v172, v248, v172, vcc
	v_lshlrev_b32_e32 v187, 2, v172
	s_bitcmp1_b32 s6, 0
	s_cselect_b64 s[6:7], -1, 0
	s_ashr_i32 s83, s82, 31
	s_mov_b64 s[24:25], -1
	v_lshlrev_b64 v[188:189], 9, v[188:189]
	s_waitcnt vmcnt(0)
	v_mov_b32_e32 v194, v191
	v_mov_b32_e32 v195, v192
	v_mov_b32_e32 v191, v193
	v_mov_b32_e32 v192, v211
	v_mov_b32_e32 v193, v212
	v_mov_b32_e32 v211, v213
	v_pk_add_f32 v[190:191], v[194:195], v[190:191]
	v_pk_add_f32 v[192:193], v[192:193], v[210:211]
	v_mov_b32_e32 v195, v190
	v_mov_b32_e32 v194, v192
	v_mov_b32_e32 v190, v193
	v_pk_add_f32 v[190:191], v[194:195], v[190:191]
	ds_bpermute_b32 v193, v185, v191
	ds_bpermute_b32 v192, v185, v190
	v_lshlrev_b64 v[210:211], 9, v[174:175]
	v_lshlrev_b64 v[174:175], 9, v[204:205]
	s_waitcnt lgkmcnt(0)
	v_pk_add_f32 v[190:191], v[190:191], v[192:193]
	ds_bpermute_b32 v193, v187, v191
	ds_bpermute_b32 v192, v187, v190
	s_waitcnt lgkmcnt(0)
	v_pk_add_f32 v[192:193], v[190:191], v[192:193]
	v_mov_b64_e32 v[190:191], s[0:1]
	v_pk_fma_f32 v[192:193], v[192:193], s[28:29], v[190:191] op_sel_hi:[1,0,0]
	s_nop 0
	v_mul_f32_e32 v172, 0x4b800000, v193
	v_cmp_gt_f32_e64 s[0:1], s29, v193
	v_cmp_gt_f32_e32 vcc, s29, v192
	s_nop 0
	v_cndmask_b32_e64 v172, v193, v172, s[0:1]
	v_rsq_f32_e32 v172, v172
	v_mov_b32_e32 v193, v152
	v_mov_b32_e32 v152, v147
	v_mov_b32_e32 v147, v149
	v_mul_f32_e32 v178, 0x45800000, v172
	v_cndmask_b32_e64 v200, v172, v178, s[0:1]
	v_mul_f32_e32 v172, 0x4b800000, v192
	v_cndmask_b32_e32 v172, v192, v172, vcc
	v_mov_b32_e32 v192, v151
	v_mov_b32_e32 v151, v153
	v_mov_b32_e32 v153, v148
	v_pk_add_f32 v[150:151], v[192:193], v[150:151]
	v_pk_add_f32 v[146:147], v[152:153], v[146:147]
	v_mov_b32_e32 v149, v150
	v_mov_b32_e32 v148, v146
	v_mov_b32_e32 v150, v147
	v_pk_add_f32 v[146:147], v[148:149], v[150:151]
	ds_bpermute_b32 v149, v185, v147
	ds_bpermute_b32 v148, v185, v146
	v_rsq_f32_e32 v172, v172
	v_lshlrev_b64 v[192:193], 9, v[176:177]
	v_lshlrev_b64 v[150:151], 9, v[206:207]
	s_waitcnt lgkmcnt(0)
	v_pk_add_f32 v[146:147], v[146:147], v[148:149]
	ds_bpermute_b32 v149, v187, v147
	ds_bpermute_b32 v148, v187, v146
	v_mul_f32_e32 v178, 0x45800000, v172
	v_cndmask_b32_e32 v184, v172, v178, vcc
	s_waitcnt lgkmcnt(0)
	v_pk_add_f32 v[146:147], v[146:147], v[148:149]
	s_nop 0
	v_pk_fma_f32 v[146:147], v[146:147], s[28:29], v[190:191] op_sel_hi:[1,0,0]
	s_nop 0
	v_mul_f32_e32 v148, 0x4b800000, v147
	v_cmp_gt_f32_e64 s[0:1], s29, v147
	v_cmp_gt_f32_e32 vcc, s29, v146
	s_nop 0
	v_cndmask_b32_e64 v147, v147, v148, s[0:1]
	v_rsq_f32_e32 v147, v147
	s_nop 0
	v_mul_f32_e32 v148, 0x45800000, v147
	v_cndmask_b32_e64 v186, v147, v148, s[0:1]
	v_mul_f32_e32 v147, 0x4b800000, v146
	v_cndmask_b32_e32 v146, v146, v147, vcc
	v_rsq_f32_e32 v146, v146
	s_nop 0
	v_mul_f32_e32 v147, 0x45800000, v146
	v_cndmask_b32_e32 v178, v146, v147, vcc
	v_mov_b32_e32 v146, v143
	v_mov_b32_e32 v147, v144
	v_mov_b32_e32 v143, v145
	v_mov_b32_e32 v144, v135
	v_mov_b32_e32 v145, v136
	v_mov_b32_e32 v135, v137
	v_pk_add_f32 v[142:143], v[146:147], v[142:143]
	v_pk_add_f32 v[134:135], v[144:145], v[134:135]
	v_mov_b32_e32 v137, v142
	v_mov_b32_e32 v136, v134
	v_mov_b32_e32 v142, v135
	v_pk_add_f32 v[134:135], v[136:137], v[142:143]
	ds_bpermute_b32 v137, v185, v135
	ds_bpermute_b32 v136, v185, v134
	v_lshlrev_b64 v[146:147], 9, v[208:209]
	s_waitcnt lgkmcnt(0)
	v_pk_add_f32 v[134:135], v[134:135], v[136:137]
	ds_bpermute_b32 v137, v187, v135
	ds_bpermute_b32 v136, v187, v134
	s_waitcnt lgkmcnt(0)
	v_pk_add_f32 v[134:135], v[134:135], v[136:137]
	s_nop 0
	v_pk_fma_f32 v[134:135], v[134:135], s[28:29], v[190:191] op_sel_hi:[1,0,0]
	s_nop 0
	v_mul_f32_e32 v136, 0x4b800000, v135
	v_cmp_gt_f32_e64 s[0:1], s29, v135
	v_cmp_gt_f32_e32 vcc, s29, v134
	s_nop 0
	v_cndmask_b32_e64 v135, v135, v136, s[0:1]
	v_rsq_f32_e32 v135, v135
	s_nop 0
	v_mul_f32_e32 v136, 0x45800000, v135
	v_cndmask_b32_e64 v180, v135, v136, s[0:1]
	v_mul_f32_e32 v135, 0x4b800000, v134
	v_cndmask_b32_e32 v134, v134, v135, vcc
	v_rsq_f32_e32 v134, v134
	s_nop 0
	v_mul_f32_e32 v135, 0x45800000, v134
	v_cndmask_b32_e32 v172, v134, v135, vcc
	v_mov_b32_e32 v134, v131
	v_mov_b32_e32 v135, v132
	v_mov_b32_e32 v131, v133
	v_mov_b32_e32 v132, v127
	v_mov_b32_e32 v133, v128
	v_mov_b32_e32 v127, v129
	v_pk_add_f32 v[130:131], v[134:135], v[130:131]
	v_pk_add_f32 v[126:127], v[132:133], v[126:127]
	v_mov_b32_e32 v129, v130
	v_mov_b32_e32 v128, v126
	v_mov_b32_e32 v130, v127
	v_pk_add_f32 v[126:127], v[128:129], v[130:131]
	ds_bpermute_b32 v129, v185, v127
	ds_bpermute_b32 v128, v185, v126
	s_waitcnt lgkmcnt(0)
	v_pk_add_f32 v[126:127], v[126:127], v[128:129]
	ds_bpermute_b32 v129, v187, v127
	ds_bpermute_b32 v128, v187, v126
	s_waitcnt lgkmcnt(0)
	v_pk_add_f32 v[126:127], v[126:127], v[128:129]
	s_nop 0
	v_pk_fma_f32 v[126:127], v[126:127], s[28:29], v[190:191] op_sel_hi:[1,0,0]
	v_lshlrev_b64 v[190:191], 9, v[182:183]
	v_mul_f32_e32 v128, 0x4b800000, v127
	v_cmp_gt_f32_e64 s[0:1], s29, v127
	v_cmp_gt_f32_e32 vcc, s29, v126
	v_lshlrev_b64 v[182:183], 9, v[202:203]
	v_cndmask_b32_e64 v127, v127, v128, s[0:1]
	v_rsq_f32_e32 v127, v127
	s_nop 0
	v_mul_f32_e32 v128, 0x45800000, v127
	v_cndmask_b32_e64 v152, v127, v128, s[0:1]
	v_mul_f32_e32 v127, 0x4b800000, v126
	v_cndmask_b32_e32 v126, v126, v127, vcc
	v_rsq_f32_e32 v126, v126
	s_lshl_b64 s[0:1], s[82:83], 20
	v_mul_f32_e32 v127, 0x45800000, v126
	v_cndmask_b32_e32 v148, v126, v127, vcc
	s_and_b64 vcc, exec, s[6:7]
	s_cbranch_vccnz .LBB0_210
	s_andn2_b64 vcc, exec, s[24:25]
	s_cbranch_vccz .LBB0_211

.LBB0_236:
	s_add_u32 s2, s86, 0xfffc0080
	s_addc_u32 s14, s87, -1
	s_add_i32 s15, 0, 0x10000
	s_cmp_eq_u32 s71, 12
	s_cselect_b32 s27, s6, s14
	s_cselect_b32 s26, s7, s2
	s_cselect_b32 s25, s8, s69
	s_cselect_b32 s24, s16, s68
	s_add_i32 s2, 0, 0x14000
	v_add_u32_e32 v126, s15, v250
	v_add_u32_e32 v154, s2, v250
	ds_read_b128 v[114:117], v126
	ds_read_b128 v[118:121], v126 offset:1024
	ds_read_b128 v[122:125], v126 offset:2048
	ds_read_b128 v[126:129], v126 offset:3072
	ds_read_b128 v[138:141], v154
	ds_read_b128 v[142:145], v154 offset:1024
	ds_read_b128 v[146:149], v154 offset:2048
	ds_read_b128 v[154:157], v154 offset:3072
	v_lshl_add_u64 v[194:195], s[86:87], 0, v[208:209]
	s_add_i32 m0, s43, 0xc000
	ds_read_b128 v[162:165], v251
	ds_read_b128 v[166:169], v251 offset:1024
	ds_read_b128 v[170:173], v251 offset:2048
	ds_read_b128 v[174:177], v251 offset:3072
	ds_read_b128 v[178:181], v251 offset:4096
	ds_read_b128 v[182:185], v251 offset:5120
	ds_read_b128 v[186:189], v251 offset:6144
	ds_read_b128 v[190:193], v251 offset:7168
	global_load_lds_dwordx4 v[194:195], off
	v_lshl_add_u64 v[194:195], s[86:87], 0, v[206:207]
	s_add_i32 m0, s43, 0xe000
	s_nop 0
	global_load_lds_dwordx4 v[194:195], off
	s_waitcnt vmcnt(8)
	s_waitcnt lgkmcnt(0)
	s_barrier
	s_setprio 1
	s_waitcnt lgkmcnt(0)
	v_mfma_f32_16x16x32_bf16 v[158:161], v[114:117], v[162:165], v[158:161]
	v_mfma_f32_16x16x32_bf16 v[150:153], v[122:125], v[162:165], v[150:153]
	v_mfma_f32_16x16x32_bf16 v[110:113], v[114:117], v[170:173], v[110:113]
	v_mfma_f32_16x16x32_bf16 v[106:109], v[122:125], v[170:173], v[106:109]
	v_mfma_f32_16x16x32_bf16 v[92:95], v[114:117], v[178:181], v[92:95]
	v_mfma_f32_16x16x32_bf16 v[88:91], v[122:125], v[178:181], v[88:91]
	v_mfma_f32_16x16x32_bf16 v[76:79], v[114:117], v[186:189], v[76:79]
	v_mfma_f32_16x16x32_bf16 v[72:75], v[122:125], v[186:189], v[72:75]
	v_mfma_f32_16x16x32_bf16 v[158:161], v[118:121], v[166:169], v[158:161]
	v_mfma_f32_16x16x32_bf16 v[150:153], v[126:129], v[166:169], v[150:153]
	v_mfma_f32_16x16x32_bf16 v[110:113], v[118:121], v[174:177], v[110:113]
	v_mfma_f32_16x16x32_bf16 v[106:109], v[126:129], v[174:177], v[106:109]
	v_mfma_f32_16x16x32_bf16 v[92:95], v[118:121], v[182:185], v[92:95]
	v_mfma_f32_16x16x32_bf16 v[88:91], v[126:129], v[182:185], v[88:91]
	v_mfma_f32_16x16x32_bf16 v[76:79], v[118:121], v[190:193], v[76:79]
	v_mfma_f32_16x16x32_bf16 v[72:75], v[126:129], v[190:193], v[72:75]
	s_setprio 0
	s_setprio 1
	v_mfma_f32_16x16x32_bf16 v[134:137], v[138:141], v[162:165], v[134:137]
	v_mfma_f32_16x16x32_bf16 v[130:133], v[146:149], v[162:165], v[130:133]
	v_mfma_f32_16x16x32_bf16 v[102:105], v[138:141], v[170:173], v[102:105]
	v_mfma_f32_16x16x32_bf16 v[98:101], v[146:149], v[170:173], v[98:101]
	v_mfma_f32_16x16x32_bf16 v[84:87], v[138:141], v[178:181], v[84:87]
	v_mfma_f32_16x16x32_bf16 v[80:83], v[146:149], v[178:181], v[80:83]
	v_mfma_f32_16x16x32_bf16 v[68:71], v[138:141], v[186:189], v[68:71]
	v_mfma_f32_16x16x32_bf16 v[64:67], v[146:149], v[186:189], v[64:67]
	v_mfma_f32_16x16x32_bf16 v[134:137], v[142:145], v[166:169], v[134:137]
	v_mfma_f32_16x16x32_bf16 v[130:133], v[154:157], v[166:169], v[130:133]
	v_mfma_f32_16x16x32_bf16 v[102:105], v[142:145], v[174:177], v[102:105]
	v_mfma_f32_16x16x32_bf16 v[98:101], v[154:157], v[174:177], v[98:101]
	v_mfma_f32_16x16x32_bf16 v[84:87], v[142:145], v[182:185], v[84:87]
	v_mfma_f32_16x16x32_bf16 v[80:83], v[154:157], v[182:185], v[80:83]
	v_mfma_f32_16x16x32_bf16 v[68:71], v[142:145], v[190:193], v[68:71]
	v_mfma_f32_16x16x32_bf16 v[64:67], v[154:157], v[190:193], v[64:67]
	s_setprio 0
	s_barrier
	s_add_i32 s14, s15, s42
	v_lshl_add_u64 v[194:195], s[24:25], 0, v[96:97]
	s_mov_b32 m0, s14
	ds_read_b128 v[162:165], v251 offset:16384
	ds_read_b128 v[166:169], v251 offset:17408
	ds_read_b128 v[170:173], v251 offset:18432
	ds_read_b128 v[174:177], v251 offset:19456
	ds_read_b128 v[178:181], v251 offset:20480
	ds_read_b128 v[182:185], v251 offset:21504
	ds_read_b128 v[186:189], v251 offset:22528
	ds_read_b128 v[190:193], v251 offset:23552
	global_load_lds_dwordx4 v[194:195], off
	s_add_i32 m0, s14, 0x2000
	s_add_u32 s14, s24, 0x40000
	v_lshl_add_u64 v[196:197], s[24:25], 0, v[204:205]
	s_addc_u32 s15, s25, 0
	s_add_i32 s2, s2, s42
	global_load_lds_dwordx4 v[196:197], off
	v_lshl_add_u64 v[210:211], s[14:15], 0, v[96:97]
	s_mov_b32 m0, s2
	v_lshl_add_u64 v[212:213], s[26:27], 0, v[202:203]
	global_load_lds_dwordx4 v[210:211], off
	v_lshl_add_u64 v[210:211], s[14:15], 0, v[204:205]
	s_add_i32 m0, s2, 0x2000
	s_nop 0
	global_load_lds_dwordx4 v[210:211], off
	v_lshl_add_u64 v[210:211], s[26:27], 0, v[200:201]
	s_mov_b32 m0, s43
	s_nop 0
	global_load_lds_dwordx4 v[210:211], off
	s_mov_b32 m0, s45
	s_nop 0
	global_load_lds_dwordx4 v[212:213], off
	s_waitcnt vmcnt(8)
	s_waitcnt lgkmcnt(0)
	s_barrier
	s_setprio 1
	s_waitcnt lgkmcnt(0)
	v_mfma_f32_16x16x32_bf16 v[60:63], v[114:117], v[162:165], v[60:63]
	v_mfma_f32_16x16x32_bf16 v[56:59], v[122:125], v[162:165], v[56:59]
	v_mfma_f32_16x16x32_bf16 v[44:47], v[114:117], v[170:173], v[44:47]
	v_mfma_f32_16x16x32_bf16 v[40:43], v[122:125], v[170:173], v[40:43]
	v_mfma_f32_16x16x32_bf16 v[28:31], v[114:117], v[178:181], v[28:31]
	v_mfma_f32_16x16x32_bf16 v[24:27], v[122:125], v[178:181], v[24:27]
	v_mfma_f32_16x16x32_bf16 v[12:15], v[114:117], v[186:189], v[12:15]
	v_mfma_f32_16x16x32_bf16 v[8:11], v[122:125], v[186:189], v[8:11]
	v_mfma_f32_16x16x32_bf16 v[60:63], v[118:121], v[166:169], v[60:63]
	v_mfma_f32_16x16x32_bf16 v[56:59], v[126:129], v[166:169], v[56:59]
	v_mfma_f32_16x16x32_bf16 v[44:47], v[118:121], v[174:177], v[44:47]
	v_mfma_f32_16x16x32_bf16 v[40:43], v[126:129], v[174:177], v[40:43]
	v_mfma_f32_16x16x32_bf16 v[28:31], v[118:121], v[182:185], v[28:31]
	v_mfma_f32_16x16x32_bf16 v[24:27], v[126:129], v[182:185], v[24:27]
	v_mfma_f32_16x16x32_bf16 v[12:15], v[118:121], v[190:193], v[12:15]
	v_mfma_f32_16x16x32_bf16 v[8:11], v[126:129], v[190:193], v[8:11]
	s_setprio 0
	s_setprio 1
	v_mfma_f32_16x16x32_bf16 v[52:55], v[138:141], v[162:165], v[52:55]
	v_mfma_f32_16x16x32_bf16 v[48:51], v[146:149], v[162:165], v[48:51]
	v_mfma_f32_16x16x32_bf16 v[36:39], v[138:141], v[170:173], v[36:39]
	v_mfma_f32_16x16x32_bf16 v[32:35], v[146:149], v[170:173], v[32:35]
	v_mfma_f32_16x16x32_bf16 v[20:23], v[138:141], v[178:181], v[20:23]
	v_mfma_f32_16x16x32_bf16 v[16:19], v[146:149], v[178:181], v[16:19]
	v_mfma_f32_16x16x32_bf16 v[4:7], v[138:141], v[186:189], v[4:7]
	v_mfma_f32_16x16x32_bf16 v[0:3], v[146:149], v[186:189], v[0:3]
	v_mfma_f32_16x16x32_bf16 v[52:55], v[142:145], v[166:169], v[52:55]
	v_mfma_f32_16x16x32_bf16 v[48:51], v[154:157], v[166:169], v[48:51]
	v_mfma_f32_16x16x32_bf16 v[36:39], v[142:145], v[174:177], v[36:39]
	v_mfma_f32_16x16x32_bf16 v[32:35], v[154:157], v[174:177], v[32:35]
	v_mfma_f32_16x16x32_bf16 v[20:23], v[142:145], v[182:185], v[20:23]
	v_mfma_f32_16x16x32_bf16 v[16:19], v[154:157], v[182:185], v[16:19]
	v_mfma_f32_16x16x32_bf16 v[4:7], v[142:145], v[190:193], v[4:7]
	v_mfma_f32_16x16x32_bf16 v[0:3], v[154:157], v[190:193], v[0:3]
	s_setprio 0
	s_barrier
	s_add_i32 s2, 0, 0x18000
	s_add_i32 s20, 0, 0x1c000
	v_add_u32_e32 v126, s2, v250
	v_add_u32_e32 v154, s20, v250
	ds_read_b128 v[114:117], v126
	ds_read_b128 v[118:121], v126 offset:1024
	ds_read_b128 v[122:125], v126 offset:2048
	ds_read_b128 v[126:129], v126 offset:3072
	ds_read_b128 v[138:141], v154
	ds_read_b128 v[142:145], v154 offset:1024
	ds_read_b128 v[146:149], v154 offset:2048
	ds_read_b128 v[154:157], v154 offset:3072
	s_add_u32 s14, s26, 0x40000
	s_addc_u32 s15, s27, 0
	s_mov_b32 m0, s47
	v_lshl_add_u64 v[214:215], s[14:15], 0, v[200:201]
	ds_read_b128 v[162:165], v251 offset:32768
	ds_read_b128 v[166:169], v251 offset:33792
	ds_read_b128 v[170:173], v251 offset:34816
	ds_read_b128 v[174:177], v251 offset:35840
	ds_read_b128 v[178:181], v251 offset:36864
	ds_read_b128 v[182:185], v251 offset:37888
	ds_read_b128 v[186:189], v251 offset:38912
	ds_read_b128 v[190:193], v251 offset:39936
	global_load_lds_dwordx4 v[214:215], off
	v_lshl_add_u64 v[214:215], s[14:15], 0, v[202:203]
	s_mov_b32 m0, s59
	s_nop 0
	global_load_lds_dwordx4 v[214:215], off
	s_waitcnt vmcnt(8)
	s_waitcnt lgkmcnt(0)
	s_barrier
	s_setprio 1
	s_waitcnt lgkmcnt(0)
	v_mfma_f32_16x16x32_bf16 v[158:161], v[114:117], v[162:165], v[158:161]
	v_mfma_f32_16x16x32_bf16 v[150:153], v[122:125], v[162:165], v[150:153]
	v_mfma_f32_16x16x32_bf16 v[110:113], v[114:117], v[170:173], v[110:113]
	v_mfma_f32_16x16x32_bf16 v[106:109], v[122:125], v[170:173], v[106:109]
	v_mfma_f32_16x16x32_bf16 v[92:95], v[114:117], v[178:181], v[92:95]
	v_mfma_f32_16x16x32_bf16 v[88:91], v[122:125], v[178:181], v[88:91]
	v_mfma_f32_16x16x32_bf16 v[76:79], v[114:117], v[186:189], v[76:79]
	v_mfma_f32_16x16x32_bf16 v[72:75], v[122:125], v[186:189], v[72:75]
	v_mfma_f32_16x16x32_bf16 v[158:161], v[118:121], v[166:169], v[158:161]
	v_mfma_f32_16x16x32_bf16 v[150:153], v[126:129], v[166:169], v[150:153]
	v_mfma_f32_16x16x32_bf16 v[110:113], v[118:121], v[174:177], v[110:113]
	v_mfma_f32_16x16x32_bf16 v[106:109], v[126:129], v[174:177], v[106:109]
	v_mfma_f32_16x16x32_bf16 v[92:95], v[118:121], v[182:185], v[92:95]
	v_mfma_f32_16x16x32_bf16 v[88:91], v[126:129], v[182:185], v[88:91]
	v_mfma_f32_16x16x32_bf16 v[76:79], v[118:121], v[190:193], v[76:79]
	v_mfma_f32_16x16x32_bf16 v[72:75], v[126:129], v[190:193], v[72:75]
	s_setprio 0
	s_setprio 1
	v_mfma_f32_16x16x32_bf16 v[134:137], v[138:141], v[162:165], v[134:137]
	v_mfma_f32_16x16x32_bf16 v[130:133], v[146:149], v[162:165], v[130:133]
	v_mfma_f32_16x16x32_bf16 v[102:105], v[138:141], v[170:173], v[102:105]
	v_mfma_f32_16x16x32_bf16 v[98:101], v[146:149], v[170:173], v[98:101]
	v_mfma_f32_16x16x32_bf16 v[84:87], v[138:141], v[178:181], v[84:87]
	v_mfma_f32_16x16x32_bf16 v[80:83], v[146:149], v[178:181], v[80:83]
	v_mfma_f32_16x16x32_bf16 v[68:71], v[138:141], v[186:189], v[68:71]
	v_mfma_f32_16x16x32_bf16 v[64:67], v[146:149], v[186:189], v[64:67]
	v_mfma_f32_16x16x32_bf16 v[134:137], v[142:145], v[166:169], v[134:137]
	v_mfma_f32_16x16x32_bf16 v[130:133], v[154:157], v[166:169], v[130:133]
	v_mfma_f32_16x16x32_bf16 v[102:105], v[142:145], v[174:177], v[102:105]
	v_mfma_f32_16x16x32_bf16 v[98:101], v[154:157], v[174:177], v[98:101]
	v_mfma_f32_16x16x32_bf16 v[84:87], v[142:145], v[182:185], v[84:87]
	v_mfma_f32_16x16x32_bf16 v[80:83], v[154:157], v[182:185], v[80:83]
	v_mfma_f32_16x16x32_bf16 v[68:71], v[142:145], v[190:193], v[68:71]
	v_mfma_f32_16x16x32_bf16 v[64:67], v[154:157], v[190:193], v[64:67]
	s_setprio 0
	s_barrier
	s_add_i32 s2, s2, s42
	v_lshl_add_u64 v[194:195], v[194:195], 0, s[22:23]
	s_mov_b32 m0, s2
	ds_read_b128 v[162:165], v251 offset:49152
	ds_read_b128 v[166:169], v251 offset:50176
	ds_read_b128 v[170:173], v251 offset:51200
	ds_read_b128 v[174:177], v251 offset:52224
	ds_read_b128 v[178:181], v251 offset:53248
	ds_read_b128 v[182:185], v251 offset:54272
	ds_read_b128 v[186:189], v251 offset:55296
	ds_read_b128 v[190:193], v251 offset:56320
	global_load_lds_dwordx4 v[194:195], off
	s_add_i32 m0, s2, 0x2000
	s_add_u32 s14, s24, 0x40080
	v_lshl_add_u64 v[194:195], v[196:197], 0, s[22:23]
	s_addc_u32 s15, s25, 0
	s_add_i32 s2, s20, s42
	global_load_lds_dwordx4 v[194:195], off
	v_lshl_add_u64 v[194:195], s[14:15], 0, v[96:97]
	s_mov_b32 m0, s2
	s_nop 0
	global_load_lds_dwordx4 v[194:195], off
	v_lshl_add_u64 v[194:195], s[14:15], 0, v[204:205]
	s_add_i32 m0, s2, 0x2000
	s_nop 0
	global_load_lds_dwordx4 v[194:195], off
	v_lshl_add_u64 v[194:195], v[210:211], 0, s[22:23]
	s_mov_b32 m0, s18
	s_nop 0
	global_load_lds_dwordx4 v[194:195], off
	v_lshl_add_u64 v[194:195], v[212:213], 0, s[22:23]
	s_mov_b32 m0, s19
	s_nop 0
	global_load_lds_dwordx4 v[194:195], off
	s_waitcnt vmcnt(8)
	s_waitcnt lgkmcnt(0)
	s_barrier
	s_setprio 1
	s_waitcnt lgkmcnt(0)
	v_mfma_f32_16x16x32_bf16 v[60:63], v[114:117], v[162:165], v[60:63]
	v_mfma_f32_16x16x32_bf16 v[56:59], v[122:125], v[162:165], v[56:59]
	v_mfma_f32_16x16x32_bf16 v[44:47], v[114:117], v[170:173], v[44:47]
	v_mfma_f32_16x16x32_bf16 v[40:43], v[122:125], v[170:173], v[40:43]
	v_mfma_f32_16x16x32_bf16 v[28:31], v[114:117], v[178:181], v[28:31]
	v_mfma_f32_16x16x32_bf16 v[24:27], v[122:125], v[178:181], v[24:27]
	v_mfma_f32_16x16x32_bf16 v[12:15], v[114:117], v[186:189], v[12:15]
	v_mfma_f32_16x16x32_bf16 v[8:11], v[122:125], v[186:189], v[8:11]
	v_mfma_f32_16x16x32_bf16 v[60:63], v[118:121], v[166:169], v[60:63]
	v_mfma_f32_16x16x32_bf16 v[56:59], v[126:129], v[166:169], v[56:59]
	v_mfma_f32_16x16x32_bf16 v[44:47], v[118:121], v[174:177], v[44:47]
	v_mfma_f32_16x16x32_bf16 v[40:43], v[126:129], v[174:177], v[40:43]
	v_mfma_f32_16x16x32_bf16 v[28:31], v[118:121], v[182:185], v[28:31]
	v_mfma_f32_16x16x32_bf16 v[24:27], v[126:129], v[182:185], v[24:27]
	v_mfma_f32_16x16x32_bf16 v[12:15], v[118:121], v[190:193], v[12:15]
	v_mfma_f32_16x16x32_bf16 v[8:11], v[126:129], v[190:193], v[8:11]
	s_setprio 0
	s_setprio 1
	v_mfma_f32_16x16x32_bf16 v[52:55], v[138:141], v[162:165], v[52:55]
	v_mfma_f32_16x16x32_bf16 v[48:51], v[146:149], v[162:165], v[48:51]
	v_mfma_f32_16x16x32_bf16 v[36:39], v[138:141], v[170:173], v[36:39]
	v_mfma_f32_16x16x32_bf16 v[32:35], v[146:149], v[170:173], v[32:35]
	v_mfma_f32_16x16x32_bf16 v[20:23], v[138:141], v[178:181], v[20:23]
	v_mfma_f32_16x16x32_bf16 v[16:19], v[146:149], v[178:181], v[16:19]
	v_mfma_f32_16x16x32_bf16 v[4:7], v[138:141], v[186:189], v[4:7]
	v_mfma_f32_16x16x32_bf16 v[0:3], v[146:149], v[186:189], v[0:3]
	v_mfma_f32_16x16x32_bf16 v[52:55], v[142:145], v[166:169], v[52:55]
	v_mfma_f32_16x16x32_bf16 v[48:51], v[154:157], v[166:169], v[48:51]
	v_mfma_f32_16x16x32_bf16 v[36:39], v[142:145], v[174:177], v[36:39]
	v_mfma_f32_16x16x32_bf16 v[32:35], v[154:157], v[174:177], v[32:35]
	v_mfma_f32_16x16x32_bf16 v[20:23], v[142:145], v[182:185], v[20:23]
	v_mfma_f32_16x16x32_bf16 v[16:19], v[154:157], v[182:185], v[16:19]
	v_mfma_f32_16x16x32_bf16 v[4:7], v[142:145], v[190:193], v[4:7]
	v_mfma_f32_16x16x32_bf16 v[0:3], v[154:157], v[190:193], v[0:3]
	s_setprio 0
	s_barrier
	s_add_i32 s71, s71, 2
	s_add_u32 s68, s68, 0x100
	s_addc_u32 s69, s69, 0
	s_add_u32 s86, s86, 0x100
	s_addc_u32 s87, s87, 0
	s_cmp_gt_u32 s71, 13
	s_cbranch_scc0 .LBB0_236
	v_mov_b64_e32 v[252:253], 0x200
	v_lshl_or_b32 v210, s70, 8, v254
	v_lshl_add_u32 v240, s84, 8, v199
	v_ashrrev_i32_e32 v211, 31, v210
	v_lshlrev_b64 v[242:243], 1, v[210:211]
	v_ashrrev_i32_e32 v241, 31, v240
	v_lshl_add_u64 v[118:119], s[52:53], 0, v[242:243]
	v_lshlrev_b64 v[244:245], 11, v[240:241]
	v_lshl_add_u64 v[114:115], v[118:119], 0, v[244:245]
	global_load_dwordx4 v[190:193], v[114:115], off
	global_load_dwordx4 v[186:189], v[114:115], off offset:256
	v_or_b32_e32 v236, 16, v240
	v_ashrrev_i32_e32 v237, 31, v236
	v_or_b32_e32 v232, 32, v240
	v_lshlrev_b64 v[238:239], 11, v[236:237]
	v_ashrrev_i32_e32 v233, 31, v232
	v_or_b32_e32 v228, 48, v240
	v_lshl_add_u64 v[114:115], v[118:119], 0, v[238:239]
	v_lshlrev_b64 v[234:235], 11, v[232:233]
	v_ashrrev_i32_e32 v229, 31, v228
	v_add_u32_e32 v224, 0x80, v240
	global_load_dwordx4 v[182:185], v[114:115], off
	global_load_dwordx4 v[178:181], v[114:115], off offset:256
	v_lshl_add_u64 v[114:115], v[118:119], 0, v[234:235]
	v_lshlrev_b64 v[230:231], 11, v[228:229]
	v_ashrrev_i32_e32 v225, 31, v224
	v_add_u32_e32 v220, 0x90, v240
	global_load_dwordx4 v[174:177], v[114:115], off
	global_load_dwordx4 v[170:173], v[114:115], off offset:256
	v_lshl_add_u64 v[114:115], v[118:119], 0, v[230:231]
	v_lshlrev_b64 v[226:227], 11, v[224:225]
	v_ashrrev_i32_e32 v221, 31, v220
	v_add_u32_e32 v216, 0xa0, v240
	v_add_u32_e32 v212, 0xb0, v240
	global_load_dwordx4 v[166:169], v[114:115], off
	global_load_dwordx4 v[162:165], v[114:115], off offset:256
	v_lshl_add_u64 v[114:115], v[118:119], 0, v[226:227]
	v_lshlrev_b64 v[222:223], 11, v[220:221]
	v_ashrrev_i32_e32 v217, 31, v216
	v_ashrrev_i32_e32 v213, 31, v212
	global_load_dwordx4 v[154:157], v[114:115], off
	global_load_dwordx4 v[146:149], v[114:115], off offset:256
	v_lshl_add_u64 v[114:115], v[118:119], 0, v[222:223]
	v_lshlrev_b64 v[218:219], 11, v[216:217]
	v_lshlrev_b64 v[214:215], 11, v[212:213]
	global_load_dwordx4 v[142:145], v[114:115], off
	global_load_dwordx4 v[138:141], v[114:115], off offset:256
	v_lshl_add_u64 v[114:115], v[118:119], 0, v[218:219]
	v_lshl_add_u64 v[118:119], v[118:119], 0, v[214:215]
	global_load_dwordx4 v[122:125], v[114:115], off
	global_load_dwordx4 v[114:117], v[114:115], off offset:256
	global_load_dwordx4 v[126:129], v[118:119], off
	global_load_dwordx4 v[118:121], v[118:119], off offset:256
	s_and_b64 vcc, exec, s[74:75]
	s_cbranch_vccz .LBB0_239
	s_barrier
.LBB0_239:
	s_nop 0
	s_nop 0
	s_nop 0
	s_waitcnt vmcnt(0)
	v_lshlrev_b32_e32 v194, 16, v190
	v_and_b32_e32 v195, 0xffff0000, v190
	v_lshlrev_b32_e32 v190, 16, v191
	v_and_b32_e32 v191, 0xffff0000, v191
	v_lshlrev_b32_e32 v196, 16, v192
	v_and_b32_e32 v197, 0xffff0000, v192
	v_lshlrev_b32_e32 v192, 16, v193
	v_and_b32_e32 v193, 0xffff0000, v193
	v_pk_add_f32 v[158:159], v[158:159], v[194:195]
	v_lshl_add_u64 v[194:195], s[52:53], 0, v[244:245]
	v_pk_add_f32 v[160:161], v[160:161], v[190:191]
	v_pk_add_f32 v[190:191], v[152:153], v[192:193]
	v_pk_add_f32 v[192:193], v[150:151], v[196:197]
	v_cvt_pk_bf16_f32 v150, v158, v159
	v_cvt_pk_bf16_f32 v151, v160, v161
	v_lshl_add_u64 v[194:195], v[194:195], 0, v[242:243]
	v_cvt_pk_bf16_f32 v152, v192, v193
	v_cvt_pk_bf16_f32 v153, v190, v191
	global_store_dwordx4 v[194:195], v[150:153], off
	s_nop 1
	v_mul_f32_e32 v150, v159, v159
	v_mul_f32_e32 v151, v161, v161
	v_fmac_f32_e32 v150, v158, v158
	v_fmac_f32_e32 v151, v160, v160
	v_add_f32_e32 v150, v150, v151
	v_mul_f32_e32 v151, v193, v193
	v_mul_f32_e32 v152, v191, v191
	v_fmac_f32_e32 v151, v192, v192
	v_fmac_f32_e32 v152, v190, v190
	v_add_f32_e32 v151, v151, v152
	v_add_f32_e32 v190, v150, v151
	v_lshlrev_b32_e32 v150, 16, v186
	v_and_b32_e32 v151, 0xffff0000, v186
	v_lshlrev_b32_e32 v152, 16, v187
	v_and_b32_e32 v153, 0xffff0000, v187
	v_lshlrev_b32_e32 v158, 16, v188
	v_and_b32_e32 v159, 0xffff0000, v188
	v_lshlrev_b32_e32 v160, 16, v189
	v_and_b32_e32 v161, 0xffff0000, v189
	v_pk_add_f32 v[136:137], v[136:137], v[152:153]
	v_pk_add_f32 v[134:135], v[134:135], v[150:151]
	v_pk_add_f32 v[152:153], v[130:131], v[158:159]
	v_cvt_pk_bf16_f32 v130, v134, v135
	v_cvt_pk_bf16_f32 v131, v136, v137
	v_pk_add_f32 v[150:151], v[132:133], v[160:161]
	v_cvt_pk_bf16_f32 v132, v152, v153
	s_nop 0
	v_cvt_pk_bf16_f32 v133, v150, v151
	global_store_dwordx4 v[194:195], v[130:133], off offset:256
	s_nop 1
	v_mul_f32_e32 v130, v135, v135
	v_mul_f32_e32 v131, v137, v137
	v_fmac_f32_e32 v130, v134, v134
	v_fmac_f32_e32 v131, v136, v136
	v_add_f32_e32 v130, v130, v131
	v_mul_f32_e32 v131, v153, v153
	v_mul_f32_e32 v132, v151, v151
	v_fmac_f32_e32 v131, v152, v152
	v_fmac_f32_e32 v132, v150, v150
	v_add_f32_e32 v131, v131, v132
	v_add_f32_e32 v130, v130, v131
	v_and_b32_e32 v132, 64, v248
	v_add_f32_e32 v131, v190, v130
	v_xor_b32_e32 v130, 16, v248
	v_add_u32_e32 v133, 64, v132
	v_cmp_lt_i32_e32 vcc, v130, v133
	s_nop 1
	v_cndmask_b32_e32 v130, v248, v130, vcc
	v_lshlrev_b32_e32 v130, 2, v130
	ds_bpermute_b32 v132, v130, v131
	s_waitcnt lgkmcnt(0)
	v_add_f32_e32 v132, v131, v132
	v_xor_b32_e32 v131, 32, v248
	v_cmp_lt_i32_e32 vcc, v131, v133
	s_nop 1
	v_cndmask_b32_e32 v131, v248, v131, vcc
	v_lshlrev_b32_e32 v131, 2, v131
	ds_bpermute_b32 v133, v131, v132
	s_and_saveexec_b64 s[24:25], s[0:1]
	s_cbranch_execz .LBB0_241
	s_waitcnt lgkmcnt(0)
	v_add_f32_e32 v134, v132, v133
	s_lshl_b32 s6, s70, 2
	v_lshlrev_b64 v[132:133], 6, v[240:241]
	s_ashr_i32 s7, s6, 31
	v_lshl_add_u64 v[132:133], s[56:57], 0, v[132:133]
	v_lshl_add_u64 v[132:133], s[6:7], 2, v[132:133]
	s_lshl_b32 s16, s60, 2
	v_lshl_add_u64 v[132:133], v[132:133], 0, s[16:17]
	global_store_dword v[132:133], v134, off

.LBB0_503:
	s_add_u32 s2, s86, 0xfffc0080
	s_addc_u32 s14, s87, -1
	s_add_i32 s15, 0, 0x10000
	s_cmp_eq_u32 s63, 12
	s_cselect_b32 s27, s5, s14
	s_cselect_b32 s26, s6, s2
	s_cselect_b32 s25, s7, s19
	s_cselect_b32 s24, s8, s18
	s_add_i32 s2, 0, 0x14000
	v_add_u32_e32 v142, s15, v199
	v_add_u32_e32 v172, s2, v199
	ds_read_b128 v[130:133], v142
	ds_read_b128 v[134:137], v142 offset:1024
	ds_read_b128 v[138:141], v142 offset:2048
	ds_read_b128 v[142:145], v142 offset:3072
	ds_read_b128 v[146:149], v172
	ds_read_b128 v[150:153], v172 offset:1024
	ds_read_b128 v[168:171], v172 offset:2048
	ds_read_b128 v[172:175], v172 offset:3072
	v_lshl_add_u64 v[180:181], s[86:87], 0, v[166:167]
	s_add_i32 m0, s92, 0xc000
	ds_read_b128 v[176:179], v202
	ds_read_b128 v[184:187], v202 offset:1024
	ds_read_b128 v[188:191], v202 offset:2048
	ds_read_b128 v[204:207], v202 offset:3072
	ds_read_b128 v[208:211], v202 offset:4096
	ds_read_b128 v[212:215], v202 offset:5120
	ds_read_b128 v[216:219], v202 offset:6144
	ds_read_b128 v[220:223], v202 offset:7168
	global_load_lds_dwordx4 v[180:181], off
	v_lshl_add_u64 v[180:181], s[86:87], 0, v[164:165]
	s_add_i32 m0, s92, 0xe000
	s_nop 0
	global_load_lds_dwordx4 v[180:181], off
	s_waitcnt vmcnt(8)
	s_waitcnt lgkmcnt(0)
	s_barrier
	s_setprio 1
	s_waitcnt lgkmcnt(0)
	v_mfma_f32_16x16x32_bf16 v[126:129], v[130:133], v[176:179], v[126:129]
	v_mfma_f32_16x16x32_bf16 v[122:125], v[138:141], v[176:179], v[122:125]
	v_mfma_f32_16x16x32_bf16 v[110:113], v[130:133], v[188:191], v[110:113]
	v_mfma_f32_16x16x32_bf16 v[106:109], v[138:141], v[188:191], v[106:109]
	v_mfma_f32_16x16x32_bf16 v[92:95], v[130:133], v[208:211], v[92:95]
	v_mfma_f32_16x16x32_bf16 v[88:91], v[138:141], v[208:211], v[88:91]
	v_mfma_f32_16x16x32_bf16 v[76:79], v[130:133], v[216:219], v[76:79]
	v_mfma_f32_16x16x32_bf16 v[72:75], v[138:141], v[216:219], v[72:75]
	v_mfma_f32_16x16x32_bf16 v[126:129], v[134:137], v[184:187], v[126:129]
	v_mfma_f32_16x16x32_bf16 v[122:125], v[142:145], v[184:187], v[122:125]
	v_mfma_f32_16x16x32_bf16 v[110:113], v[134:137], v[204:207], v[110:113]
	v_mfma_f32_16x16x32_bf16 v[106:109], v[142:145], v[204:207], v[106:109]
	v_mfma_f32_16x16x32_bf16 v[92:95], v[134:137], v[212:215], v[92:95]
	v_mfma_f32_16x16x32_bf16 v[88:91], v[142:145], v[212:215], v[88:91]
	v_mfma_f32_16x16x32_bf16 v[76:79], v[134:137], v[220:223], v[76:79]
	v_mfma_f32_16x16x32_bf16 v[72:75], v[142:145], v[220:223], v[72:75]
	s_setprio 0
	s_setprio 1
	v_mfma_f32_16x16x32_bf16 v[118:121], v[146:149], v[176:179], v[118:121]
	v_mfma_f32_16x16x32_bf16 v[114:117], v[168:171], v[176:179], v[114:117]
	v_mfma_f32_16x16x32_bf16 v[102:105], v[146:149], v[188:191], v[102:105]
	v_mfma_f32_16x16x32_bf16 v[98:101], v[168:171], v[188:191], v[98:101]
	v_mfma_f32_16x16x32_bf16 v[84:87], v[146:149], v[208:211], v[84:87]
	v_mfma_f32_16x16x32_bf16 v[80:83], v[168:171], v[208:211], v[80:83]
	v_mfma_f32_16x16x32_bf16 v[68:71], v[146:149], v[216:219], v[68:71]
	v_mfma_f32_16x16x32_bf16 v[64:67], v[168:171], v[216:219], v[64:67]
	v_mfma_f32_16x16x32_bf16 v[118:121], v[150:153], v[184:187], v[118:121]
	v_mfma_f32_16x16x32_bf16 v[114:117], v[172:175], v[184:187], v[114:117]
	v_mfma_f32_16x16x32_bf16 v[102:105], v[150:153], v[204:207], v[102:105]
	v_mfma_f32_16x16x32_bf16 v[98:101], v[172:175], v[204:207], v[98:101]
	v_mfma_f32_16x16x32_bf16 v[84:87], v[150:153], v[212:215], v[84:87]
	v_mfma_f32_16x16x32_bf16 v[80:83], v[172:175], v[212:215], v[80:83]
	v_mfma_f32_16x16x32_bf16 v[68:71], v[150:153], v[220:223], v[68:71]
	v_mfma_f32_16x16x32_bf16 v[64:67], v[172:175], v[220:223], v[64:67]
	s_setprio 0
	s_barrier
	s_add_i32 s14, s15, s90
	v_lshl_add_u64 v[180:181], s[24:25], 0, v[158:159]
	s_mov_b32 m0, s14
	ds_read_b128 v[176:179], v202 offset:16384
	ds_read_b128 v[184:187], v202 offset:17408
	ds_read_b128 v[188:191], v202 offset:18432
	ds_read_b128 v[204:207], v202 offset:19456
	ds_read_b128 v[208:211], v202 offset:20480
	ds_read_b128 v[212:215], v202 offset:21504
	ds_read_b128 v[216:219], v202 offset:22528
	ds_read_b128 v[220:223], v202 offset:23552
	global_load_lds_dwordx4 v[180:181], off
	s_add_i32 m0, s14, 0x2000
	s_add_u32 s14, s24, 0x40000
	v_lshl_add_u64 v[192:193], s[24:25], 0, v[154:155]
	s_addc_u32 s15, s25, 0
	s_add_i32 s2, s2, s90
	global_load_lds_dwordx4 v[192:193], off
	v_lshl_add_u64 v[194:195], s[14:15], 0, v[158:159]
	s_mov_b32 m0, s2
	v_lshl_add_u64 v[196:197], s[26:27], 0, v[156:157]
	global_load_lds_dwordx4 v[194:195], off
	v_lshl_add_u64 v[194:195], s[14:15], 0, v[154:155]
	s_add_i32 m0, s2, 0x2000
	s_nop 0
	global_load_lds_dwordx4 v[194:195], off
	v_lshl_add_u64 v[194:195], s[26:27], 0, v[160:161]
	s_mov_b32 m0, s92
	s_nop 0
	global_load_lds_dwordx4 v[194:195], off
	s_mov_b32 m0, s93
	s_nop 0
	global_load_lds_dwordx4 v[196:197], off
	s_waitcnt vmcnt(8)
	s_waitcnt lgkmcnt(0)
	s_barrier
	s_setprio 1
	s_waitcnt lgkmcnt(0)
	v_mfma_f32_16x16x32_bf16 v[60:63], v[130:133], v[176:179], v[60:63]
	v_mfma_f32_16x16x32_bf16 v[56:59], v[138:141], v[176:179], v[56:59]
	v_mfma_f32_16x16x32_bf16 v[44:47], v[130:133], v[188:191], v[44:47]
	v_mfma_f32_16x16x32_bf16 v[40:43], v[138:141], v[188:191], v[40:43]
	v_mfma_f32_16x16x32_bf16 v[28:31], v[130:133], v[208:211], v[28:31]
	v_mfma_f32_16x16x32_bf16 v[24:27], v[138:141], v[208:211], v[24:27]
	v_mfma_f32_16x16x32_bf16 v[12:15], v[130:133], v[216:219], v[12:15]
	v_mfma_f32_16x16x32_bf16 v[8:11], v[138:141], v[216:219], v[8:11]
	v_mfma_f32_16x16x32_bf16 v[60:63], v[134:137], v[184:187], v[60:63]
	v_mfma_f32_16x16x32_bf16 v[56:59], v[142:145], v[184:187], v[56:59]
	v_mfma_f32_16x16x32_bf16 v[44:47], v[134:137], v[204:207], v[44:47]
	v_mfma_f32_16x16x32_bf16 v[40:43], v[142:145], v[204:207], v[40:43]
	v_mfma_f32_16x16x32_bf16 v[28:31], v[134:137], v[212:215], v[28:31]
	v_mfma_f32_16x16x32_bf16 v[24:27], v[142:145], v[212:215], v[24:27]
	v_mfma_f32_16x16x32_bf16 v[12:15], v[134:137], v[220:223], v[12:15]
	v_mfma_f32_16x16x32_bf16 v[8:11], v[142:145], v[220:223], v[8:11]
	s_setprio 0
	s_setprio 1
	v_mfma_f32_16x16x32_bf16 v[52:55], v[146:149], v[176:179], v[52:55]
	v_mfma_f32_16x16x32_bf16 v[48:51], v[168:171], v[176:179], v[48:51]
	v_mfma_f32_16x16x32_bf16 v[36:39], v[146:149], v[188:191], v[36:39]
	v_mfma_f32_16x16x32_bf16 v[32:35], v[168:171], v[188:191], v[32:35]
	v_mfma_f32_16x16x32_bf16 v[20:23], v[146:149], v[208:211], v[20:23]
	v_mfma_f32_16x16x32_bf16 v[16:19], v[168:171], v[208:211], v[16:19]
	v_mfma_f32_16x16x32_bf16 v[4:7], v[146:149], v[216:219], v[4:7]
	v_mfma_f32_16x16x32_bf16 v[0:3], v[168:171], v[216:219], v[0:3]
	v_mfma_f32_16x16x32_bf16 v[52:55], v[150:153], v[184:187], v[52:55]
	v_mfma_f32_16x16x32_bf16 v[48:51], v[172:175], v[184:187], v[48:51]
	v_mfma_f32_16x16x32_bf16 v[36:39], v[150:153], v[204:207], v[36:39]
	v_mfma_f32_16x16x32_bf16 v[32:35], v[172:175], v[204:207], v[32:35]
	v_mfma_f32_16x16x32_bf16 v[20:23], v[150:153], v[212:215], v[20:23]
	v_mfma_f32_16x16x32_bf16 v[16:19], v[172:175], v[212:215], v[16:19]
	v_mfma_f32_16x16x32_bf16 v[4:7], v[150:153], v[220:223], v[4:7]
	v_mfma_f32_16x16x32_bf16 v[0:3], v[172:175], v[220:223], v[0:3]
	s_setprio 0
	s_barrier
	s_add_i32 s2, 0, 0x18000
	s_add_i32 s20, 0, 0x1c000
	v_add_u32_e32 v142, s2, v199
	v_add_u32_e32 v172, s20, v199
	ds_read_b128 v[130:133], v142
	ds_read_b128 v[134:137], v142 offset:1024
	ds_read_b128 v[138:141], v142 offset:2048
	ds_read_b128 v[142:145], v142 offset:3072
	ds_read_b128 v[146:149], v172
	ds_read_b128 v[150:153], v172 offset:1024
	ds_read_b128 v[168:171], v172 offset:2048
	ds_read_b128 v[172:175], v172 offset:3072
	s_add_u32 s14, s26, 0x40000
	s_addc_u32 s15, s27, 0
	s_mov_b32 m0, s94
	v_lshl_add_u64 v[224:225], s[14:15], 0, v[160:161]
	ds_read_b128 v[176:179], v202 offset:32768
	ds_read_b128 v[184:187], v202 offset:33792
	ds_read_b128 v[188:191], v202 offset:34816
	ds_read_b128 v[204:207], v202 offset:35840
	ds_read_b128 v[208:211], v202 offset:36864
	ds_read_b128 v[212:215], v202 offset:37888
	ds_read_b128 v[216:219], v202 offset:38912
	ds_read_b128 v[220:223], v202 offset:39936
	global_load_lds_dwordx4 v[224:225], off
	v_lshl_add_u64 v[224:225], s[14:15], 0, v[156:157]
	s_mov_b32 m0, s95
	s_nop 0
	global_load_lds_dwordx4 v[224:225], off
	s_waitcnt vmcnt(8)
	s_waitcnt lgkmcnt(0)
	s_barrier
	s_setprio 1
	s_waitcnt lgkmcnt(0)
	v_mfma_f32_16x16x32_bf16 v[126:129], v[130:133], v[176:179], v[126:129]
	v_mfma_f32_16x16x32_bf16 v[122:125], v[138:141], v[176:179], v[122:125]
	v_mfma_f32_16x16x32_bf16 v[110:113], v[130:133], v[188:191], v[110:113]
	v_mfma_f32_16x16x32_bf16 v[106:109], v[138:141], v[188:191], v[106:109]
	v_mfma_f32_16x16x32_bf16 v[92:95], v[130:133], v[208:211], v[92:95]
	v_mfma_f32_16x16x32_bf16 v[88:91], v[138:141], v[208:211], v[88:91]
	v_mfma_f32_16x16x32_bf16 v[76:79], v[130:133], v[216:219], v[76:79]
	v_mfma_f32_16x16x32_bf16 v[72:75], v[138:141], v[216:219], v[72:75]
	v_mfma_f32_16x16x32_bf16 v[126:129], v[134:137], v[184:187], v[126:129]
	v_mfma_f32_16x16x32_bf16 v[122:125], v[142:145], v[184:187], v[122:125]
	v_mfma_f32_16x16x32_bf16 v[110:113], v[134:137], v[204:207], v[110:113]
	v_mfma_f32_16x16x32_bf16 v[106:109], v[142:145], v[204:207], v[106:109]
	v_mfma_f32_16x16x32_bf16 v[92:95], v[134:137], v[212:215], v[92:95]
	v_mfma_f32_16x16x32_bf16 v[88:91], v[142:145], v[212:215], v[88:91]
	v_mfma_f32_16x16x32_bf16 v[76:79], v[134:137], v[220:223], v[76:79]
	v_mfma_f32_16x16x32_bf16 v[72:75], v[142:145], v[220:223], v[72:75]
	s_setprio 0
	s_setprio 1
	v_mfma_f32_16x16x32_bf16 v[118:121], v[146:149], v[176:179], v[118:121]
	v_mfma_f32_16x16x32_bf16 v[114:117], v[168:171], v[176:179], v[114:117]
	v_mfma_f32_16x16x32_bf16 v[102:105], v[146:149], v[188:191], v[102:105]
	v_mfma_f32_16x16x32_bf16 v[98:101], v[168:171], v[188:191], v[98:101]
	v_mfma_f32_16x16x32_bf16 v[84:87], v[146:149], v[208:211], v[84:87]
	v_mfma_f32_16x16x32_bf16 v[80:83], v[168:171], v[208:211], v[80:83]
	v_mfma_f32_16x16x32_bf16 v[68:71], v[146:149], v[216:219], v[68:71]
	v_mfma_f32_16x16x32_bf16 v[64:67], v[168:171], v[216:219], v[64:67]
	v_mfma_f32_16x16x32_bf16 v[118:121], v[150:153], v[184:187], v[118:121]
	v_mfma_f32_16x16x32_bf16 v[114:117], v[172:175], v[184:187], v[114:117]
	v_mfma_f32_16x16x32_bf16 v[102:105], v[150:153], v[204:207], v[102:105]
	v_mfma_f32_16x16x32_bf16 v[98:101], v[172:175], v[204:207], v[98:101]
	v_mfma_f32_16x16x32_bf16 v[84:87], v[150:153], v[212:215], v[84:87]
	v_mfma_f32_16x16x32_bf16 v[80:83], v[172:175], v[212:215], v[80:83]
	v_mfma_f32_16x16x32_bf16 v[68:71], v[150:153], v[220:223], v[68:71]
	v_mfma_f32_16x16x32_bf16 v[64:67], v[172:175], v[220:223], v[64:67]
	s_setprio 0
	s_barrier
	s_add_i32 s2, s2, s90
	v_lshl_add_u64 v[180:181], v[180:181], 0, s[22:23]
	s_mov_b32 m0, s2
	ds_read_b128 v[176:179], v202 offset:49152
	ds_read_b128 v[184:187], v202 offset:50176
	ds_read_b128 v[188:191], v202 offset:51200
	ds_read_b128 v[204:207], v202 offset:52224
	ds_read_b128 v[208:211], v202 offset:53248
	ds_read_b128 v[212:215], v202 offset:54272
	ds_read_b128 v[216:219], v202 offset:55296
	ds_read_b128 v[220:223], v202 offset:56320
	global_load_lds_dwordx4 v[180:181], off
	s_add_i32 m0, s2, 0x2000
	s_add_u32 s14, s24, 0x40080
	v_lshl_add_u64 v[180:181], v[192:193], 0, s[22:23]
	s_addc_u32 s15, s25, 0
	s_add_i32 s2, s20, s90
	global_load_lds_dwordx4 v[180:181], off
	v_lshl_add_u64 v[180:181], s[14:15], 0, v[158:159]
	s_mov_b32 m0, s2
	s_nop 0
	global_load_lds_dwordx4 v[180:181], off
	v_lshl_add_u64 v[180:181], s[14:15], 0, v[154:155]
	s_add_i32 m0, s2, 0x2000
	s_nop 0
	global_load_lds_dwordx4 v[180:181], off
	v_lshl_add_u64 v[180:181], v[194:195], 0, s[22:23]
	s_mov_b32 m0, s96
	s_nop 0
	global_load_lds_dwordx4 v[180:181], off
	v_lshl_add_u64 v[180:181], v[196:197], 0, s[22:23]
	s_mov_b32 m0, s97
	s_nop 0
	global_load_lds_dwordx4 v[180:181], off
	s_waitcnt vmcnt(8)
	s_waitcnt lgkmcnt(0)
	s_barrier
	s_setprio 1
	s_waitcnt lgkmcnt(0)
	v_mfma_f32_16x16x32_bf16 v[60:63], v[130:133], v[176:179], v[60:63]
	v_mfma_f32_16x16x32_bf16 v[56:59], v[138:141], v[176:179], v[56:59]
	v_mfma_f32_16x16x32_bf16 v[44:47], v[130:133], v[188:191], v[44:47]
	v_mfma_f32_16x16x32_bf16 v[40:43], v[138:141], v[188:191], v[40:43]
	v_mfma_f32_16x16x32_bf16 v[28:31], v[130:133], v[208:211], v[28:31]
	v_mfma_f32_16x16x32_bf16 v[24:27], v[138:141], v[208:211], v[24:27]
	v_mfma_f32_16x16x32_bf16 v[12:15], v[130:133], v[216:219], v[12:15]
	v_mfma_f32_16x16x32_bf16 v[8:11], v[138:141], v[216:219], v[8:11]
	v_mfma_f32_16x16x32_bf16 v[60:63], v[134:137], v[184:187], v[60:63]
	v_mfma_f32_16x16x32_bf16 v[56:59], v[142:145], v[184:187], v[56:59]
	v_mfma_f32_16x16x32_bf16 v[44:47], v[134:137], v[204:207], v[44:47]
	v_mfma_f32_16x16x32_bf16 v[40:43], v[142:145], v[204:207], v[40:43]
	v_mfma_f32_16x16x32_bf16 v[28:31], v[134:137], v[212:215], v[28:31]
	v_mfma_f32_16x16x32_bf16 v[24:27], v[142:145], v[212:215], v[24:27]
	v_mfma_f32_16x16x32_bf16 v[12:15], v[134:137], v[220:223], v[12:15]
	v_mfma_f32_16x16x32_bf16 v[8:11], v[142:145], v[220:223], v[8:11]
	s_setprio 0
	s_setprio 1
	v_mfma_f32_16x16x32_bf16 v[52:55], v[146:149], v[176:179], v[52:55]
	v_mfma_f32_16x16x32_bf16 v[48:51], v[168:171], v[176:179], v[48:51]
	v_mfma_f32_16x16x32_bf16 v[36:39], v[146:149], v[188:191], v[36:39]
	v_mfma_f32_16x16x32_bf16 v[32:35], v[168:171], v[188:191], v[32:35]
	v_mfma_f32_16x16x32_bf16 v[20:23], v[146:149], v[208:211], v[20:23]
	v_mfma_f32_16x16x32_bf16 v[16:19], v[168:171], v[208:211], v[16:19]
	v_mfma_f32_16x16x32_bf16 v[4:7], v[146:149], v[216:219], v[4:7]
	v_mfma_f32_16x16x32_bf16 v[0:3], v[168:171], v[216:219], v[0:3]
	v_mfma_f32_16x16x32_bf16 v[52:55], v[150:153], v[184:187], v[52:55]
	v_mfma_f32_16x16x32_bf16 v[48:51], v[172:175], v[184:187], v[48:51]
	v_mfma_f32_16x16x32_bf16 v[36:39], v[150:153], v[204:207], v[36:39]
	v_mfma_f32_16x16x32_bf16 v[32:35], v[172:175], v[204:207], v[32:35]
	v_mfma_f32_16x16x32_bf16 v[20:23], v[150:153], v[212:215], v[20:23]
	v_mfma_f32_16x16x32_bf16 v[16:19], v[172:175], v[212:215], v[16:19]
	v_mfma_f32_16x16x32_bf16 v[4:7], v[150:153], v[220:223], v[4:7]
	v_mfma_f32_16x16x32_bf16 v[0:3], v[172:175], v[220:223], v[0:3]
	s_setprio 0
	s_barrier
	s_add_i32 s63, s63, 2
	s_add_u32 s18, s18, 0x100
	s_addc_u32 s19, s19, 0
	s_add_u32 s86, s86, 0x100
	s_addc_u32 s87, s87, 0
	s_cmp_gt_u32 s63, 13
	s_cbranch_scc0 .LBB0_503
	v_lshl_add_u32 v184, s4, 8, v183
	v_ashrrev_i32_e32 v185, 31, v184
	v_lshlrev_b64 v[130:131], 6, v[184:185]
	v_or_b32_e32 v180, 16, v184
	v_lshl_add_u64 v[130:131], v[162:163], 0, v[130:131]
	v_ashrrev_i32_e32 v181, 31, v180
	global_load_dwordx4 v[186:189], v[130:131], off
	v_lshlrev_b64 v[130:131], 6, v[180:181]
	v_lshl_add_u64 v[130:131], v[162:163], 0, v[130:131]
	global_load_dwordx4 v[190:193], v[130:131], off
	v_or_b32_e32 v178, 32, v184
	v_ashrrev_i32_e32 v179, 31, v178
	v_lshlrev_b64 v[130:131], 6, v[178:179]
	v_or_b32_e32 v176, 48, v184
	v_lshl_add_u64 v[130:131], v[162:163], 0, v[130:131]
	v_ashrrev_i32_e32 v177, 31, v176
	global_load_dwordx4 v[150:153], v[130:131], off
	v_lshlrev_b64 v[130:131], 6, v[176:177]
	v_lshl_add_u64 v[130:131], v[162:163], 0, v[130:131]
	global_load_dwordx4 v[146:149], v[130:131], off
	v_add_u32_e32 v174, 0x80, v184
	v_ashrrev_i32_e32 v175, 31, v174
	v_lshlrev_b64 v[130:131], 6, v[174:175]
	v_add_u32_e32 v172, 0x90, v184
	v_lshl_add_u64 v[130:131], v[162:163], 0, v[130:131]
	v_ashrrev_i32_e32 v173, 31, v172
	global_load_dwordx4 v[142:145], v[130:131], off
	v_lshlrev_b64 v[130:131], 6, v[172:173]
	v_lshl_add_u64 v[130:131], v[162:163], 0, v[130:131]
	global_load_dwordx4 v[138:141], v[130:131], off
	v_add_u32_e32 v170, 0xa0, v184
	v_ashrrev_i32_e32 v171, 31, v170
	v_lshlrev_b64 v[130:131], 6, v[170:171]
	v_add_u32_e32 v168, 0xb0, v184
	v_lshl_add_u64 v[130:131], v[162:163], 0, v[130:131]
	v_ashrrev_i32_e32 v169, 31, v168
	global_load_dwordx4 v[134:137], v[130:131], off
	v_lshlrev_b64 v[130:131], 6, v[168:169]
	v_lshl_add_u64 v[130:131], v[162:163], 0, v[130:131]
	global_load_dwordx4 v[130:133], v[130:131], off
	s_and_b64 vcc, exec, s[74:75]
	s_cbranch_vccz .LBB0_506
	s_barrier
.LBB0_506:
	v_and_b32_e32 v194, 64, v248
	v_xor_b32_e32 v182, 16, v248
	v_add_u32_e32 v194, 64, v194
	v_cmp_lt_i32_e32 vcc, v182, v194
	s_nop 1
	v_cndmask_b32_e32 v182, v248, v182, vcc
	v_lshlrev_b32_e32 v203, 2, v182
	v_xor_b32_e32 v182, 32, v248
	v_cmp_lt_i32_e32 vcc, v182, v194
	s_nop 1
	v_cndmask_b32_e32 v182, v248, v182, vcc
	v_lshlrev_b32_e32 v204, 2, v182
	s_mov_b32 s2, 0x358637bd
	s_cmp_gt_i32 s62, 3
	s_waitcnt vmcnt(0)
	v_mov_b32_e32 v194, v187
	v_mov_b32_e32 v195, v188
	v_mov_b32_e32 v187, v189
	v_mov_b32_e32 v188, v191
	v_mov_b32_e32 v189, v192
	v_mov_b32_e32 v191, v193
	v_pk_add_f32 v[186:187], v[194:195], v[186:187]
	v_pk_add_f32 v[188:189], v[188:189], v[190:191]
	v_mov_b32_e32 v191, v186
	v_mov_b32_e32 v190, v188
	v_mov_b32_e32 v186, v189
	v_pk_add_f32 v[186:187], v[190:191], v[186:187]
	ds_bpermute_b32 v189, v203, v187
	ds_bpermute_b32 v188, v203, v186
	s_waitcnt lgkmcnt(0)
	v_pk_add_f32 v[186:187], v[186:187], v[188:189]
	ds_bpermute_b32 v189, v204, v187
	ds_bpermute_b32 v188, v204, v186
	s_waitcnt lgkmcnt(0)
	v_pk_add_f32 v[186:187], v[186:187], v[188:189]
	v_mov_b64_e32 v[188:189], s[2:3]
	v_pk_fma_f32 v[190:191], v[186:187], s[28:29], v[188:189] op_sel_hi:[1,0,0]
	s_nop 0
	v_mul_f32_e32 v182, 0x4b800000, v191
	v_cmp_gt_f32_e64 s[4:5], s29, v191
	v_cmp_gt_f32_e32 vcc, s29, v190
	s_nop 0
	v_cndmask_b32_e64 v182, v191, v182, s[4:5]
	v_rsq_f32_e32 v182, v182
	v_mov_b32_e32 v191, v152
	v_mov_b32_e32 v152, v147
	v_mov_b32_e32 v147, v149
	v_mul_f32_e32 v186, 0x45800000, v182
	v_cndmask_b32_e64 v186, v182, v186, s[4:5]
	v_mul_f32_e32 v182, 0x4b800000, v190
	v_cndmask_b32_e32 v182, v190, v182, vcc
	v_mov_b32_e32 v190, v151
	v_mov_b32_e32 v151, v153
	v_mov_b32_e32 v153, v148
	v_pk_add_f32 v[150:151], v[190:191], v[150:151]
	v_pk_add_f32 v[146:147], v[152:153], v[146:147]
	v_mov_b32_e32 v149, v150
	v_mov_b32_e32 v148, v146
	v_mov_b32_e32 v150, v147
	v_pk_add_f32 v[146:147], v[148:149], v[150:151]
	ds_bpermute_b32 v149, v203, v147
	ds_bpermute_b32 v148, v203, v146
	v_rsq_f32_e32 v182, v182
	s_waitcnt lgkmcnt(0)
	v_pk_add_f32 v[146:147], v[146:147], v[148:149]
	ds_bpermute_b32 v149, v204, v147
	ds_bpermute_b32 v148, v204, v146
	v_mul_f32_e32 v187, 0x45800000, v182
	v_cndmask_b32_e32 v182, v182, v187, vcc
	s_waitcnt lgkmcnt(0)
	v_pk_add_f32 v[146:147], v[146:147], v[148:149]
	s_nop 0
	v_pk_fma_f32 v[146:147], v[146:147], s[28:29], v[188:189] op_sel_hi:[1,0,0]
	s_nop 0
	v_mul_f32_e32 v148, 0x4b800000, v147
	v_cmp_gt_f32_e64 s[4:5], s29, v147
	v_cmp_gt_f32_e32 vcc, s29, v146
	s_nop 0
	v_cndmask_b32_e64 v147, v147, v148, s[4:5]
	v_rsq_f32_e32 v147, v147
	s_nop 0
	v_mul_f32_e32 v148, 0x45800000, v147
	v_cndmask_b32_e64 v152, v147, v148, s[4:5]
	v_mul_f32_e32 v147, 0x4b800000, v146
	v_cndmask_b32_e32 v146, v146, v147, vcc
	v_rsq_f32_e32 v146, v146
	s_nop 0
	v_mul_f32_e32 v147, 0x45800000, v146
	v_cndmask_b32_e32 v148, v146, v147, vcc
	v_mov_b32_e32 v146, v143
	v_mov_b32_e32 v147, v144
	v_mov_b32_e32 v143, v145
	v_mov_b32_e32 v144, v139
	v_mov_b32_e32 v145, v140
	v_mov_b32_e32 v139, v141
	v_pk_add_f32 v[142:143], v[146:147], v[142:143]
	v_pk_add_f32 v[138:139], v[144:145], v[138:139]
	v_mov_b32_e32 v141, v142
	v_mov_b32_e32 v140, v138
	v_mov_b32_e32 v142, v139
	v_pk_add_f32 v[138:139], v[140:141], v[142:143]
	ds_bpermute_b32 v141, v203, v139
	ds_bpermute_b32 v140, v203, v138
	s_waitcnt lgkmcnt(0)
	v_pk_add_f32 v[138:139], v[138:139], v[140:141]
	ds_bpermute_b32 v141, v204, v139
	ds_bpermute_b32 v140, v204, v138
	s_waitcnt lgkmcnt(0)
	v_pk_add_f32 v[138:139], v[138:139], v[140:141]
	s_nop 0
	v_pk_fma_f32 v[138:139], v[138:139], s[28:29], v[188:189] op_sel_hi:[1,0,0]
	s_nop 0
	v_mul_f32_e32 v140, 0x4b800000, v139
	v_cmp_gt_f32_e64 s[4:5], s29, v139
	v_cmp_gt_f32_e32 vcc, s29, v138
	s_nop 0
	v_cndmask_b32_e64 v139, v139, v140, s[4:5]
	v_rsq_f32_e32 v139, v139
	s_nop 0
	v_mul_f32_e32 v140, 0x45800000, v139
	v_cndmask_b32_e64 v150, v139, v140, s[4:5]
	v_mul_f32_e32 v139, 0x4b800000, v138
	v_cndmask_b32_e32 v138, v138, v139, vcc
	v_rsq_f32_e32 v138, v138
	s_nop 0
	v_mul_f32_e32 v139, 0x45800000, v138
	v_cndmask_b32_e32 v146, v138, v139, vcc
	v_mov_b32_e32 v138, v135
	v_mov_b32_e32 v139, v136
	v_mov_b32_e32 v135, v137
	v_mov_b32_e32 v136, v131
	v_mov_b32_e32 v137, v132
	v_mov_b32_e32 v131, v133
	v_pk_add_f32 v[134:135], v[138:139], v[134:135]
	v_pk_add_f32 v[130:131], v[136:137], v[130:131]
	v_mov_b32_e32 v133, v134
	v_mov_b32_e32 v132, v130
	v_mov_b32_e32 v134, v131
	v_pk_add_f32 v[130:131], v[132:133], v[134:135]
	ds_bpermute_b32 v133, v203, v131
	ds_bpermute_b32 v132, v203, v130
	s_waitcnt lgkmcnt(0)
	v_pk_add_f32 v[130:131], v[130:131], v[132:133]
	ds_bpermute_b32 v133, v204, v131
	ds_bpermute_b32 v132, v204, v130
	s_waitcnt lgkmcnt(0)
	v_pk_add_f32 v[130:131], v[130:131], v[132:133]
	s_nop 0
	v_pk_fma_f32 v[130:131], v[130:131], s[28:29], v[188:189] op_sel_hi:[1,0,0]
	s_nop 0
	v_mul_f32_e32 v132, 0x4b800000, v131
	v_cmp_gt_f32_e64 s[4:5], s29, v131
	v_cmp_gt_f32_e32 vcc, s29, v130
	s_nop 0
	v_cndmask_b32_e64 v131, v131, v132, s[4:5]
	v_rsq_f32_e32 v131, v131
	s_nop 0
	v_mul_f32_e32 v132, 0x45800000, v131
	v_cndmask_b32_e64 v144, v131, v132, s[4:5]
	v_mul_f32_e32 v131, 0x4b800000, v130
	v_cndmask_b32_e32 v130, v130, v131, vcc
	v_rsq_f32_e32 v130, v130
	s_mov_b64 s[4:5], -1
	v_mul_f32_e32 v131, 0x45800000, v130
	v_cndmask_b32_e32 v142, v130, v131, vcc
	s_cbranch_scc1 .LBB0_509
	s_andn2_b64 vcc, exec, s[4:5]
	s_cbranch_vccz .LBB0_518

.LBB0_552:
	s_add_u32 s74, s72, 0x100
	s_addc_u32 s75, s73, 0
	s_add_i32 s2, 0, 0x10000
	s_cmp_eq_u32 s80, 40
	s_cselect_b32 s27, s5, s75
	s_cselect_b32 s26, s4, s74
	s_cselect_b32 s25, s71, s79
	s_cselect_b32 s24, s70, s8
	s_add_i32 s20, 0, 0x14000
	v_add_u32_e32 v126, s2, v254
	v_add_u32_e32 v150, s20, v254
	ds_read_b128 v[114:117], v126
	ds_read_b128 v[118:121], v126 offset:1024
	ds_read_b128 v[122:125], v126 offset:2048
	ds_read_b128 v[126:129], v126 offset:3072
	ds_read_b128 v[138:141], v150
	ds_read_b128 v[142:145], v150 offset:1024
	ds_read_b128 v[146:149], v150 offset:2048
	ds_read_b128 v[150:153], v150 offset:3072
	v_lshl_add_u64 v[210:211], s[72:73], 0, v[208:209]
	s_add_i32 m0, s45, 0xc000
	ds_read_b128 v[162:165], v251
	ds_read_b128 v[166:169], v251 offset:1024
	ds_read_b128 v[170:173], v251 offset:2048
	ds_read_b128 v[174:177], v251 offset:3072
	ds_read_b128 v[178:181], v251 offset:4096
	ds_read_b128 v[182:185], v251 offset:5120
	ds_read_b128 v[186:189], v251 offset:6144
	ds_read_b128 v[190:193], v251 offset:7168
	global_load_lds_dwordx4 v[210:211], off
	v_lshl_add_u64 v[210:211], s[72:73], 0, v[206:207]
	s_add_i32 m0, s45, 0xe000
	s_nop 0
	global_load_lds_dwordx4 v[210:211], off
	s_waitcnt vmcnt(8)
	s_waitcnt lgkmcnt(0)
	s_barrier
	s_setprio 1
	s_waitcnt lgkmcnt(0)
	v_mfma_f32_16x16x32_bf16 v[158:161], v[114:117], v[162:165], v[158:161]
	v_mfma_f32_16x16x32_bf16 v[154:157], v[122:125], v[162:165], v[154:157]
	v_mfma_f32_16x16x32_bf16 v[110:113], v[114:117], v[170:173], v[110:113]
	v_mfma_f32_16x16x32_bf16 v[106:109], v[122:125], v[170:173], v[106:109]
	v_mfma_f32_16x16x32_bf16 v[92:95], v[114:117], v[178:181], v[92:95]
	v_mfma_f32_16x16x32_bf16 v[88:91], v[122:125], v[178:181], v[88:91]
	v_mfma_f32_16x16x32_bf16 v[76:79], v[114:117], v[186:189], v[76:79]
	v_mfma_f32_16x16x32_bf16 v[72:75], v[122:125], v[186:189], v[72:75]
	v_mfma_f32_16x16x32_bf16 v[158:161], v[118:121], v[166:169], v[158:161]
	v_mfma_f32_16x16x32_bf16 v[154:157], v[126:129], v[166:169], v[154:157]
	v_mfma_f32_16x16x32_bf16 v[110:113], v[118:121], v[174:177], v[110:113]
	v_mfma_f32_16x16x32_bf16 v[106:109], v[126:129], v[174:177], v[106:109]
	v_mfma_f32_16x16x32_bf16 v[92:95], v[118:121], v[182:185], v[92:95]
	v_mfma_f32_16x16x32_bf16 v[88:91], v[126:129], v[182:185], v[88:91]
	v_mfma_f32_16x16x32_bf16 v[76:79], v[118:121], v[190:193], v[76:79]
	v_mfma_f32_16x16x32_bf16 v[72:75], v[126:129], v[190:193], v[72:75]
	s_setprio 0
	s_setprio 1
	v_mfma_f32_16x16x32_bf16 v[134:137], v[138:141], v[162:165], v[134:137]
	v_mfma_f32_16x16x32_bf16 v[130:133], v[146:149], v[162:165], v[130:133]
	v_mfma_f32_16x16x32_bf16 v[102:105], v[138:141], v[170:173], v[102:105]
	v_mfma_f32_16x16x32_bf16 v[98:101], v[146:149], v[170:173], v[98:101]
	v_mfma_f32_16x16x32_bf16 v[84:87], v[138:141], v[178:181], v[84:87]
	v_mfma_f32_16x16x32_bf16 v[80:83], v[146:149], v[178:181], v[80:83]
	v_mfma_f32_16x16x32_bf16 v[68:71], v[138:141], v[186:189], v[68:71]
	v_mfma_f32_16x16x32_bf16 v[64:67], v[146:149], v[186:189], v[64:67]
	v_mfma_f32_16x16x32_bf16 v[134:137], v[142:145], v[166:169], v[134:137]
	v_mfma_f32_16x16x32_bf16 v[130:133], v[150:153], v[166:169], v[130:133]
	v_mfma_f32_16x16x32_bf16 v[102:105], v[142:145], v[174:177], v[102:105]
	v_mfma_f32_16x16x32_bf16 v[98:101], v[150:153], v[174:177], v[98:101]
	v_mfma_f32_16x16x32_bf16 v[84:87], v[142:145], v[182:185], v[84:87]
	v_mfma_f32_16x16x32_bf16 v[80:83], v[150:153], v[182:185], v[80:83]
	v_mfma_f32_16x16x32_bf16 v[68:71], v[142:145], v[190:193], v[68:71]
	v_mfma_f32_16x16x32_bf16 v[64:67], v[150:153], v[190:193], v[64:67]
	s_setprio 0
	s_barrier
	s_add_i32 s2, s2, s43
	v_lshl_add_u64 v[210:211], s[24:25], 0, v[96:97]
	s_mov_b32 m0, s2
	ds_read_b128 v[162:165], v251 offset:16384
	ds_read_b128 v[166:169], v251 offset:17408
	ds_read_b128 v[170:173], v251 offset:18432
	ds_read_b128 v[174:177], v251 offset:19456
	ds_read_b128 v[178:181], v251 offset:20480
	ds_read_b128 v[182:185], v251 offset:21504
	ds_read_b128 v[186:189], v251 offset:22528
	ds_read_b128 v[190:193], v251 offset:23552
	global_load_lds_dwordx4 v[210:211], off
	s_add_i32 m0, s2, 0x2000
	s_add_u32 s14, s24, 0xb0000
	v_lshl_add_u64 v[212:213], s[24:25], 0, v[204:205]
	s_addc_u32 s15, s25, 0
	s_add_i32 s2, s20, s43
	global_load_lds_dwordx4 v[212:213], off
	v_lshl_add_u64 v[214:215], s[14:15], 0, v[96:97]
	s_mov_b32 m0, s2
	v_lshl_add_u64 v[216:217], s[26:27], 0, v[202:203]
	global_load_lds_dwordx4 v[214:215], off
	v_lshl_add_u64 v[214:215], s[14:15], 0, v[204:205]
	s_add_i32 m0, s2, 0x2000
	s_nop 0
	global_load_lds_dwordx4 v[214:215], off
	v_lshl_add_u64 v[214:215], s[26:27], 0, v[200:201]
	s_mov_b32 m0, s45
	s_nop 0
	global_load_lds_dwordx4 v[214:215], off
	s_mov_b32 m0, s47
	s_nop 0
	global_load_lds_dwordx4 v[216:217], off
	s_waitcnt vmcnt(8)
	s_waitcnt lgkmcnt(0)
	s_barrier
	s_setprio 1
	s_waitcnt lgkmcnt(0)
	v_mfma_f32_16x16x32_bf16 v[60:63], v[114:117], v[162:165], v[60:63]
	v_mfma_f32_16x16x32_bf16 v[56:59], v[122:125], v[162:165], v[56:59]
	v_mfma_f32_16x16x32_bf16 v[44:47], v[114:117], v[170:173], v[44:47]
	v_mfma_f32_16x16x32_bf16 v[40:43], v[122:125], v[170:173], v[40:43]
	v_mfma_f32_16x16x32_bf16 v[28:31], v[114:117], v[178:181], v[28:31]
	v_mfma_f32_16x16x32_bf16 v[24:27], v[122:125], v[178:181], v[24:27]
	v_mfma_f32_16x16x32_bf16 v[12:15], v[114:117], v[186:189], v[12:15]
	v_mfma_f32_16x16x32_bf16 v[8:11], v[122:125], v[186:189], v[8:11]
	v_mfma_f32_16x16x32_bf16 v[60:63], v[118:121], v[166:169], v[60:63]
	v_mfma_f32_16x16x32_bf16 v[56:59], v[126:129], v[166:169], v[56:59]
	v_mfma_f32_16x16x32_bf16 v[44:47], v[118:121], v[174:177], v[44:47]
	v_mfma_f32_16x16x32_bf16 v[40:43], v[126:129], v[174:177], v[40:43]
	v_mfma_f32_16x16x32_bf16 v[28:31], v[118:121], v[182:185], v[28:31]
	v_mfma_f32_16x16x32_bf16 v[24:27], v[126:129], v[182:185], v[24:27]
	v_mfma_f32_16x16x32_bf16 v[12:15], v[118:121], v[190:193], v[12:15]
	v_mfma_f32_16x16x32_bf16 v[8:11], v[126:129], v[190:193], v[8:11]
	s_setprio 0
	s_setprio 1
	v_mfma_f32_16x16x32_bf16 v[52:55], v[138:141], v[162:165], v[52:55]
	v_mfma_f32_16x16x32_bf16 v[48:51], v[146:149], v[162:165], v[48:51]
	v_mfma_f32_16x16x32_bf16 v[36:39], v[138:141], v[170:173], v[36:39]
	v_mfma_f32_16x16x32_bf16 v[32:35], v[146:149], v[170:173], v[32:35]
	v_mfma_f32_16x16x32_bf16 v[20:23], v[138:141], v[178:181], v[20:23]
	v_mfma_f32_16x16x32_bf16 v[16:19], v[146:149], v[178:181], v[16:19]
	v_mfma_f32_16x16x32_bf16 v[4:7], v[138:141], v[186:189], v[4:7]
	v_mfma_f32_16x16x32_bf16 v[0:3], v[146:149], v[186:189], v[0:3]
	v_mfma_f32_16x16x32_bf16 v[52:55], v[142:145], v[166:169], v[52:55]
	v_mfma_f32_16x16x32_bf16 v[48:51], v[150:153], v[166:169], v[48:51]
	v_mfma_f32_16x16x32_bf16 v[36:39], v[142:145], v[174:177], v[36:39]
	v_mfma_f32_16x16x32_bf16 v[32:35], v[150:153], v[174:177], v[32:35]
	v_mfma_f32_16x16x32_bf16 v[20:23], v[142:145], v[182:185], v[20:23]
	v_mfma_f32_16x16x32_bf16 v[16:19], v[150:153], v[182:185], v[16:19]
	v_mfma_f32_16x16x32_bf16 v[4:7], v[142:145], v[190:193], v[4:7]
	v_mfma_f32_16x16x32_bf16 v[0:3], v[150:153], v[190:193], v[0:3]
	s_setprio 0
	s_barrier
	s_add_i32 s2, 0, 0x18000
	s_add_i32 s20, 0, 0x1c000
	v_add_u32_e32 v126, s2, v254
	v_add_u32_e32 v150, s20, v254
	ds_read_b128 v[114:117], v126
	ds_read_b128 v[118:121], v126 offset:1024
	ds_read_b128 v[122:125], v126 offset:2048
	ds_read_b128 v[126:129], v126 offset:3072
	ds_read_b128 v[138:141], v150
	ds_read_b128 v[142:145], v150 offset:1024
	ds_read_b128 v[146:149], v150 offset:2048
	ds_read_b128 v[150:153], v150 offset:3072
	s_add_u32 s14, s26, 0xb0000
	s_addc_u32 s15, s27, 0
	s_mov_b32 m0, s59
	v_lshl_add_u64 v[218:219], s[14:15], 0, v[200:201]
	ds_read_b128 v[162:165], v251 offset:32768
	ds_read_b128 v[166:169], v251 offset:33792
	ds_read_b128 v[170:173], v251 offset:34816
	ds_read_b128 v[174:177], v251 offset:35840
	ds_read_b128 v[178:181], v251 offset:36864
	ds_read_b128 v[182:185], v251 offset:37888
	ds_read_b128 v[186:189], v251 offset:38912
	ds_read_b128 v[190:193], v251 offset:39936
	global_load_lds_dwordx4 v[218:219], off
	v_lshl_add_u64 v[218:219], s[14:15], 0, v[202:203]
	s_mov_b32 m0, s60
	s_nop 0
	global_load_lds_dwordx4 v[218:219], off
	s_waitcnt vmcnt(8)
	s_waitcnt lgkmcnt(0)
	s_barrier
	s_setprio 1
	s_waitcnt lgkmcnt(0)
	v_mfma_f32_16x16x32_bf16 v[158:161], v[114:117], v[162:165], v[158:161]
	v_mfma_f32_16x16x32_bf16 v[154:157], v[122:125], v[162:165], v[154:157]
	v_mfma_f32_16x16x32_bf16 v[110:113], v[114:117], v[170:173], v[110:113]
	v_mfma_f32_16x16x32_bf16 v[106:109], v[122:125], v[170:173], v[106:109]
	v_mfma_f32_16x16x32_bf16 v[92:95], v[114:117], v[178:181], v[92:95]
	v_mfma_f32_16x16x32_bf16 v[88:91], v[122:125], v[178:181], v[88:91]
	v_mfma_f32_16x16x32_bf16 v[76:79], v[114:117], v[186:189], v[76:79]
	v_mfma_f32_16x16x32_bf16 v[72:75], v[122:125], v[186:189], v[72:75]
	v_mfma_f32_16x16x32_bf16 v[158:161], v[118:121], v[166:169], v[158:161]
	v_mfma_f32_16x16x32_bf16 v[154:157], v[126:129], v[166:169], v[154:157]
	v_mfma_f32_16x16x32_bf16 v[110:113], v[118:121], v[174:177], v[110:113]
	v_mfma_f32_16x16x32_bf16 v[106:109], v[126:129], v[174:177], v[106:109]
	v_mfma_f32_16x16x32_bf16 v[92:95], v[118:121], v[182:185], v[92:95]
	v_mfma_f32_16x16x32_bf16 v[88:91], v[126:129], v[182:185], v[88:91]
	v_mfma_f32_16x16x32_bf16 v[76:79], v[118:121], v[190:193], v[76:79]
	v_mfma_f32_16x16x32_bf16 v[72:75], v[126:129], v[190:193], v[72:75]
	s_setprio 0
	s_setprio 1
	v_mfma_f32_16x16x32_bf16 v[134:137], v[138:141], v[162:165], v[134:137]
	v_mfma_f32_16x16x32_bf16 v[130:133], v[146:149], v[162:165], v[130:133]
	v_mfma_f32_16x16x32_bf16 v[102:105], v[138:141], v[170:173], v[102:105]
	v_mfma_f32_16x16x32_bf16 v[98:101], v[146:149], v[170:173], v[98:101]
	v_mfma_f32_16x16x32_bf16 v[84:87], v[138:141], v[178:181], v[84:87]
	v_mfma_f32_16x16x32_bf16 v[80:83], v[146:149], v[178:181], v[80:83]
	v_mfma_f32_16x16x32_bf16 v[68:71], v[138:141], v[186:189], v[68:71]
	v_mfma_f32_16x16x32_bf16 v[64:67], v[146:149], v[186:189], v[64:67]
	v_mfma_f32_16x16x32_bf16 v[134:137], v[142:145], v[166:169], v[134:137]
	v_mfma_f32_16x16x32_bf16 v[130:133], v[150:153], v[166:169], v[130:133]
	v_mfma_f32_16x16x32_bf16 v[102:105], v[142:145], v[174:177], v[102:105]
	v_mfma_f32_16x16x32_bf16 v[98:101], v[150:153], v[174:177], v[98:101]
	v_mfma_f32_16x16x32_bf16 v[84:87], v[142:145], v[182:185], v[84:87]
	v_mfma_f32_16x16x32_bf16 v[80:83], v[150:153], v[182:185], v[80:83]
	v_mfma_f32_16x16x32_bf16 v[68:71], v[142:145], v[190:193], v[68:71]
	v_mfma_f32_16x16x32_bf16 v[64:67], v[150:153], v[190:193], v[64:67]
	s_setprio 0
	s_barrier
	s_add_i32 s2, s2, s43
	v_lshl_add_u64 v[210:211], v[210:211], 0, s[22:23]
	s_mov_b32 m0, s2
	ds_read_b128 v[162:165], v251 offset:49152
	ds_read_b128 v[166:169], v251 offset:50176
	ds_read_b128 v[170:173], v251 offset:51200
	ds_read_b128 v[174:177], v251 offset:52224
	ds_read_b128 v[178:181], v251 offset:53248
	ds_read_b128 v[182:185], v251 offset:54272
	ds_read_b128 v[186:189], v251 offset:55296
	ds_read_b128 v[190:193], v251 offset:56320
	global_load_lds_dwordx4 v[210:211], off
	s_add_i32 m0, s2, 0x2000
	s_add_u32 s14, s24, 0xb0080
	v_lshl_add_u64 v[210:211], v[212:213], 0, s[22:23]
	s_addc_u32 s15, s25, 0
	s_add_i32 s2, s20, s43
	global_load_lds_dwordx4 v[210:211], off
	v_lshl_add_u64 v[210:211], s[14:15], 0, v[96:97]
	s_mov_b32 m0, s2
	s_nop 0
	global_load_lds_dwordx4 v[210:211], off
	v_lshl_add_u64 v[210:211], s[14:15], 0, v[204:205]
	s_add_i32 m0, s2, 0x2000
	s_nop 0
	global_load_lds_dwordx4 v[210:211], off
	v_lshl_add_u64 v[210:211], v[214:215], 0, s[22:23]
	s_mov_b32 m0, s18
	s_nop 0
	global_load_lds_dwordx4 v[210:211], off
	v_lshl_add_u64 v[210:211], v[216:217], 0, s[22:23]
	s_mov_b32 m0, s19
	s_nop 0
	global_load_lds_dwordx4 v[210:211], off
	s_waitcnt vmcnt(8)
	s_waitcnt lgkmcnt(0)
	s_barrier
	s_setprio 1
	s_waitcnt lgkmcnt(0)
	v_mfma_f32_16x16x32_bf16 v[60:63], v[114:117], v[162:165], v[60:63]
	v_mfma_f32_16x16x32_bf16 v[56:59], v[122:125], v[162:165], v[56:59]
	v_mfma_f32_16x16x32_bf16 v[44:47], v[114:117], v[170:173], v[44:47]
	v_mfma_f32_16x16x32_bf16 v[40:43], v[122:125], v[170:173], v[40:43]
	v_mfma_f32_16x16x32_bf16 v[28:31], v[114:117], v[178:181], v[28:31]
	v_mfma_f32_16x16x32_bf16 v[24:27], v[122:125], v[178:181], v[24:27]
	v_mfma_f32_16x16x32_bf16 v[12:15], v[114:117], v[186:189], v[12:15]
	v_mfma_f32_16x16x32_bf16 v[8:11], v[122:125], v[186:189], v[8:11]
	v_mfma_f32_16x16x32_bf16 v[60:63], v[118:121], v[166:169], v[60:63]
	v_mfma_f32_16x16x32_bf16 v[56:59], v[126:129], v[166:169], v[56:59]
	v_mfma_f32_16x16x32_bf16 v[44:47], v[118:121], v[174:177], v[44:47]
	v_mfma_f32_16x16x32_bf16 v[40:43], v[126:129], v[174:177], v[40:43]
	v_mfma_f32_16x16x32_bf16 v[28:31], v[118:121], v[182:185], v[28:31]
	v_mfma_f32_16x16x32_bf16 v[24:27], v[126:129], v[182:185], v[24:27]
	v_mfma_f32_16x16x32_bf16 v[12:15], v[118:121], v[190:193], v[12:15]
	v_mfma_f32_16x16x32_bf16 v[8:11], v[126:129], v[190:193], v[8:11]
	s_setprio 0
	s_setprio 1
	v_mfma_f32_16x16x32_bf16 v[52:55], v[138:141], v[162:165], v[52:55]
	v_mfma_f32_16x16x32_bf16 v[48:51], v[146:149], v[162:165], v[48:51]
	v_mfma_f32_16x16x32_bf16 v[36:39], v[138:141], v[170:173], v[36:39]
	v_mfma_f32_16x16x32_bf16 v[32:35], v[146:149], v[170:173], v[32:35]
	v_mfma_f32_16x16x32_bf16 v[20:23], v[138:141], v[178:181], v[20:23]
	v_mfma_f32_16x16x32_bf16 v[16:19], v[146:149], v[178:181], v[16:19]
	v_mfma_f32_16x16x32_bf16 v[4:7], v[138:141], v[186:189], v[4:7]
	v_mfma_f32_16x16x32_bf16 v[0:3], v[146:149], v[186:189], v[0:3]
	v_mfma_f32_16x16x32_bf16 v[52:55], v[142:145], v[166:169], v[52:55]
	v_mfma_f32_16x16x32_bf16 v[48:51], v[150:153], v[166:169], v[48:51]
	v_mfma_f32_16x16x32_bf16 v[36:39], v[142:145], v[174:177], v[36:39]
	v_mfma_f32_16x16x32_bf16 v[32:35], v[150:153], v[174:177], v[32:35]
	v_mfma_f32_16x16x32_bf16 v[20:23], v[142:145], v[182:185], v[20:23]
	v_mfma_f32_16x16x32_bf16 v[16:19], v[150:153], v[182:185], v[16:19]
	v_mfma_f32_16x16x32_bf16 v[4:7], v[142:145], v[190:193], v[4:7]
	v_mfma_f32_16x16x32_bf16 v[0:3], v[150:153], v[190:193], v[0:3]
	s_setprio 0
	s_barrier
	s_add_i32 s80, s80, 2
	s_add_u32 s8, s8, 0x100
	s_addc_u32 s79, s79, 0
	s_cmp_gt_u32 s80, 41
	s_mov_b64 s[72:73], s[74:75]
	s_cbranch_scc0 .LBB0_552
	v_mov_b64_e32 v[252:253], 0x200
	v_lshl_or_b32 v210, s42, 8, v250
	v_lshl_add_u32 v240, s16, 8, v199
	v_ashrrev_i32_e32 v211, 31, v210
	v_lshlrev_b64 v[242:243], 1, v[210:211]
	v_ashrrev_i32_e32 v241, 31, v240
	v_lshl_add_u64 v[118:119], s[52:53], 0, v[242:243]
	v_lshlrev_b64 v[244:245], 11, v[240:241]
	v_lshl_add_u64 v[114:115], v[118:119], 0, v[244:245]
	global_load_dwordx4 v[190:193], v[114:115], off
	global_load_dwordx4 v[186:189], v[114:115], off offset:256
	v_or_b32_e32 v236, 16, v240
	v_ashrrev_i32_e32 v237, 31, v236
	v_or_b32_e32 v232, 32, v240
	v_lshlrev_b64 v[238:239], 11, v[236:237]
	v_ashrrev_i32_e32 v233, 31, v232
	v_or_b32_e32 v228, 48, v240
	v_lshl_add_u64 v[114:115], v[118:119], 0, v[238:239]
	v_lshlrev_b64 v[234:235], 11, v[232:233]
	v_ashrrev_i32_e32 v229, 31, v228
	v_add_u32_e32 v224, 0x80, v240
	global_load_dwordx4 v[182:185], v[114:115], off
	global_load_dwordx4 v[178:181], v[114:115], off offset:256
	v_lshl_add_u64 v[114:115], v[118:119], 0, v[234:235]
	v_lshlrev_b64 v[230:231], 11, v[228:229]
	v_ashrrev_i32_e32 v225, 31, v224
	v_add_u32_e32 v220, 0x90, v240
	global_load_dwordx4 v[174:177], v[114:115], off
	global_load_dwordx4 v[170:173], v[114:115], off offset:256
	v_lshl_add_u64 v[114:115], v[118:119], 0, v[230:231]
	v_lshlrev_b64 v[226:227], 11, v[224:225]
	v_ashrrev_i32_e32 v221, 31, v220
	v_add_u32_e32 v216, 0xa0, v240
	v_add_u32_e32 v212, 0xb0, v240
	global_load_dwordx4 v[166:169], v[114:115], off
	global_load_dwordx4 v[162:165], v[114:115], off offset:256
	v_lshl_add_u64 v[114:115], v[118:119], 0, v[226:227]
	v_lshlrev_b64 v[222:223], 11, v[220:221]
	v_ashrrev_i32_e32 v217, 31, v216
	v_ashrrev_i32_e32 v213, 31, v212
	global_load_dwordx4 v[150:153], v[114:115], off
	global_load_dwordx4 v[146:149], v[114:115], off offset:256
	v_lshl_add_u64 v[114:115], v[118:119], 0, v[222:223]
	v_lshlrev_b64 v[218:219], 11, v[216:217]
	v_lshlrev_b64 v[214:215], 11, v[212:213]
	global_load_dwordx4 v[142:145], v[114:115], off
	global_load_dwordx4 v[138:141], v[114:115], off offset:256
	v_lshl_add_u64 v[114:115], v[118:119], 0, v[218:219]
	v_lshl_add_u64 v[118:119], v[118:119], 0, v[214:215]
	global_load_dwordx4 v[122:125], v[114:115], off
	global_load_dwordx4 v[114:117], v[114:115], off offset:256
	global_load_dwordx4 v[126:129], v[118:119], off
	global_load_dwordx4 v[118:121], v[118:119], off offset:256
	s_and_b64 vcc, exec, s[66:67]
	s_cbranch_vccz .LBB0_555
	s_barrier
.LBB0_555:
	s_nop 0
	s_nop 0
	s_nop 0
	s_waitcnt vmcnt(0)
	v_lshlrev_b32_e32 v194, 16, v190
	v_and_b32_e32 v195, 0xffff0000, v190
	v_lshlrev_b32_e32 v190, 16, v191
	v_and_b32_e32 v191, 0xffff0000, v191
	v_lshlrev_b32_e32 v196, 16, v192
	v_and_b32_e32 v197, 0xffff0000, v192
	v_lshlrev_b32_e32 v192, 16, v193
	v_and_b32_e32 v193, 0xffff0000, v193
	v_pk_fma_f32 v[158:159], v[158:159], 0.5, v[194:195] op_sel_hi:[1,0,1]
	v_lshl_add_u64 v[194:195], s[52:53], 0, v[244:245]
	v_pk_fma_f32 v[160:161], v[160:161], 0.5, v[190:191] op_sel_hi:[1,0,1]
	v_pk_fma_f32 v[190:191], v[156:157], 0.5, v[192:193] op_sel_hi:[1,0,1]
	v_pk_fma_f32 v[192:193], v[154:155], 0.5, v[196:197] op_sel_hi:[1,0,1]
	v_cvt_pk_bf16_f32 v154, v158, v159
	v_cvt_pk_bf16_f32 v155, v160, v161
	v_lshl_add_u64 v[194:195], v[194:195], 0, v[242:243]
	v_cvt_pk_bf16_f32 v156, v192, v193
	v_cvt_pk_bf16_f32 v157, v190, v191
	global_store_dwordx4 v[194:195], v[154:157], off
	s_nop 1
	v_mul_f32_e32 v154, v159, v159
	v_mul_f32_e32 v155, v161, v161
	v_fmac_f32_e32 v154, v158, v158
	v_fmac_f32_e32 v155, v160, v160
	v_add_f32_e32 v154, v154, v155
	v_mul_f32_e32 v155, v193, v193
	v_mul_f32_e32 v156, v191, v191
	v_fmac_f32_e32 v155, v192, v192
	v_fmac_f32_e32 v156, v190, v190
	v_add_f32_e32 v155, v155, v156
	v_add_f32_e32 v190, v154, v155
	v_lshlrev_b32_e32 v154, 16, v186
	v_and_b32_e32 v155, 0xffff0000, v186
	v_lshlrev_b32_e32 v156, 16, v187
	v_and_b32_e32 v157, 0xffff0000, v187
	v_lshlrev_b32_e32 v158, 16, v188
	v_and_b32_e32 v159, 0xffff0000, v188
	v_lshlrev_b32_e32 v160, 16, v189
	v_and_b32_e32 v161, 0xffff0000, v189
	v_pk_fma_f32 v[136:137], v[136:137], 0.5, v[156:157] op_sel_hi:[1,0,1]
	v_pk_fma_f32 v[134:135], v[134:135], 0.5, v[154:155] op_sel_hi:[1,0,1]
	v_pk_fma_f32 v[156:157], v[130:131], 0.5, v[158:159] op_sel_hi:[1,0,1]
	v_cvt_pk_bf16_f32 v130, v134, v135
	v_cvt_pk_bf16_f32 v131, v136, v137
	v_pk_fma_f32 v[154:155], v[132:133], 0.5, v[160:161] op_sel_hi:[1,0,1]
	v_cvt_pk_bf16_f32 v132, v156, v157
	s_nop 0
	v_cvt_pk_bf16_f32 v133, v154, v155
	global_store_dwordx4 v[194:195], v[130:133], off offset:256
	s_nop 1
	v_mul_f32_e32 v130, v135, v135
	v_mul_f32_e32 v131, v137, v137
	v_fmac_f32_e32 v130, v134, v134
	v_fmac_f32_e32 v131, v136, v136
	v_add_f32_e32 v130, v130, v131
	v_mul_f32_e32 v131, v157, v157
	v_mul_f32_e32 v132, v155, v155
	v_fmac_f32_e32 v131, v156, v156
	v_fmac_f32_e32 v132, v154, v154
	v_add_f32_e32 v131, v131, v132
	v_add_f32_e32 v130, v130, v131
	v_and_b32_e32 v132, 64, v248
	v_add_f32_e32 v131, v190, v130
	v_xor_b32_e32 v130, 16, v248
	v_add_u32_e32 v133, 64, v132
	v_cmp_lt_i32_e32 vcc, v130, v133
	s_nop 1
	v_cndmask_b32_e32 v130, v248, v130, vcc
	v_lshlrev_b32_e32 v130, 2, v130
	ds_bpermute_b32 v132, v130, v131
	s_waitcnt lgkmcnt(0)
	v_add_f32_e32 v132, v131, v132
	v_xor_b32_e32 v131, 32, v248
	v_cmp_lt_i32_e32 vcc, v131, v133
	s_nop 1
	v_cndmask_b32_e32 v131, v248, v131, vcc
	v_lshlrev_b32_e32 v131, 2, v131
	ds_bpermute_b32 v133, v131, v132
	s_and_saveexec_b64 s[24:25], s[0:1]
	s_cbranch_execz .LBB0_557
	s_waitcnt lgkmcnt(0)
	v_add_f32_e32 v134, v132, v133
	s_lshl_b32 s14, s42, 2
	v_lshlrev_b64 v[132:133], 6, v[240:241]
	s_ashr_i32 s15, s14, 31
	v_lshl_add_u64 v[132:133], s[56:57], 0, v[132:133]
	v_lshl_add_u64 v[132:133], s[14:15], 2, v[132:133]
	s_lshl_b32 s16, s61, 2
	v_lshl_add_u64 v[132:133], v[132:133], 0, s[16:17]
	global_store_dword v[132:133], v134, off

.LBB0_598:
	s_add_u32 s72, s70, 0x100
	s_addc_u32 s73, s71, 0
	s_add_i32 s2, 0, 0x10000
	s_cmp_eq_u32 s77, 40
	s_cselect_b32 s27, s5, s73
	s_cselect_b32 s26, s4, s72
	s_cselect_b32 s25, s67, s76
	s_cselect_b32 s24, s66, s8
	s_add_i32 s20, 0, 0x14000
	v_add_u32_e32 v142, s2, v224
	v_add_u32_e32 v158, s20, v224
	ds_read_b128 v[130:133], v142
	ds_read_b128 v[134:137], v142 offset:1024
	ds_read_b128 v[138:141], v142 offset:2048
	ds_read_b128 v[142:145], v142 offset:3072
	ds_read_b128 v[146:149], v158
	ds_read_b128 v[150:153], v158 offset:1024
	ds_read_b128 v[154:157], v158 offset:2048
	ds_read_b128 v[158:161], v158 offset:3072
	v_lshl_add_u64 v[210:211], s[70:71], 0, v[204:205]
	s_add_i32 m0, s39, 0xc000
	ds_read_b128 v[162:165], v226
	ds_read_b128 v[166:169], v226 offset:1024
	ds_read_b128 v[170:173], v226 offset:2048
	ds_read_b128 v[174:177], v226 offset:3072
	ds_read_b128 v[178:181], v226 offset:4096
	ds_read_b128 v[182:185], v226 offset:5120
	ds_read_b128 v[186:189], v226 offset:6144
	ds_read_b128 v[206:209], v226 offset:7168
	global_load_lds_dwordx4 v[210:211], off
	v_lshl_add_u64 v[210:211], s[70:71], 0, v[202:203]
	s_add_i32 m0, s39, 0xe000
	s_nop 0
	global_load_lds_dwordx4 v[210:211], off
	s_waitcnt vmcnt(8)
	s_waitcnt lgkmcnt(0)
	s_barrier
	s_setprio 1
	s_waitcnt lgkmcnt(0)
	v_mfma_f32_16x16x32_bf16 v[126:129], v[130:133], v[162:165], v[126:129]
	v_mfma_f32_16x16x32_bf16 v[122:125], v[138:141], v[162:165], v[122:125]
	v_mfma_f32_16x16x32_bf16 v[110:113], v[130:133], v[170:173], v[110:113]
	v_mfma_f32_16x16x32_bf16 v[106:109], v[138:141], v[170:173], v[106:109]
	v_mfma_f32_16x16x32_bf16 v[98:101], v[130:133], v[178:181], v[98:101]
	v_mfma_f32_16x16x32_bf16 v[88:91], v[138:141], v[178:181], v[88:91]
	v_mfma_f32_16x16x32_bf16 v[80:83], v[130:133], v[186:189], v[80:83]
	v_mfma_f32_16x16x32_bf16 v[72:75], v[138:141], v[186:189], v[72:75]
	v_mfma_f32_16x16x32_bf16 v[126:129], v[134:137], v[166:169], v[126:129]
	v_mfma_f32_16x16x32_bf16 v[122:125], v[142:145], v[166:169], v[122:125]
	v_mfma_f32_16x16x32_bf16 v[110:113], v[134:137], v[174:177], v[110:113]
	v_mfma_f32_16x16x32_bf16 v[106:109], v[142:145], v[174:177], v[106:109]
	v_mfma_f32_16x16x32_bf16 v[98:101], v[134:137], v[182:185], v[98:101]
	v_mfma_f32_16x16x32_bf16 v[88:91], v[142:145], v[182:185], v[88:91]
	v_mfma_f32_16x16x32_bf16 v[80:83], v[134:137], v[206:209], v[80:83]
	v_mfma_f32_16x16x32_bf16 v[72:75], v[142:145], v[206:209], v[72:75]
	s_setprio 0
	s_setprio 1
	v_mfma_f32_16x16x32_bf16 v[118:121], v[146:149], v[162:165], v[118:121]
	v_mfma_f32_16x16x32_bf16 v[114:117], v[154:157], v[162:165], v[114:117]
	v_mfma_f32_16x16x32_bf16 v[102:105], v[146:149], v[170:173], v[102:105]
	v_mfma_f32_16x16x32_bf16 v[92:95], v[154:157], v[170:173], v[92:95]
	v_mfma_f32_16x16x32_bf16 v[84:87], v[146:149], v[178:181], v[84:87]
	v_mfma_f32_16x16x32_bf16 v[76:79], v[154:157], v[178:181], v[76:79]
	v_mfma_f32_16x16x32_bf16 v[68:71], v[146:149], v[186:189], v[68:71]
	v_mfma_f32_16x16x32_bf16 v[64:67], v[154:157], v[186:189], v[64:67]
	v_mfma_f32_16x16x32_bf16 v[118:121], v[150:153], v[166:169], v[118:121]
	v_mfma_f32_16x16x32_bf16 v[114:117], v[158:161], v[166:169], v[114:117]
	v_mfma_f32_16x16x32_bf16 v[102:105], v[150:153], v[174:177], v[102:105]
	v_mfma_f32_16x16x32_bf16 v[92:95], v[158:161], v[174:177], v[92:95]
	v_mfma_f32_16x16x32_bf16 v[84:87], v[150:153], v[182:185], v[84:87]
	v_mfma_f32_16x16x32_bf16 v[76:79], v[158:161], v[182:185], v[76:79]
	v_mfma_f32_16x16x32_bf16 v[68:71], v[150:153], v[206:209], v[68:71]
	v_mfma_f32_16x16x32_bf16 v[64:67], v[158:161], v[206:209], v[64:67]
	s_setprio 0
	s_barrier
	s_add_i32 s2, s2, s38
	v_lshl_add_u64 v[210:211], s[24:25], 0, v[96:97]
	s_mov_b32 m0, s2
	ds_read_b128 v[162:165], v226 offset:16384
	ds_read_b128 v[166:169], v226 offset:17408
	ds_read_b128 v[170:173], v226 offset:18432
	ds_read_b128 v[174:177], v226 offset:19456
	ds_read_b128 v[178:181], v226 offset:20480
	ds_read_b128 v[182:185], v226 offset:21504
	ds_read_b128 v[186:189], v226 offset:22528
	ds_read_b128 v[206:209], v226 offset:23552
	global_load_lds_dwordx4 v[210:211], off
	s_add_i32 m0, s2, 0x2000
	s_add_u32 s14, s24, 0xb0000
	v_lshl_add_u64 v[212:213], s[24:25], 0, v[200:201]
	s_addc_u32 s15, s25, 0
	s_add_i32 s2, s20, s38
	global_load_lds_dwordx4 v[212:213], off
	v_lshl_add_u64 v[214:215], s[14:15], 0, v[96:97]
	s_mov_b32 m0, s2
	v_lshl_add_u64 v[216:217], s[26:27], 0, v[192:193]
	global_load_lds_dwordx4 v[214:215], off
	v_lshl_add_u64 v[214:215], s[14:15], 0, v[200:201]
	s_add_i32 m0, s2, 0x2000
	s_nop 0
	global_load_lds_dwordx4 v[214:215], off
	v_lshl_add_u64 v[214:215], s[26:27], 0, v[190:191]
	s_mov_b32 m0, s39
	s_nop 0
	global_load_lds_dwordx4 v[214:215], off
	s_mov_b32 m0, s42
	s_nop 0
	global_load_lds_dwordx4 v[216:217], off
	s_waitcnt vmcnt(8)
	s_waitcnt lgkmcnt(0)
	s_barrier
	s_setprio 1
	s_waitcnt lgkmcnt(0)
	v_mfma_f32_16x16x32_bf16 v[60:63], v[130:133], v[162:165], v[60:63]
	v_mfma_f32_16x16x32_bf16 v[56:59], v[138:141], v[162:165], v[56:59]
	v_mfma_f32_16x16x32_bf16 v[48:51], v[130:133], v[170:173], v[48:51]
	v_mfma_f32_16x16x32_bf16 v[40:43], v[138:141], v[170:173], v[40:43]
	v_mfma_f32_16x16x32_bf16 v[32:35], v[130:133], v[178:181], v[32:35]
	v_mfma_f32_16x16x32_bf16 v[24:27], v[138:141], v[178:181], v[24:27]
	v_mfma_f32_16x16x32_bf16 v[16:19], v[130:133], v[186:189], v[16:19]
	v_mfma_f32_16x16x32_bf16 v[8:11], v[138:141], v[186:189], v[8:11]
	v_mfma_f32_16x16x32_bf16 v[60:63], v[134:137], v[166:169], v[60:63]
	v_mfma_f32_16x16x32_bf16 v[56:59], v[142:145], v[166:169], v[56:59]
	v_mfma_f32_16x16x32_bf16 v[48:51], v[134:137], v[174:177], v[48:51]
	v_mfma_f32_16x16x32_bf16 v[40:43], v[142:145], v[174:177], v[40:43]
	v_mfma_f32_16x16x32_bf16 v[32:35], v[134:137], v[182:185], v[32:35]
	v_mfma_f32_16x16x32_bf16 v[24:27], v[142:145], v[182:185], v[24:27]
	v_mfma_f32_16x16x32_bf16 v[16:19], v[134:137], v[206:209], v[16:19]
	v_mfma_f32_16x16x32_bf16 v[8:11], v[142:145], v[206:209], v[8:11]
	s_setprio 0
	s_setprio 1
	v_mfma_f32_16x16x32_bf16 v[52:55], v[146:149], v[162:165], v[52:55]
	v_mfma_f32_16x16x32_bf16 v[44:47], v[154:157], v[162:165], v[44:47]
	v_mfma_f32_16x16x32_bf16 v[36:39], v[146:149], v[170:173], v[36:39]
	v_mfma_f32_16x16x32_bf16 v[28:31], v[154:157], v[170:173], v[28:31]
	v_mfma_f32_16x16x32_bf16 v[20:23], v[146:149], v[178:181], v[20:23]
	v_mfma_f32_16x16x32_bf16 v[12:15], v[154:157], v[178:181], v[12:15]
	v_mfma_f32_16x16x32_bf16 v[4:7], v[146:149], v[186:189], v[4:7]
	v_mfma_f32_16x16x32_bf16 v[0:3], v[154:157], v[186:189], v[0:3]
	v_mfma_f32_16x16x32_bf16 v[52:55], v[150:153], v[166:169], v[52:55]
	v_mfma_f32_16x16x32_bf16 v[44:47], v[158:161], v[166:169], v[44:47]
	v_mfma_f32_16x16x32_bf16 v[36:39], v[150:153], v[174:177], v[36:39]
	v_mfma_f32_16x16x32_bf16 v[28:31], v[158:161], v[174:177], v[28:31]
	v_mfma_f32_16x16x32_bf16 v[20:23], v[150:153], v[182:185], v[20:23]
	v_mfma_f32_16x16x32_bf16 v[12:15], v[158:161], v[182:185], v[12:15]
	v_mfma_f32_16x16x32_bf16 v[4:7], v[150:153], v[206:209], v[4:7]
	v_mfma_f32_16x16x32_bf16 v[0:3], v[158:161], v[206:209], v[0:3]
	s_setprio 0
	s_barrier
	s_add_i32 s2, 0, 0x18000
	s_add_i32 s20, 0, 0x1c000
	v_add_u32_e32 v142, s2, v224
	v_add_u32_e32 v158, s20, v224
	ds_read_b128 v[130:133], v142
	ds_read_b128 v[134:137], v142 offset:1024
	ds_read_b128 v[138:141], v142 offset:2048
	ds_read_b128 v[142:145], v142 offset:3072
	ds_read_b128 v[146:149], v158
	ds_read_b128 v[150:153], v158 offset:1024
	ds_read_b128 v[154:157], v158 offset:2048
	ds_read_b128 v[158:161], v158 offset:3072
	s_add_u32 s14, s26, 0xb0000
	s_addc_u32 s15, s27, 0
	s_mov_b32 m0, s43
	v_lshl_add_u64 v[218:219], s[14:15], 0, v[190:191]
	ds_read_b128 v[162:165], v226 offset:32768
	ds_read_b128 v[166:169], v226 offset:33792
	ds_read_b128 v[170:173], v226 offset:34816
	ds_read_b128 v[174:177], v226 offset:35840
	ds_read_b128 v[178:181], v226 offset:36864
	ds_read_b128 v[182:185], v226 offset:37888
	ds_read_b128 v[186:189], v226 offset:38912
	ds_read_b128 v[206:209], v226 offset:39936
	global_load_lds_dwordx4 v[218:219], off
	v_lshl_add_u64 v[218:219], s[14:15], 0, v[192:193]
	s_mov_b32 m0, s45
	s_nop 0
	global_load_lds_dwordx4 v[218:219], off
	s_waitcnt vmcnt(8)
	s_waitcnt lgkmcnt(0)
	s_barrier
	s_setprio 1
	s_waitcnt lgkmcnt(0)
	v_mfma_f32_16x16x32_bf16 v[126:129], v[130:133], v[162:165], v[126:129]
	v_mfma_f32_16x16x32_bf16 v[122:125], v[138:141], v[162:165], v[122:125]
	v_mfma_f32_16x16x32_bf16 v[110:113], v[130:133], v[170:173], v[110:113]
	v_mfma_f32_16x16x32_bf16 v[106:109], v[138:141], v[170:173], v[106:109]
	v_mfma_f32_16x16x32_bf16 v[98:101], v[130:133], v[178:181], v[98:101]
	v_mfma_f32_16x16x32_bf16 v[88:91], v[138:141], v[178:181], v[88:91]
	v_mfma_f32_16x16x32_bf16 v[80:83], v[130:133], v[186:189], v[80:83]
	v_mfma_f32_16x16x32_bf16 v[72:75], v[138:141], v[186:189], v[72:75]
	v_mfma_f32_16x16x32_bf16 v[126:129], v[134:137], v[166:169], v[126:129]
	v_mfma_f32_16x16x32_bf16 v[122:125], v[142:145], v[166:169], v[122:125]
	v_mfma_f32_16x16x32_bf16 v[110:113], v[134:137], v[174:177], v[110:113]
	v_mfma_f32_16x16x32_bf16 v[106:109], v[142:145], v[174:177], v[106:109]
	v_mfma_f32_16x16x32_bf16 v[98:101], v[134:137], v[182:185], v[98:101]
	v_mfma_f32_16x16x32_bf16 v[88:91], v[142:145], v[182:185], v[88:91]
	v_mfma_f32_16x16x32_bf16 v[80:83], v[134:137], v[206:209], v[80:83]
	v_mfma_f32_16x16x32_bf16 v[72:75], v[142:145], v[206:209], v[72:75]
	s_setprio 0
	s_setprio 1
	v_mfma_f32_16x16x32_bf16 v[118:121], v[146:149], v[162:165], v[118:121]
	v_mfma_f32_16x16x32_bf16 v[114:117], v[154:157], v[162:165], v[114:117]
	v_mfma_f32_16x16x32_bf16 v[102:105], v[146:149], v[170:173], v[102:105]
	v_mfma_f32_16x16x32_bf16 v[92:95], v[154:157], v[170:173], v[92:95]
	v_mfma_f32_16x16x32_bf16 v[84:87], v[146:149], v[178:181], v[84:87]
	v_mfma_f32_16x16x32_bf16 v[76:79], v[154:157], v[178:181], v[76:79]
	v_mfma_f32_16x16x32_bf16 v[68:71], v[146:149], v[186:189], v[68:71]
	v_mfma_f32_16x16x32_bf16 v[64:67], v[154:157], v[186:189], v[64:67]
	v_mfma_f32_16x16x32_bf16 v[118:121], v[150:153], v[166:169], v[118:121]
	v_mfma_f32_16x16x32_bf16 v[114:117], v[158:161], v[166:169], v[114:117]
	v_mfma_f32_16x16x32_bf16 v[102:105], v[150:153], v[174:177], v[102:105]
	v_mfma_f32_16x16x32_bf16 v[92:95], v[158:161], v[174:177], v[92:95]
	v_mfma_f32_16x16x32_bf16 v[84:87], v[150:153], v[182:185], v[84:87]
	v_mfma_f32_16x16x32_bf16 v[76:79], v[158:161], v[182:185], v[76:79]
	v_mfma_f32_16x16x32_bf16 v[68:71], v[150:153], v[206:209], v[68:71]
	v_mfma_f32_16x16x32_bf16 v[64:67], v[158:161], v[206:209], v[64:67]
	s_setprio 0
	s_barrier
	s_add_i32 s2, s2, s38
	v_lshl_add_u64 v[210:211], v[210:211], 0, s[22:23]
	s_mov_b32 m0, s2
	ds_read_b128 v[162:165], v226 offset:49152
	ds_read_b128 v[166:169], v226 offset:50176
	ds_read_b128 v[170:173], v226 offset:51200
	ds_read_b128 v[174:177], v226 offset:52224
	ds_read_b128 v[178:181], v226 offset:53248
	ds_read_b128 v[182:185], v226 offset:54272
	ds_read_b128 v[186:189], v226 offset:55296
	ds_read_b128 v[206:209], v226 offset:56320
	global_load_lds_dwordx4 v[210:211], off
	s_add_i32 m0, s2, 0x2000
	s_add_u32 s14, s24, 0xb0080
	v_lshl_add_u64 v[210:211], v[212:213], 0, s[22:23]
	s_addc_u32 s15, s25, 0
	s_add_i32 s2, s20, s38
	global_load_lds_dwordx4 v[210:211], off
	v_lshl_add_u64 v[210:211], s[14:15], 0, v[96:97]
	s_mov_b32 m0, s2
	s_nop 0
	global_load_lds_dwordx4 v[210:211], off
	v_lshl_add_u64 v[210:211], s[14:15], 0, v[200:201]
	s_add_i32 m0, s2, 0x2000
	s_nop 0
	global_load_lds_dwordx4 v[210:211], off
	v_lshl_add_u64 v[210:211], v[214:215], 0, s[22:23]
	s_mov_b32 m0, s47
	s_nop 0
	global_load_lds_dwordx4 v[210:211], off
	v_lshl_add_u64 v[210:211], v[216:217], 0, s[22:23]
	s_mov_b32 m0, s59
	s_nop 0
	global_load_lds_dwordx4 v[210:211], off
	s_waitcnt vmcnt(8)
	s_waitcnt lgkmcnt(0)
	s_barrier
	s_setprio 1
	s_waitcnt lgkmcnt(0)
	v_mfma_f32_16x16x32_bf16 v[60:63], v[130:133], v[162:165], v[60:63]
	v_mfma_f32_16x16x32_bf16 v[56:59], v[138:141], v[162:165], v[56:59]
	v_mfma_f32_16x16x32_bf16 v[48:51], v[130:133], v[170:173], v[48:51]
	v_mfma_f32_16x16x32_bf16 v[40:43], v[138:141], v[170:173], v[40:43]
	v_mfma_f32_16x16x32_bf16 v[32:35], v[130:133], v[178:181], v[32:35]
	v_mfma_f32_16x16x32_bf16 v[24:27], v[138:141], v[178:181], v[24:27]
	v_mfma_f32_16x16x32_bf16 v[16:19], v[130:133], v[186:189], v[16:19]
	v_mfma_f32_16x16x32_bf16 v[8:11], v[138:141], v[186:189], v[8:11]
	v_mfma_f32_16x16x32_bf16 v[60:63], v[134:137], v[166:169], v[60:63]
	v_mfma_f32_16x16x32_bf16 v[56:59], v[142:145], v[166:169], v[56:59]
	v_mfma_f32_16x16x32_bf16 v[48:51], v[134:137], v[174:177], v[48:51]
	v_mfma_f32_16x16x32_bf16 v[40:43], v[142:145], v[174:177], v[40:43]
	v_mfma_f32_16x16x32_bf16 v[32:35], v[134:137], v[182:185], v[32:35]
	v_mfma_f32_16x16x32_bf16 v[24:27], v[142:145], v[182:185], v[24:27]
	v_mfma_f32_16x16x32_bf16 v[16:19], v[134:137], v[206:209], v[16:19]
	v_mfma_f32_16x16x32_bf16 v[8:11], v[142:145], v[206:209], v[8:11]
	s_setprio 0
	s_setprio 1
	v_mfma_f32_16x16x32_bf16 v[52:55], v[146:149], v[162:165], v[52:55]
	v_mfma_f32_16x16x32_bf16 v[44:47], v[154:157], v[162:165], v[44:47]
	v_mfma_f32_16x16x32_bf16 v[36:39], v[146:149], v[170:173], v[36:39]
	v_mfma_f32_16x16x32_bf16 v[28:31], v[154:157], v[170:173], v[28:31]
	v_mfma_f32_16x16x32_bf16 v[20:23], v[146:149], v[178:181], v[20:23]
	v_mfma_f32_16x16x32_bf16 v[12:15], v[154:157], v[178:181], v[12:15]
	v_mfma_f32_16x16x32_bf16 v[4:7], v[146:149], v[186:189], v[4:7]
	v_mfma_f32_16x16x32_bf16 v[0:3], v[154:157], v[186:189], v[0:3]
	v_mfma_f32_16x16x32_bf16 v[52:55], v[150:153], v[166:169], v[52:55]
	v_mfma_f32_16x16x32_bf16 v[44:47], v[158:161], v[166:169], v[44:47]
	v_mfma_f32_16x16x32_bf16 v[36:39], v[150:153], v[174:177], v[36:39]
	v_mfma_f32_16x16x32_bf16 v[28:31], v[158:161], v[174:177], v[28:31]
	v_mfma_f32_16x16x32_bf16 v[20:23], v[150:153], v[182:185], v[20:23]
	v_mfma_f32_16x16x32_bf16 v[12:15], v[158:161], v[182:185], v[12:15]
	v_mfma_f32_16x16x32_bf16 v[4:7], v[150:153], v[206:209], v[4:7]
	v_mfma_f32_16x16x32_bf16 v[0:3], v[158:161], v[206:209], v[0:3]
	s_setprio 0
	s_barrier
	s_add_i32 s77, s77, 2
	s_add_u32 s8, s8, 0x100
	s_addc_u32 s76, s76, 0
	s_cmp_gt_u32 s77, 41
	s_mov_b64 s[70:71], s[72:73]
	s_cbranch_scc0 .LBB0_598
	v_lshl_add_u32 v222, s74, 8, v199
	v_lshl_or_b32 v220, s75, 8, v225
	v_ashrrev_i32_e32 v221, 31, v220
	v_ashrrev_i32_e32 v223, 31, v222
	v_lshl_add_u64 v[130:131], v[220:221], 1, s[52:53]
	v_lshlrev_b64 v[132:133], 11, v[222:223]
	v_lshl_add_u64 v[132:133], v[130:131], 0, v[132:133]
	global_load_dwordx4 v[228:231], v[132:133], off
	global_load_dwordx4 v[186:189], v[132:133], off offset:256
	v_or_b32_e32 v218, 16, v222
	v_ashrrev_i32_e32 v219, 31, v218
	v_lshlrev_b64 v[132:133], 11, v[218:219]
	v_lshl_add_u64 v[132:133], v[130:131], 0, v[132:133]
	global_load_dwordx4 v[182:185], v[132:133], off
	global_load_dwordx4 v[178:181], v[132:133], off offset:256
	v_or_b32_e32 v216, 32, v222
	v_ashrrev_i32_e32 v217, 31, v216
	v_lshlrev_b64 v[132:133], 11, v[216:217]
	v_lshl_add_u64 v[132:133], v[130:131], 0, v[132:133]
	global_load_dwordx4 v[174:177], v[132:133], off
	global_load_dwordx4 v[170:173], v[132:133], off offset:256
	v_or_b32_e32 v214, 48, v222
	v_ashrrev_i32_e32 v215, 31, v214
	v_lshlrev_b64 v[132:133], 11, v[214:215]
	v_lshl_add_u64 v[132:133], v[130:131], 0, v[132:133]
	global_load_dwordx4 v[166:169], v[132:133], off
	global_load_dwordx4 v[162:165], v[132:133], off offset:256
	v_add_u32_e32 v212, 0x80, v222
	v_ashrrev_i32_e32 v213, 31, v212
	v_lshlrev_b64 v[132:133], 11, v[212:213]
	v_lshl_add_u64 v[132:133], v[130:131], 0, v[132:133]
	global_load_dwordx4 v[158:161], v[132:133], off
	global_load_dwordx4 v[154:157], v[132:133], off offset:256
	v_add_u32_e32 v210, 0x90, v222
	v_ashrrev_i32_e32 v211, 31, v210
	v_lshlrev_b64 v[132:133], 11, v[210:211]
	v_lshl_add_u64 v[132:133], v[130:131], 0, v[132:133]
	global_load_dwordx4 v[150:153], v[132:133], off
	global_load_dwordx4 v[146:149], v[132:133], off offset:256
	v_add_u32_e32 v208, 0xa0, v222
	v_ashrrev_i32_e32 v209, 31, v208
	v_lshlrev_b64 v[132:133], 11, v[208:209]
	v_lshl_add_u64 v[132:133], v[130:131], 0, v[132:133]
	global_load_dwordx4 v[142:145], v[132:133], off
	global_load_dwordx4 v[134:137], v[132:133], off offset:256
	v_add_u32_e32 v206, 0xb0, v222
	v_ashrrev_i32_e32 v207, 31, v206
	v_lshlrev_b64 v[132:133], 11, v[206:207]
	v_lshl_add_u64 v[130:131], v[130:131], 0, v[132:133]
	global_load_dwordx4 v[138:141], v[130:131], off
	global_load_dwordx4 v[130:133], v[130:131], off offset:256
	s_and_b64 vcc, exec, s[64:65]
	s_cbranch_vccz .LBB0_601
	s_barrier
.LBB0_601:
	s_nop 0
	s_mov_b64 s[24:25], -1
	s_and_b64 vcc, exec, s[0:1]
	s_waitcnt vmcnt(0)
	v_lshlrev_b32_e32 v232, 16, v228
	v_and_b32_e32 v233, 0xffff0000, v228
	v_lshlrev_b32_e32 v228, 16, v229
	v_and_b32_e32 v229, 0xffff0000, v229
	v_lshlrev_b32_e32 v234, 16, v230
	v_and_b32_e32 v235, 0xffff0000, v230
	v_lshlrev_b32_e32 v230, 16, v231
	v_and_b32_e32 v231, 0xffff0000, v231
	v_pk_fma_f32 v[128:129], v[128:129], 0.5, v[228:229] op_sel_hi:[1,0,1]
	v_pk_fma_f32 v[228:229], v[122:123], 0.5, v[234:235] op_sel_hi:[1,0,1]
	v_lshlrev_b64 v[122:123], 12, v[222:223]
	v_pk_fma_f32 v[230:231], v[124:125], 0.5, v[230:231] op_sel_hi:[1,0,1]
	v_lshl_add_u64 v[124:125], s[50:51], 0, v[122:123]
	v_lshlrev_b64 v[122:123], 2, v[220:221]
	v_pk_fma_f32 v[126:127], v[126:127], 0.5, v[232:233] op_sel_hi:[1,0,1]
	v_lshl_add_u64 v[124:125], v[124:125], 0, v[122:123]
	global_store_dwordx4 v[124:125], v[126:129], off
	global_store_dwordx4 v[124:125], v[228:231], off offset:16
	s_nop 0
	v_lshlrev_b32_e32 v126, 16, v186
	v_and_b32_e32 v127, 0xffff0000, v186
	v_lshlrev_b32_e32 v128, 16, v187
	v_and_b32_e32 v129, 0xffff0000, v187
	v_lshlrev_b32_e32 v186, 16, v188
	v_and_b32_e32 v187, 0xffff0000, v188
	v_lshlrev_b32_e32 v188, 16, v189
	v_and_b32_e32 v189, 0xffff0000, v189
	v_pk_fma_f32 v[120:121], v[120:121], 0.5, v[128:129] op_sel_hi:[1,0,1]
	v_pk_fma_f32 v[118:119], v[118:119], 0.5, v[126:127] op_sel_hi:[1,0,1]
	v_pk_fma_f32 v[114:115], v[114:115], 0.5, v[186:187] op_sel_hi:[1,0,1]
	v_pk_fma_f32 v[116:117], v[116:117], 0.5, v[188:189] op_sel_hi:[1,0,1]
	global_store_dwordx4 v[124:125], v[118:121], off offset:512
	global_store_dwordx4 v[124:125], v[114:117], off offset:528
	s_nop 0
	v_lshlrev_b32_e32 v118, 16, v184
	v_lshlrev_b32_e32 v114, 16, v182
	v_and_b32_e32 v115, 0xffff0000, v182
	v_pk_fma_f32 v[110:111], v[110:111], 0.5, v[114:115] op_sel_hi:[1,0,1]
	v_lshlrev_b64 v[114:115], 12, v[218:219]
	v_lshlrev_b32_e32 v116, 16, v183
	v_and_b32_e32 v117, 0xffff0000, v183
	v_and_b32_e32 v119, 0xffff0000, v184
	v_lshlrev_b32_e32 v120, 16, v185
	v_and_b32_e32 v121, 0xffff0000, v185
	v_lshl_add_u64 v[114:115], s[50:51], 0, v[114:115]
	v_pk_fma_f32 v[112:113], v[112:113], 0.5, v[116:117] op_sel_hi:[1,0,1]
	v_pk_fma_f32 v[108:109], v[108:109], 0.5, v[120:121] op_sel_hi:[1,0,1]
	v_pk_fma_f32 v[106:107], v[106:107], 0.5, v[118:119] op_sel_hi:[1,0,1]
	v_lshl_add_u64 v[114:115], v[114:115], 0, v[122:123]
	global_store_dwordx4 v[114:115], v[110:113], off
	global_store_dwordx4 v[114:115], v[106:109], off offset:16
	s_nop 0
	v_lshlrev_b32_e32 v110, 16, v180
	v_lshlrev_b32_e32 v106, 16, v178
	v_and_b32_e32 v107, 0xffff0000, v178
	v_lshlrev_b32_e32 v108, 16, v179
	v_and_b32_e32 v109, 0xffff0000, v179
	v_and_b32_e32 v111, 0xffff0000, v180
	v_lshlrev_b32_e32 v112, 16, v181
	v_and_b32_e32 v113, 0xffff0000, v181
	v_pk_fma_f32 v[104:105], v[104:105], 0.5, v[108:109] op_sel_hi:[1,0,1]
	v_pk_fma_f32 v[102:103], v[102:103], 0.5, v[106:107] op_sel_hi:[1,0,1]
	v_pk_fma_f32 v[92:93], v[92:93], 0.5, v[110:111] op_sel_hi:[1,0,1]
	v_pk_fma_f32 v[94:95], v[94:95], 0.5, v[112:113] op_sel_hi:[1,0,1]
	global_store_dwordx4 v[114:115], v[102:105], off offset:512
	global_store_dwordx4 v[114:115], v[92:95], off offset:528
	s_nop 0
	v_lshlrev_b32_e32 v102, 16, v176
	v_lshlrev_b32_e32 v92, 16, v174
	v_and_b32_e32 v93, 0xffff0000, v174
	v_pk_fma_f32 v[92:93], v[98:99], 0.5, v[92:93] op_sel_hi:[1,0,1]
	v_lshlrev_b64 v[98:99], 12, v[216:217]
	v_lshlrev_b32_e32 v94, 16, v175
	v_and_b32_e32 v95, 0xffff0000, v175
	v_and_b32_e32 v103, 0xffff0000, v176
	v_lshlrev_b32_e32 v104, 16, v177
	v_and_b32_e32 v105, 0xffff0000, v177
	v_lshl_add_u64 v[98:99], s[50:51], 0, v[98:99]
	v_pk_fma_f32 v[94:95], v[100:101], 0.5, v[94:95] op_sel_hi:[1,0,1]
	v_pk_fma_f32 v[90:91], v[90:91], 0.5, v[104:105] op_sel_hi:[1,0,1]
	v_pk_fma_f32 v[88:89], v[88:89], 0.5, v[102:103] op_sel_hi:[1,0,1]
	v_lshl_add_u64 v[98:99], v[98:99], 0, v[122:123]
	global_store_dwordx4 v[98:99], v[92:95], off
	global_store_dwordx4 v[98:99], v[88:91], off offset:16
	s_nop 0
	v_lshlrev_b32_e32 v92, 16, v172
	v_lshlrev_b32_e32 v88, 16, v170
	v_and_b32_e32 v89, 0xffff0000, v170
	v_lshlrev_b32_e32 v90, 16, v171
	v_and_b32_e32 v91, 0xffff0000, v171
	v_and_b32_e32 v93, 0xffff0000, v172
	v_lshlrev_b32_e32 v94, 16, v173
	v_and_b32_e32 v95, 0xffff0000, v173
	v_pk_fma_f32 v[86:87], v[86:87], 0.5, v[90:91] op_sel_hi:[1,0,1]
	v_pk_fma_f32 v[84:85], v[84:85], 0.5, v[88:89] op_sel_hi:[1,0,1]
	v_pk_fma_f32 v[76:77], v[76:77], 0.5, v[92:93] op_sel_hi:[1,0,1]
	v_pk_fma_f32 v[78:79], v[78:79], 0.5, v[94:95] op_sel_hi:[1,0,1]
	global_store_dwordx4 v[98:99], v[84:87], off offset:512
	global_store_dwordx4 v[98:99], v[76:79], off offset:528
	s_nop 0
	v_lshlrev_b32_e32 v84, 16, v168
	v_lshlrev_b32_e32 v76, 16, v166
	v_and_b32_e32 v77, 0xffff0000, v166
	v_pk_fma_f32 v[76:77], v[80:81], 0.5, v[76:77] op_sel_hi:[1,0,1]
	v_lshlrev_b64 v[80:81], 12, v[214:215]
	v_lshlrev_b32_e32 v78, 16, v167
	v_and_b32_e32 v79, 0xffff0000, v167
	v_and_b32_e32 v85, 0xffff0000, v168
	v_lshlrev_b32_e32 v86, 16, v169
	v_and_b32_e32 v87, 0xffff0000, v169
	v_lshl_add_u64 v[80:81], s[50:51], 0, v[80:81]
	v_pk_fma_f32 v[78:79], v[82:83], 0.5, v[78:79] op_sel_hi:[1,0,1]
	v_pk_fma_f32 v[74:75], v[74:75], 0.5, v[86:87] op_sel_hi:[1,0,1]
	v_pk_fma_f32 v[72:73], v[72:73], 0.5, v[84:85] op_sel_hi:[1,0,1]
	v_lshl_add_u64 v[80:81], v[80:81], 0, v[122:123]
	global_store_dwordx4 v[80:81], v[76:79], off
	global_store_dwordx4 v[80:81], v[72:75], off offset:16
	s_nop 0
	v_lshlrev_b32_e32 v76, 16, v164
	v_lshlrev_b32_e32 v72, 16, v162
	v_and_b32_e32 v73, 0xffff0000, v162
	v_lshlrev_b32_e32 v74, 16, v163
	v_and_b32_e32 v75, 0xffff0000, v163
	v_and_b32_e32 v77, 0xffff0000, v164
	v_lshlrev_b32_e32 v78, 16, v165
	v_and_b32_e32 v79, 0xffff0000, v165
	v_pk_fma_f32 v[70:71], v[70:71], 0.5, v[74:75] op_sel_hi:[1,0,1]
	v_pk_fma_f32 v[68:69], v[68:69], 0.5, v[72:73] op_sel_hi:[1,0,1]
	v_pk_fma_f32 v[64:65], v[64:65], 0.5, v[76:77] op_sel_hi:[1,0,1]
	v_pk_fma_f32 v[66:67], v[66:67], 0.5, v[78:79] op_sel_hi:[1,0,1]
	global_store_dwordx4 v[80:81], v[68:71], off offset:512
	global_store_dwordx4 v[80:81], v[64:67], off offset:528
	s_nop 0
	v_lshlrev_b32_e32 v68, 16, v160
	v_lshlrev_b32_e32 v64, 16, v158
	v_and_b32_e32 v65, 0xffff0000, v158
	v_pk_fma_f32 v[60:61], v[60:61], 0.5, v[64:65] op_sel_hi:[1,0,1]
	v_lshlrev_b64 v[64:65], 12, v[212:213]
	v_lshlrev_b32_e32 v66, 16, v159
	v_and_b32_e32 v67, 0xffff0000, v159
	v_and_b32_e32 v69, 0xffff0000, v160
	v_lshlrev_b32_e32 v70, 16, v161
	v_and_b32_e32 v71, 0xffff0000, v161
	v_lshl_add_u64 v[64:65], s[50:51], 0, v[64:65]
	v_pk_fma_f32 v[62:63], v[62:63], 0.5, v[66:67] op_sel_hi:[1,0,1]
	v_pk_fma_f32 v[58:59], v[58:59], 0.5, v[70:71] op_sel_hi:[1,0,1]
	v_pk_fma_f32 v[56:57], v[56:57], 0.5, v[68:69] op_sel_hi:[1,0,1]
	v_lshl_add_u64 v[64:65], v[64:65], 0, v[122:123]
	global_store_dwordx4 v[64:65], v[60:63], off
	global_store_dwordx4 v[64:65], v[56:59], off offset:16
	s_nop 0
	v_lshlrev_b32_e32 v60, 16, v156
	v_lshlrev_b32_e32 v56, 16, v154
	v_and_b32_e32 v57, 0xffff0000, v154
	v_lshlrev_b32_e32 v58, 16, v155
	v_and_b32_e32 v59, 0xffff0000, v155
	v_and_b32_e32 v61, 0xffff0000, v156
	v_lshlrev_b32_e32 v62, 16, v157
	v_and_b32_e32 v63, 0xffff0000, v157
	v_pk_fma_f32 v[54:55], v[54:55], 0.5, v[58:59] op_sel_hi:[1,0,1]
	v_pk_fma_f32 v[52:53], v[52:53], 0.5, v[56:57] op_sel_hi:[1,0,1]
	v_pk_fma_f32 v[44:45], v[44:45], 0.5, v[60:61] op_sel_hi:[1,0,1]
	v_pk_fma_f32 v[46:47], v[46:47], 0.5, v[62:63] op_sel_hi:[1,0,1]
	global_store_dwordx4 v[64:65], v[52:55], off offset:512
	global_store_dwordx4 v[64:65], v[44:47], off offset:528
	s_nop 0
	v_lshlrev_b32_e32 v52, 16, v152
	v_lshlrev_b32_e32 v44, 16, v150
	v_and_b32_e32 v45, 0xffff0000, v150
	v_pk_fma_f32 v[44:45], v[48:49], 0.5, v[44:45] op_sel_hi:[1,0,1]
	v_lshlrev_b64 v[48:49], 12, v[210:211]
	v_lshlrev_b32_e32 v46, 16, v151
	v_and_b32_e32 v47, 0xffff0000, v151
	v_and_b32_e32 v53, 0xffff0000, v152
	v_lshlrev_b32_e32 v54, 16, v153
	v_and_b32_e32 v55, 0xffff0000, v153
	v_lshl_add_u64 v[48:49], s[50:51], 0, v[48:49]
	v_pk_fma_f32 v[46:47], v[50:51], 0.5, v[46:47] op_sel_hi:[1,0,1]
	v_pk_fma_f32 v[42:43], v[42:43], 0.5, v[54:55] op_sel_hi:[1,0,1]
	v_pk_fma_f32 v[40:41], v[40:41], 0.5, v[52:53] op_sel_hi:[1,0,1]
	v_lshl_add_u64 v[48:49], v[48:49], 0, v[122:123]
	global_store_dwordx4 v[48:49], v[44:47], off
	global_store_dwordx4 v[48:49], v[40:43], off offset:16
	s_nop 0
	v_lshlrev_b32_e32 v44, 16, v148
	v_lshlrev_b32_e32 v40, 16, v146
	v_and_b32_e32 v41, 0xffff0000, v146
	v_lshlrev_b32_e32 v42, 16, v147
	v_and_b32_e32 v43, 0xffff0000, v147
	v_and_b32_e32 v45, 0xffff0000, v148
	v_lshlrev_b32_e32 v46, 16, v149
	v_and_b32_e32 v47, 0xffff0000, v149
	v_pk_fma_f32 v[38:39], v[38:39], 0.5, v[42:43] op_sel_hi:[1,0,1]
	v_pk_fma_f32 v[36:37], v[36:37], 0.5, v[40:41] op_sel_hi:[1,0,1]
	v_pk_fma_f32 v[28:29], v[28:29], 0.5, v[44:45] op_sel_hi:[1,0,1]
	v_pk_fma_f32 v[30:31], v[30:31], 0.5, v[46:47] op_sel_hi:[1,0,1]
	global_store_dwordx4 v[48:49], v[36:39], off offset:512
	global_store_dwordx4 v[48:49], v[28:31], off offset:528
	s_nop 0
	v_lshlrev_b32_e32 v36, 16, v144
	v_lshlrev_b32_e32 v28, 16, v142
	v_and_b32_e32 v29, 0xffff0000, v142
	v_pk_fma_f32 v[28:29], v[32:33], 0.5, v[28:29] op_sel_hi:[1,0,1]
	v_lshlrev_b64 v[32:33], 12, v[208:209]
	v_lshlrev_b32_e32 v30, 16, v143
	v_and_b32_e32 v31, 0xffff0000, v143
	v_and_b32_e32 v37, 0xffff0000, v144
	v_lshlrev_b32_e32 v38, 16, v145
	v_and_b32_e32 v39, 0xffff0000, v145
	v_lshl_add_u64 v[32:33], s[50:51], 0, v[32:33]
	v_pk_fma_f32 v[30:31], v[34:35], 0.5, v[30:31] op_sel_hi:[1,0,1]
	v_pk_fma_f32 v[26:27], v[26:27], 0.5, v[38:39] op_sel_hi:[1,0,1]
	v_pk_fma_f32 v[24:25], v[24:25], 0.5, v[36:37] op_sel_hi:[1,0,1]
	v_lshl_add_u64 v[32:33], v[32:33], 0, v[122:123]
	global_store_dwordx4 v[32:33], v[28:31], off
	global_store_dwordx4 v[32:33], v[24:27], off offset:16
	s_nop 0
	v_lshlrev_b32_e32 v28, 16, v136
	v_lshlrev_b32_e32 v24, 16, v134
	v_and_b32_e32 v25, 0xffff0000, v134
	v_lshlrev_b32_e32 v26, 16, v135
	v_and_b32_e32 v27, 0xffff0000, v135
	v_and_b32_e32 v29, 0xffff0000, v136
	v_lshlrev_b32_e32 v30, 16, v137
	v_and_b32_e32 v31, 0xffff0000, v137
	v_pk_fma_f32 v[22:23], v[22:23], 0.5, v[26:27] op_sel_hi:[1,0,1]
	v_pk_fma_f32 v[20:21], v[20:21], 0.5, v[24:25] op_sel_hi:[1,0,1]
	v_pk_fma_f32 v[12:13], v[12:13], 0.5, v[28:29] op_sel_hi:[1,0,1]
	v_pk_fma_f32 v[14:15], v[14:15], 0.5, v[30:31] op_sel_hi:[1,0,1]
	global_store_dwordx4 v[32:33], v[20:23], off offset:512
	global_store_dwordx4 v[32:33], v[12:15], off offset:528
	s_nop 0
	v_lshlrev_b32_e32 v20, 16, v140
	v_lshlrev_b32_e32 v12, 16, v138
	v_and_b32_e32 v13, 0xffff0000, v138
	v_pk_fma_f32 v[12:13], v[16:17], 0.5, v[12:13] op_sel_hi:[1,0,1]
	v_lshlrev_b64 v[16:17], 12, v[206:207]
	v_lshlrev_b32_e32 v14, 16, v139
	v_and_b32_e32 v15, 0xffff0000, v139
	v_and_b32_e32 v21, 0xffff0000, v140
	v_lshlrev_b32_e32 v22, 16, v141
	v_and_b32_e32 v23, 0xffff0000, v141
	v_lshl_add_u64 v[16:17], s[50:51], 0, v[16:17]
	v_pk_fma_f32 v[14:15], v[18:19], 0.5, v[14:15] op_sel_hi:[1,0,1]
	v_pk_fma_f32 v[10:11], v[10:11], 0.5, v[22:23] op_sel_hi:[1,0,1]
	v_pk_fma_f32 v[8:9], v[8:9], 0.5, v[20:21] op_sel_hi:[1,0,1]
	v_lshl_add_u64 v[16:17], v[16:17], 0, v[122:123]
	global_store_dwordx4 v[16:17], v[12:15], off
	global_store_dwordx4 v[16:17], v[8:11], off offset:16
	s_nop 0
	v_lshlrev_b32_e32 v12, 16, v132
	v_lshlrev_b32_e32 v8, 16, v130
	v_and_b32_e32 v9, 0xffff0000, v130
	v_lshlrev_b32_e32 v10, 16, v131
	v_and_b32_e32 v11, 0xffff0000, v131
	v_and_b32_e32 v13, 0xffff0000, v132
	v_lshlrev_b32_e32 v14, 16, v133
	v_and_b32_e32 v15, 0xffff0000, v133
	v_pk_fma_f32 v[6:7], v[6:7], 0.5, v[10:11] op_sel_hi:[1,0,1]
	v_pk_fma_f32 v[4:5], v[4:5], 0.5, v[8:9] op_sel_hi:[1,0,1]
	v_pk_fma_f32 v[2:3], v[2:3], 0.5, v[14:15] op_sel_hi:[1,0,1]
	v_pk_fma_f32 v[0:1], v[0:1], 0.5, v[12:13] op_sel_hi:[1,0,1]
	global_store_dwordx4 v[16:17], v[4:7], off offset:512
	global_store_dwordx4 v[16:17], v[0:3], off offset:528
	s_cbranch_vccnz .LBB0_586
	s_andn2_b64 vcc, exec, s[6:7]
	s_cbranch_vccnz .LBB0_585
	s_barrier
	s_branch .LBB0_585

.LBB0_944:
	s_add_u32 s2, s66, 0xfffc0080
	s_addc_u32 s14, s67, -1
	s_add_i32 s15, 0, 0x10000
	s_cmp_eq_u32 s42, 12
	s_cselect_b32 s27, s18, s14
	s_cselect_b32 s26, s19, s2
	s_cselect_b32 s25, s8, s68
	s_cselect_b32 s24, s57, s61
	s_add_i32 s2, 0, 0x14000
	v_add_u32_e32 v142, s15, v187
	v_add_u32_e32 v170, s2, v187
	ds_read_b128 v[130:133], v142
	ds_read_b128 v[134:137], v142 offset:1024
	ds_read_b128 v[138:141], v142 offset:2048
	ds_read_b128 v[142:145], v142 offset:3072
	ds_read_b128 v[146:149], v170
	ds_read_b128 v[150:153], v170 offset:1024
	ds_read_b128 v[166:169], v170 offset:2048
	ds_read_b128 v[170:173], v170 offset:3072
	v_lshl_add_u64 v[182:183], s[66:67], 0, v[164:165]
	s_add_i32 m0, s47, 0xc000
	ds_read_b128 v[174:177], v191
	ds_read_b128 v[178:181], v191 offset:1024
	ds_read_b128 v[200:203], v191 offset:2048
	ds_read_b128 v[204:207], v191 offset:3072
	ds_read_b128 v[208:211], v191 offset:4096
	ds_read_b128 v[212:215], v191 offset:5120
	ds_read_b128 v[216:219], v191 offset:6144
	ds_read_b128 v[220:223], v191 offset:7168
	global_load_lds_dwordx4 v[182:183], off
	v_lshl_add_u64 v[182:183], s[66:67], 0, v[162:163]
	s_add_i32 m0, s47, 0xe000
	s_nop 0
	global_load_lds_dwordx4 v[182:183], off
	s_waitcnt vmcnt(8)
	s_waitcnt lgkmcnt(0)
	s_barrier
	s_setprio 1
	s_waitcnt lgkmcnt(0)
	v_mfma_f32_16x16x32_bf16 v[126:129], v[130:133], v[174:177], v[126:129]
	v_mfma_f32_16x16x32_bf16 v[118:121], v[138:141], v[174:177], v[118:121]
	v_mfma_f32_16x16x32_bf16 v[110:113], v[130:133], v[200:203], v[110:113]
	v_mfma_f32_16x16x32_bf16 v[102:105], v[138:141], v[200:203], v[102:105]
	v_mfma_f32_16x16x32_bf16 v[92:95], v[130:133], v[208:211], v[92:95]
	v_mfma_f32_16x16x32_bf16 v[84:87], v[138:141], v[208:211], v[84:87]
	v_mfma_f32_16x16x32_bf16 v[76:79], v[130:133], v[216:219], v[76:79]
	v_mfma_f32_16x16x32_bf16 v[68:71], v[138:141], v[216:219], v[68:71]
	v_mfma_f32_16x16x32_bf16 v[126:129], v[134:137], v[178:181], v[126:129]
	v_mfma_f32_16x16x32_bf16 v[118:121], v[142:145], v[178:181], v[118:121]
	v_mfma_f32_16x16x32_bf16 v[110:113], v[134:137], v[204:207], v[110:113]
	v_mfma_f32_16x16x32_bf16 v[102:105], v[142:145], v[204:207], v[102:105]
	v_mfma_f32_16x16x32_bf16 v[92:95], v[134:137], v[212:215], v[92:95]
	v_mfma_f32_16x16x32_bf16 v[84:87], v[142:145], v[212:215], v[84:87]
	v_mfma_f32_16x16x32_bf16 v[76:79], v[134:137], v[220:223], v[76:79]
	v_mfma_f32_16x16x32_bf16 v[68:71], v[142:145], v[220:223], v[68:71]
	s_setprio 0
	s_setprio 1
	v_mfma_f32_16x16x32_bf16 v[122:125], v[146:149], v[174:177], v[122:125]
	v_mfma_f32_16x16x32_bf16 v[114:117], v[166:169], v[174:177], v[114:117]
	v_mfma_f32_16x16x32_bf16 v[106:109], v[146:149], v[200:203], v[106:109]
	v_mfma_f32_16x16x32_bf16 v[98:101], v[166:169], v[200:203], v[98:101]
	v_mfma_f32_16x16x32_bf16 v[88:91], v[146:149], v[208:211], v[88:91]
	v_mfma_f32_16x16x32_bf16 v[80:83], v[166:169], v[208:211], v[80:83]
	v_mfma_f32_16x16x32_bf16 v[72:75], v[146:149], v[216:219], v[72:75]
	v_mfma_f32_16x16x32_bf16 v[64:67], v[166:169], v[216:219], v[64:67]
	v_mfma_f32_16x16x32_bf16 v[122:125], v[150:153], v[178:181], v[122:125]
	v_mfma_f32_16x16x32_bf16 v[114:117], v[170:173], v[178:181], v[114:117]
	v_mfma_f32_16x16x32_bf16 v[106:109], v[150:153], v[204:207], v[106:109]
	v_mfma_f32_16x16x32_bf16 v[98:101], v[170:173], v[204:207], v[98:101]
	v_mfma_f32_16x16x32_bf16 v[88:91], v[150:153], v[212:215], v[88:91]
	v_mfma_f32_16x16x32_bf16 v[80:83], v[170:173], v[212:215], v[80:83]
	v_mfma_f32_16x16x32_bf16 v[72:75], v[150:153], v[220:223], v[72:75]
	v_mfma_f32_16x16x32_bf16 v[64:67], v[170:173], v[220:223], v[64:67]
	s_setprio 0
	s_barrier
	s_add_i32 s14, s15, s39
	v_lshl_add_u64 v[182:183], s[24:25], 0, v[96:97]
	s_mov_b32 m0, s14
	ds_read_b128 v[174:177], v191 offset:16384
	ds_read_b128 v[178:181], v191 offset:17408
	ds_read_b128 v[200:203], v191 offset:18432
	ds_read_b128 v[204:207], v191 offset:19456
	ds_read_b128 v[208:211], v191 offset:20480
	ds_read_b128 v[212:215], v191 offset:21504
	ds_read_b128 v[216:219], v191 offset:22528
	ds_read_b128 v[220:223], v191 offset:23552
	global_load_lds_dwordx4 v[182:183], off
	s_add_i32 m0, s14, 0x2000
	s_add_u32 s14, s24, 0x40000
	v_lshl_add_u64 v[188:189], s[24:25], 0, v[154:155]
	s_addc_u32 s15, s25, 0
	s_add_i32 s2, s2, s39
	global_load_lds_dwordx4 v[188:189], off
	v_lshl_add_u64 v[192:193], s[14:15], 0, v[96:97]
	s_mov_b32 m0, s2
	v_lshl_add_u64 v[224:225], s[26:27], 0, v[156:157]
	global_load_lds_dwordx4 v[192:193], off
	v_lshl_add_u64 v[192:193], s[14:15], 0, v[154:155]
	s_add_i32 m0, s2, 0x2000
	s_nop 0
	global_load_lds_dwordx4 v[192:193], off
	v_lshl_add_u64 v[192:193], s[26:27], 0, v[158:159]
	s_mov_b32 m0, s47
	s_nop 0
	global_load_lds_dwordx4 v[192:193], off
	s_mov_b32 m0, s70
	s_nop 0
	global_load_lds_dwordx4 v[224:225], off
	s_waitcnt vmcnt(8)
	s_waitcnt lgkmcnt(0)
	s_barrier
	s_setprio 1
	s_waitcnt lgkmcnt(0)
	v_mfma_f32_16x16x32_bf16 v[60:63], v[130:133], v[174:177], v[60:63]
	v_mfma_f32_16x16x32_bf16 v[52:55], v[138:141], v[174:177], v[52:55]
	v_mfma_f32_16x16x32_bf16 v[44:47], v[130:133], v[200:203], v[44:47]
	v_mfma_f32_16x16x32_bf16 v[36:39], v[138:141], v[200:203], v[36:39]
	v_mfma_f32_16x16x32_bf16 v[28:31], v[130:133], v[208:211], v[28:31]
	v_mfma_f32_16x16x32_bf16 v[20:23], v[138:141], v[208:211], v[20:23]
	v_mfma_f32_16x16x32_bf16 v[12:15], v[130:133], v[216:219], v[12:15]
	v_mfma_f32_16x16x32_bf16 v[4:7], v[138:141], v[216:219], v[4:7]
	v_mfma_f32_16x16x32_bf16 v[60:63], v[134:137], v[178:181], v[60:63]
	v_mfma_f32_16x16x32_bf16 v[52:55], v[142:145], v[178:181], v[52:55]
	v_mfma_f32_16x16x32_bf16 v[44:47], v[134:137], v[204:207], v[44:47]
	v_mfma_f32_16x16x32_bf16 v[36:39], v[142:145], v[204:207], v[36:39]
	v_mfma_f32_16x16x32_bf16 v[28:31], v[134:137], v[212:215], v[28:31]
	v_mfma_f32_16x16x32_bf16 v[20:23], v[142:145], v[212:215], v[20:23]
	v_mfma_f32_16x16x32_bf16 v[12:15], v[134:137], v[220:223], v[12:15]
	v_mfma_f32_16x16x32_bf16 v[4:7], v[142:145], v[220:223], v[4:7]
	s_setprio 0
	s_setprio 1
	v_mfma_f32_16x16x32_bf16 v[56:59], v[146:149], v[174:177], v[56:59]
	v_mfma_f32_16x16x32_bf16 v[48:51], v[166:169], v[174:177], v[48:51]
	v_mfma_f32_16x16x32_bf16 v[40:43], v[146:149], v[200:203], v[40:43]
	v_mfma_f32_16x16x32_bf16 v[32:35], v[166:169], v[200:203], v[32:35]
	v_mfma_f32_16x16x32_bf16 v[24:27], v[146:149], v[208:211], v[24:27]
	v_mfma_f32_16x16x32_bf16 v[16:19], v[166:169], v[208:211], v[16:19]
	v_mfma_f32_16x16x32_bf16 v[8:11], v[146:149], v[216:219], v[8:11]
	v_mfma_f32_16x16x32_bf16 v[0:3], v[166:169], v[216:219], v[0:3]
	v_mfma_f32_16x16x32_bf16 v[56:59], v[150:153], v[178:181], v[56:59]
	v_mfma_f32_16x16x32_bf16 v[48:51], v[170:173], v[178:181], v[48:51]
	v_mfma_f32_16x16x32_bf16 v[40:43], v[150:153], v[204:207], v[40:43]
	v_mfma_f32_16x16x32_bf16 v[32:35], v[170:173], v[204:207], v[32:35]
	v_mfma_f32_16x16x32_bf16 v[24:27], v[150:153], v[212:215], v[24:27]
	v_mfma_f32_16x16x32_bf16 v[16:19], v[170:173], v[212:215], v[16:19]
	v_mfma_f32_16x16x32_bf16 v[8:11], v[150:153], v[220:223], v[8:11]
	v_mfma_f32_16x16x32_bf16 v[0:3], v[170:173], v[220:223], v[0:3]
	s_setprio 0
	s_barrier
	s_add_i32 s2, 0, 0x18000
	s_add_i32 s20, 0, 0x1c000
	v_add_u32_e32 v142, s2, v187
	v_add_u32_e32 v170, s20, v187
	ds_read_b128 v[130:133], v142
	ds_read_b128 v[134:137], v142 offset:1024
	ds_read_b128 v[138:141], v142 offset:2048
	ds_read_b128 v[142:145], v142 offset:3072
	ds_read_b128 v[146:149], v170
	ds_read_b128 v[150:153], v170 offset:1024
	ds_read_b128 v[166:169], v170 offset:2048
	ds_read_b128 v[170:173], v170 offset:3072
	s_add_u32 s14, s26, 0x40000
	s_addc_u32 s15, s27, 0
	s_mov_b32 m0, s71
	v_lshl_add_u64 v[226:227], s[14:15], 0, v[158:159]
	ds_read_b128 v[174:177], v191 offset:32768
	ds_read_b128 v[178:181], v191 offset:33792
	ds_read_b128 v[200:203], v191 offset:34816
	ds_read_b128 v[204:207], v191 offset:35840
	ds_read_b128 v[208:211], v191 offset:36864
	ds_read_b128 v[212:215], v191 offset:37888
	ds_read_b128 v[216:219], v191 offset:38912
	ds_read_b128 v[220:223], v191 offset:39936
	global_load_lds_dwordx4 v[226:227], off
	v_lshl_add_u64 v[226:227], s[14:15], 0, v[156:157]
	s_mov_b32 m0, s72
	s_nop 0
	global_load_lds_dwordx4 v[226:227], off
	s_waitcnt vmcnt(8)
	s_waitcnt lgkmcnt(0)
	s_barrier
	s_setprio 1
	s_waitcnt lgkmcnt(0)
	v_mfma_f32_16x16x32_bf16 v[126:129], v[130:133], v[174:177], v[126:129]
	v_mfma_f32_16x16x32_bf16 v[118:121], v[138:141], v[174:177], v[118:121]
	v_mfma_f32_16x16x32_bf16 v[110:113], v[130:133], v[200:203], v[110:113]
	v_mfma_f32_16x16x32_bf16 v[102:105], v[138:141], v[200:203], v[102:105]
	v_mfma_f32_16x16x32_bf16 v[92:95], v[130:133], v[208:211], v[92:95]
	v_mfma_f32_16x16x32_bf16 v[84:87], v[138:141], v[208:211], v[84:87]
	v_mfma_f32_16x16x32_bf16 v[76:79], v[130:133], v[216:219], v[76:79]
	v_mfma_f32_16x16x32_bf16 v[68:71], v[138:141], v[216:219], v[68:71]
	v_mfma_f32_16x16x32_bf16 v[126:129], v[134:137], v[178:181], v[126:129]
	v_mfma_f32_16x16x32_bf16 v[118:121], v[142:145], v[178:181], v[118:121]
	v_mfma_f32_16x16x32_bf16 v[110:113], v[134:137], v[204:207], v[110:113]
	v_mfma_f32_16x16x32_bf16 v[102:105], v[142:145], v[204:207], v[102:105]
	v_mfma_f32_16x16x32_bf16 v[92:95], v[134:137], v[212:215], v[92:95]
	v_mfma_f32_16x16x32_bf16 v[84:87], v[142:145], v[212:215], v[84:87]
	v_mfma_f32_16x16x32_bf16 v[76:79], v[134:137], v[220:223], v[76:79]
	v_mfma_f32_16x16x32_bf16 v[68:71], v[142:145], v[220:223], v[68:71]
	s_setprio 0
	s_setprio 1
	v_mfma_f32_16x16x32_bf16 v[122:125], v[146:149], v[174:177], v[122:125]
	v_mfma_f32_16x16x32_bf16 v[114:117], v[166:169], v[174:177], v[114:117]
	v_mfma_f32_16x16x32_bf16 v[106:109], v[146:149], v[200:203], v[106:109]
	v_mfma_f32_16x16x32_bf16 v[98:101], v[166:169], v[200:203], v[98:101]
	v_mfma_f32_16x16x32_bf16 v[88:91], v[146:149], v[208:211], v[88:91]
	v_mfma_f32_16x16x32_bf16 v[80:83], v[166:169], v[208:211], v[80:83]
	v_mfma_f32_16x16x32_bf16 v[72:75], v[146:149], v[216:219], v[72:75]
	v_mfma_f32_16x16x32_bf16 v[64:67], v[166:169], v[216:219], v[64:67]
	v_mfma_f32_16x16x32_bf16 v[122:125], v[150:153], v[178:181], v[122:125]
	v_mfma_f32_16x16x32_bf16 v[114:117], v[170:173], v[178:181], v[114:117]
	v_mfma_f32_16x16x32_bf16 v[106:109], v[150:153], v[204:207], v[106:109]
	v_mfma_f32_16x16x32_bf16 v[98:101], v[170:173], v[204:207], v[98:101]
	v_mfma_f32_16x16x32_bf16 v[88:91], v[150:153], v[212:215], v[88:91]
	v_mfma_f32_16x16x32_bf16 v[80:83], v[170:173], v[212:215], v[80:83]
	v_mfma_f32_16x16x32_bf16 v[72:75], v[150:153], v[220:223], v[72:75]
	v_mfma_f32_16x16x32_bf16 v[64:67], v[170:173], v[220:223], v[64:67]
	s_setprio 0
	s_barrier
	s_add_i32 s2, s2, s39
	v_lshl_add_u64 v[182:183], v[182:183], 0, s[22:23]
	s_mov_b32 m0, s2
	ds_read_b128 v[174:177], v191 offset:49152
	ds_read_b128 v[178:181], v191 offset:50176
	ds_read_b128 v[200:203], v191 offset:51200
	ds_read_b128 v[204:207], v191 offset:52224
	ds_read_b128 v[208:211], v191 offset:53248
	ds_read_b128 v[212:215], v191 offset:54272
	ds_read_b128 v[216:219], v191 offset:55296
	ds_read_b128 v[220:223], v191 offset:56320
	global_load_lds_dwordx4 v[182:183], off
	s_add_i32 m0, s2, 0x2000
	s_add_u32 s14, s24, 0x40080
	v_lshl_add_u64 v[182:183], v[188:189], 0, s[22:23]
	s_addc_u32 s15, s25, 0
	s_add_i32 s2, s20, s39
	global_load_lds_dwordx4 v[182:183], off
	v_lshl_add_u64 v[182:183], s[14:15], 0, v[96:97]
	s_mov_b32 m0, s2
	s_nop 0
	global_load_lds_dwordx4 v[182:183], off
	v_lshl_add_u64 v[182:183], s[14:15], 0, v[154:155]
	s_add_i32 m0, s2, 0x2000
	s_nop 0
	global_load_lds_dwordx4 v[182:183], off
	v_lshl_add_u64 v[182:183], v[192:193], 0, s[22:23]
	s_mov_b32 m0, s73
	s_nop 0
	global_load_lds_dwordx4 v[182:183], off
	v_lshl_add_u64 v[182:183], v[224:225], 0, s[22:23]
	s_mov_b32 m0, s74
	s_nop 0
	global_load_lds_dwordx4 v[182:183], off
	s_waitcnt vmcnt(8)
	s_waitcnt lgkmcnt(0)
	s_barrier
	s_setprio 1
	s_waitcnt lgkmcnt(0)
	v_mfma_f32_16x16x32_bf16 v[60:63], v[130:133], v[174:177], v[60:63]
	v_mfma_f32_16x16x32_bf16 v[52:55], v[138:141], v[174:177], v[52:55]
	v_mfma_f32_16x16x32_bf16 v[44:47], v[130:133], v[200:203], v[44:47]
	v_mfma_f32_16x16x32_bf16 v[36:39], v[138:141], v[200:203], v[36:39]
	v_mfma_f32_16x16x32_bf16 v[28:31], v[130:133], v[208:211], v[28:31]
	v_mfma_f32_16x16x32_bf16 v[20:23], v[138:141], v[208:211], v[20:23]
	v_mfma_f32_16x16x32_bf16 v[12:15], v[130:133], v[216:219], v[12:15]
	v_mfma_f32_16x16x32_bf16 v[4:7], v[138:141], v[216:219], v[4:7]
	v_mfma_f32_16x16x32_bf16 v[60:63], v[134:137], v[178:181], v[60:63]
	v_mfma_f32_16x16x32_bf16 v[52:55], v[142:145], v[178:181], v[52:55]
	v_mfma_f32_16x16x32_bf16 v[44:47], v[134:137], v[204:207], v[44:47]
	v_mfma_f32_16x16x32_bf16 v[36:39], v[142:145], v[204:207], v[36:39]
	v_mfma_f32_16x16x32_bf16 v[28:31], v[134:137], v[212:215], v[28:31]
	v_mfma_f32_16x16x32_bf16 v[20:23], v[142:145], v[212:215], v[20:23]
	v_mfma_f32_16x16x32_bf16 v[12:15], v[134:137], v[220:223], v[12:15]
	v_mfma_f32_16x16x32_bf16 v[4:7], v[142:145], v[220:223], v[4:7]
	s_setprio 0
	s_setprio 1
	v_mfma_f32_16x16x32_bf16 v[56:59], v[146:149], v[174:177], v[56:59]
	v_mfma_f32_16x16x32_bf16 v[48:51], v[166:169], v[174:177], v[48:51]
	v_mfma_f32_16x16x32_bf16 v[40:43], v[146:149], v[200:203], v[40:43]
	v_mfma_f32_16x16x32_bf16 v[32:35], v[166:169], v[200:203], v[32:35]
	v_mfma_f32_16x16x32_bf16 v[24:27], v[146:149], v[208:211], v[24:27]
	v_mfma_f32_16x16x32_bf16 v[16:19], v[166:169], v[208:211], v[16:19]
	v_mfma_f32_16x16x32_bf16 v[8:11], v[146:149], v[216:219], v[8:11]
	v_mfma_f32_16x16x32_bf16 v[0:3], v[166:169], v[216:219], v[0:3]
	v_mfma_f32_16x16x32_bf16 v[56:59], v[150:153], v[178:181], v[56:59]
	v_mfma_f32_16x16x32_bf16 v[48:51], v[170:173], v[178:181], v[48:51]
	v_mfma_f32_16x16x32_bf16 v[40:43], v[150:153], v[204:207], v[40:43]
	v_mfma_f32_16x16x32_bf16 v[32:35], v[170:173], v[204:207], v[32:35]
	v_mfma_f32_16x16x32_bf16 v[24:27], v[150:153], v[212:215], v[24:27]
	v_mfma_f32_16x16x32_bf16 v[16:19], v[170:173], v[212:215], v[16:19]
	v_mfma_f32_16x16x32_bf16 v[8:11], v[150:153], v[220:223], v[8:11]
	v_mfma_f32_16x16x32_bf16 v[0:3], v[170:173], v[220:223], v[0:3]
	s_setprio 0
	s_barrier
	s_add_i32 s42, s42, 2
	s_add_u32 s61, s61, 0x100
	s_addc_u32 s68, s68, 0
	s_add_u32 s66, s66, 0x100
	s_addc_u32 s67, s67, 0
	s_cmp_gt_u32 s42, 13
	s_cbranch_scc0 .LBB0_944
	v_lshl_add_u32 v180, s4, 8, v185
	v_ashrrev_i32_e32 v181, 31, v180
	v_lshlrev_b64 v[130:131], 6, v[180:181]
	v_or_b32_e32 v178, 16, v180
	v_lshl_add_u64 v[130:131], v[160:161], 0, v[130:131]
	v_ashrrev_i32_e32 v179, 31, v178
	global_load_dwordx4 v[200:203], v[130:131], off
	v_lshlrev_b64 v[130:131], 6, v[178:179]
	v_lshl_add_u64 v[130:131], v[160:161], 0, v[130:131]
	global_load_dwordx4 v[204:207], v[130:131], off
	v_or_b32_e32 v176, 32, v180
	v_ashrrev_i32_e32 v177, 31, v176
	v_lshlrev_b64 v[130:131], 6, v[176:177]
	v_or_b32_e32 v174, 48, v180
	v_lshl_add_u64 v[130:131], v[160:161], 0, v[130:131]
	v_ashrrev_i32_e32 v175, 31, v174
	global_load_dwordx4 v[150:153], v[130:131], off
	v_lshlrev_b64 v[130:131], 6, v[174:175]
	v_lshl_add_u64 v[130:131], v[160:161], 0, v[130:131]
	global_load_dwordx4 v[146:149], v[130:131], off
	v_add_u32_e32 v172, 0x80, v180
	v_ashrrev_i32_e32 v173, 31, v172
	v_lshlrev_b64 v[130:131], 6, v[172:173]
	v_add_u32_e32 v170, 0x90, v180
	v_lshl_add_u64 v[130:131], v[160:161], 0, v[130:131]
	v_ashrrev_i32_e32 v171, 31, v170
	global_load_dwordx4 v[142:145], v[130:131], off
	v_lshlrev_b64 v[130:131], 6, v[170:171]
	v_lshl_add_u64 v[130:131], v[160:161], 0, v[130:131]
	global_load_dwordx4 v[138:141], v[130:131], off
	v_add_u32_e32 v168, 0xa0, v180
	v_ashrrev_i32_e32 v169, 31, v168
	v_lshlrev_b64 v[130:131], 6, v[168:169]
	v_add_u32_e32 v166, 0xb0, v180
	v_lshl_add_u64 v[130:131], v[160:161], 0, v[130:131]
	v_ashrrev_i32_e32 v167, 31, v166
	global_load_dwordx4 v[134:137], v[130:131], off
	v_lshlrev_b64 v[130:131], 6, v[166:167]
	v_lshl_add_u64 v[130:131], v[160:161], 0, v[130:131]
	global_load_dwordx4 v[130:133], v[130:131], off
	s_and_b64 vcc, exec, s[58:59]
	s_cbranch_vccz .LBB0_947
	s_barrier
.LBB0_947:
	v_and_b32_e32 v169, 64, v248
	v_xor_b32_e32 v167, 16, v248
	v_add_u32_e32 v171, 64, v169
	v_cmp_lt_i32_e32 vcc, v167, v171
	s_nop 1
	s_mov_b32 s2, 0x358637bd
	v_lshl_or_b32 v182, s5, 7, v190
	v_cndmask_b32_e32 v167, v248, v167, vcc
	v_lshlrev_b32_e32 v169, 2, v167
	v_xor_b32_e32 v167, 32, v248
	v_cmp_lt_i32_e32 vcc, v167, v171
	s_nop 1
	v_ashrrev_i32_e32 v183, 31, v182
	s_waitcnt vmcnt(0)
	v_mov_b32_e32 v188, v201
	v_mov_b32_e32 v189, v202
	v_mov_b32_e32 v201, v203
	v_mov_b32_e32 v192, v205
	v_mov_b32_e32 v193, v206
	v_mov_b32_e32 v205, v207
	v_pk_add_f32 v[188:189], v[188:189], v[200:201]
	v_pk_add_f32 v[192:193], v[192:193], v[204:205]
	v_mov_b32_e32 v201, v188
	v_mov_b32_e32 v200, v192
	v_mov_b32_e32 v188, v193
	v_pk_add_f32 v[188:189], v[200:201], v[188:189]
	ds_bpermute_b32 v193, v169, v189
	ds_bpermute_b32 v192, v169, v188
	v_cndmask_b32_e32 v167, v248, v167, vcc
	v_lshlrev_b32_e32 v167, 2, v167
	s_waitcnt lgkmcnt(0)
	v_pk_add_f32 v[188:189], v[188:189], v[192:193]
	ds_bpermute_b32 v193, v167, v189
	ds_bpermute_b32 v192, v167, v188
	s_waitcnt lgkmcnt(0)
	v_pk_add_f32 v[192:193], v[188:189], v[192:193]
	v_mov_b64_e32 v[188:189], s[2:3]
	v_pk_fma_f32 v[192:193], v[192:193], s[28:29], v[188:189] op_sel_hi:[1,0,0]
	s_nop 0
	v_mul_f32_e32 v171, 0x4b800000, v193
	v_cmp_gt_f32_e64 s[4:5], s29, v193
	v_cmp_gt_f32_e32 vcc, s29, v192
	s_nop 0
	v_cndmask_b32_e64 v171, v193, v171, s[4:5]
	v_rsq_f32_e32 v171, v171
	v_mov_b32_e32 v193, v152
	v_mov_b32_e32 v152, v147
	v_mov_b32_e32 v147, v149
	v_mul_f32_e32 v173, 0x45800000, v171
	v_cndmask_b32_e64 v186, v171, v173, s[4:5]
	v_mul_f32_e32 v171, 0x4b800000, v192
	v_cndmask_b32_e32 v171, v192, v171, vcc
	v_mov_b32_e32 v192, v151
	v_mov_b32_e32 v151, v153
	v_mov_b32_e32 v153, v148
	v_pk_add_f32 v[150:151], v[192:193], v[150:151]
	v_pk_add_f32 v[146:147], v[152:153], v[146:147]
	v_mov_b32_e32 v149, v150
	v_mov_b32_e32 v148, v146
	v_mov_b32_e32 v150, v147
	v_pk_add_f32 v[146:147], v[148:149], v[150:151]
	ds_bpermute_b32 v149, v169, v147
	ds_bpermute_b32 v148, v169, v146
	v_mov_b32_e32 v150, v143
	v_mov_b32_e32 v151, v144
	v_mov_b32_e32 v143, v145
	v_mov_b32_e32 v144, v139
	v_mov_b32_e32 v145, v140
	v_mov_b32_e32 v139, v141
	v_pk_add_f32 v[142:143], v[150:151], v[142:143]
	v_pk_add_f32 v[138:139], v[144:145], v[138:139]
	s_waitcnt lgkmcnt(0)
	v_pk_add_f32 v[146:147], v[146:147], v[148:149]
	v_mov_b32_e32 v140, v138
	v_mov_b32_e32 v141, v142
	v_mov_b32_e32 v142, v139
	ds_bpermute_b32 v149, v167, v147
	ds_bpermute_b32 v148, v167, v146
	v_pk_add_f32 v[138:139], v[140:141], v[142:143]
	ds_bpermute_b32 v141, v169, v139
	ds_bpermute_b32 v140, v169, v138
	v_mov_b32_e32 v142, v135
	v_mov_b32_e32 v143, v136
	v_mov_b32_e32 v135, v137
	v_mov_b32_e32 v136, v131
	v_mov_b32_e32 v137, v132
	v_mov_b32_e32 v131, v133
	s_waitcnt lgkmcnt(2)
	v_pk_add_f32 v[146:147], v[146:147], v[148:149]
	v_pk_add_f32 v[134:135], v[142:143], v[134:135]
	v_pk_add_f32 v[130:131], v[136:137], v[130:131]
	v_pk_fma_f32 v[146:147], v[146:147], s[28:29], v[188:189] op_sel_hi:[1,0,0]
	s_waitcnt lgkmcnt(0)
	v_pk_add_f32 v[138:139], v[138:139], v[140:141]
	v_mov_b32_e32 v132, v130
	v_mov_b32_e32 v133, v134
	v_mov_b32_e32 v134, v131
	v_mul_f32_e32 v148, 0x4b800000, v147
	v_cmp_gt_f32_e64 s[4:5], s29, v147
	ds_bpermute_b32 v141, v167, v139
	ds_bpermute_b32 v140, v167, v138
	v_pk_add_f32 v[130:131], v[132:133], v[134:135]
	v_cndmask_b32_e64 v147, v147, v148, s[4:5]
	ds_bpermute_b32 v133, v169, v131
	ds_bpermute_b32 v132, v169, v130
	v_rsq_f32_e32 v171, v171
	v_rsq_f32_e32 v147, v147
	s_waitcnt lgkmcnt(2)
	v_pk_add_f32 v[138:139], v[138:139], v[140:141]
	v_mov_b32_e32 v134, v122
	v_mul_f32_e32 v173, 0x45800000, v171
	v_mul_f32_e32 v148, 0x45800000, v147
	v_pk_fma_f32 v[138:139], v[138:139], s[28:29], v[188:189] op_sel_hi:[1,0,0]
	s_waitcnt lgkmcnt(0)
	v_pk_add_f32 v[130:131], v[130:131], v[132:133]
	v_cndmask_b32_e32 v184, v171, v173, vcc
	v_cmp_gt_f32_e32 vcc, s29, v146
	v_cndmask_b32_e64 v148, v147, v148, s[4:5]
	v_mul_f32_e32 v147, 0x4b800000, v146
	v_mul_f32_e32 v140, 0x4b800000, v139
	v_cmp_gt_f32_e64 s[4:5], s29, v139
	ds_bpermute_b32 v133, v167, v131
	ds_bpermute_b32 v132, v167, v130
	v_cndmask_b32_e32 v146, v146, v147, vcc
	v_cndmask_b32_e64 v139, v139, v140, s[4:5]
	v_rsq_f32_e32 v146, v146
	v_rsq_f32_e32 v139, v139
	s_waitcnt lgkmcnt(0)
	v_pk_add_f32 v[130:131], v[130:131], v[132:133]
	v_mov_b32_e32 v135, v126
	v_mul_f32_e32 v147, 0x45800000, v146
	v_mul_f32_e32 v140, 0x45800000, v139
	v_pk_fma_f32 v[130:131], v[130:131], s[28:29], v[188:189] op_sel_hi:[1,0,0]
	v_cndmask_b32_e32 v146, v146, v147, vcc
	v_cmp_gt_f32_e32 vcc, s29, v138
	v_cndmask_b32_e64 v140, v139, v140, s[4:5]
	v_mul_f32_e32 v139, 0x4b800000, v138
	v_mul_f32_e32 v132, 0x4b800000, v131
	v_cmp_gt_f32_e64 s[4:5], s29, v131
	v_cndmask_b32_e32 v138, v138, v139, vcc
	v_rsq_f32_e32 v138, v138
	v_cndmask_b32_e64 v131, v131, v132, s[4:5]
	v_rsq_f32_e32 v131, v131
	v_pk_mul_f32 v[134:135], v[134:135], v[186:187] op_sel_hi:[1,0]
	v_mul_f32_e32 v139, 0x45800000, v138
	v_mul_f32_e32 v122, 0xbfb8aa3b, v135
	v_exp_f32_e32 v122, v122
	v_mul_f32_e32 v132, 0x45800000, v131
	v_cndmask_b32_e32 v138, v138, v139, vcc
	v_cmp_gt_f32_e32 vcc, s29, v130
	v_cndmask_b32_e64 v132, v131, v132, s[4:5]
	v_mul_f32_e32 v131, 0x4b800000, v130
	v_cndmask_b32_e32 v130, v130, v131, vcc
	v_add_f32_e32 v122, 1.0, v122
	v_rsq_f32_e32 v130, v130
	v_rcp_f32_e32 v122, v122
	v_mov_b32_e32 v126, v123
	v_mul_f32_e32 v131, 0x45800000, v130
	v_mul_f32_e32 v122, v135, v122
	v_cndmask_b32_e32 v130, v130, v131, vcc
	v_mul_f32_e32 v131, v134, v122
	v_pk_mul_f32 v[122:123], v[126:127], v[186:187] op_sel_hi:[1,0]
	s_andn2_b64 vcc, exec, s[0:1]
	v_mul_f32_e32 v126, 0xbfb8aa3b, v123
	v_exp_f32_e32 v126, v126
	s_nop 0
	v_add_f32_e32 v126, 1.0, v126
	v_rcp_f32_e32 v126, v126
	s_nop 0
	v_mul_f32_e32 v123, v123, v126
	v_mul_f32_e32 v126, v122, v123
	v_mov_b32_e32 v122, v124
	v_mov_b32_e32 v123, v128
	v_pk_mul_f32 v[122:123], v[122:123], v[186:187] op_sel_hi:[1,0]
	v_mov_b32_e32 v128, v125
	v_mul_f32_e32 v124, 0xbfb8aa3b, v123
	v_exp_f32_e32 v124, v124
	s_nop 0
	v_add_f32_e32 v124, 1.0, v124
	v_rcp_f32_e32 v124, v124
	s_nop 0
	v_mul_f32_e32 v123, v123, v124
	v_mul_f32_e32 v124, v122, v123
	v_pk_mul_f32 v[122:123], v[128:129], v[186:187] op_sel_hi:[1,0]
	s_nop 0
	v_mul_f32_e32 v125, 0xbfb8aa3b, v123
	v_exp_f32_e32 v125, v125
	s_nop 0
	v_add_f32_e32 v125, 1.0, v125
	v_rcp_f32_e32 v125, v125
	s_nop 0
	v_mul_f32_e32 v123, v123, v125
	v_mul_f32_e32 v125, v122, v123
	v_mov_b32_e32 v122, v114
	v_mov_b32_e32 v123, v118
	v_pk_mul_f32 v[122:123], v[122:123], v[186:187] op_sel_hi:[1,0]
	v_mov_b32_e32 v118, v115
	v_mul_f32_e32 v114, 0xbfb8aa3b, v123
	v_exp_f32_e32 v114, v114
	s_nop 0
	v_add_f32_e32 v114, 1.0, v114
	v_rcp_f32_e32 v114, v114
	s_nop 0
	v_mul_f32_e32 v114, v123, v114
	v_mul_f32_e32 v122, v122, v114
	v_pk_mul_f32 v[114:115], v[118:119], v[186:187] op_sel_hi:[1,0]
	s_nop 0
	v_mul_f32_e32 v118, 0xbfb8aa3b, v115
	v_exp_f32_e32 v118, v118
	s_nop 0
	v_add_f32_e32 v118, 1.0, v118
	v_rcp_f32_e32 v118, v118
	s_nop 0
	v_mul_f32_e32 v115, v115, v118
	v_mul_f32_e32 v123, v114, v115
	v_mov_b32_e32 v114, v116
	v_mov_b32_e32 v115, v120
	v_pk_mul_f32 v[114:115], v[114:115], v[186:187] op_sel_hi:[1,0]
	v_mov_b32_e32 v120, v117
	v_mul_f32_e32 v116, 0xbfb8aa3b, v115
	v_exp_f32_e32 v116, v116
	v_cvt_pk_bf16_f32 v118, v131, v126
	v_cvt_pk_bf16_f32 v119, v124, v125
	s_nop 0
	v_add_f32_e32 v116, 1.0, v116
	v_rcp_f32_e32 v116, v116
	s_nop 0
	v_mul_f32_e32 v115, v115, v116
	v_mul_f32_e32 v116, v114, v115
	v_pk_mul_f32 v[114:115], v[120:121], v[186:187] op_sel_hi:[1,0]
	v_cvt_pk_bf16_f32 v120, v122, v123
	s_nop 0
	v_mul_f32_e32 v117, 0xbfb8aa3b, v115
	v_exp_f32_e32 v117, v117
	s_nop 0
	v_add_f32_e32 v117, 1.0, v117
	v_rcp_f32_e32 v117, v117
	s_nop 0
	v_mul_f32_e32 v115, v115, v117
	v_mul_f32_e32 v114, v114, v115
	v_cvt_pk_bf16_f32 v121, v116, v114
	v_mov_b64_e32 v[114:115], s[54:55]
	v_mad_i64_i32 v[122:123], s[4:5], v180, s31, v[114:115]
	v_lshlrev_b64 v[116:117], 1, v[182:183]
	v_lshl_add_u64 v[122:123], v[122:123], 0, v[116:117]
	global_store_dwordx4 v[122:123], v[118:121], off
	s_nop 1
	v_mov_b32_e32 v118, v106
	v_mov_b32_e32 v119, v110
	v_pk_mul_f32 v[118:119], v[118:119], v[184:185] op_sel_hi:[1,0]
	v_mov_b32_e32 v110, v107
	v_mul_f32_e32 v106, 0xbfb8aa3b, v119
	v_exp_f32_e32 v106, v106
	s_nop 0
	v_add_f32_e32 v106, 1.0, v106
	v_rcp_f32_e32 v106, v106
	s_nop 0
	v_mul_f32_e32 v106, v119, v106
	v_mul_f32_e32 v118, v118, v106
	v_pk_mul_f32 v[106:107], v[110:111], v[184:185] op_sel_hi:[1,0]
	s_nop 0
	v_mul_f32_e32 v110, 0xbfb8aa3b, v107
	v_exp_f32_e32 v110, v110
	s_nop 0
	v_add_f32_e32 v110, 1.0, v110
	v_rcp_f32_e32 v110, v110
	s_nop 0
	v_mul_f32_e32 v107, v107, v110
	v_mul_f32_e32 v110, v106, v107
	v_mov_b32_e32 v106, v108
	v_mov_b32_e32 v107, v112
	v_pk_mul_f32 v[106:107], v[106:107], v[184:185] op_sel_hi:[1,0]
	v_mov_b32_e32 v112, v109
	v_mul_f32_e32 v108, 0xbfb8aa3b, v107
	v_exp_f32_e32 v108, v108
	s_nop 0
	v_add_f32_e32 v108, 1.0, v108
	v_rcp_f32_e32 v108, v108
	s_nop 0
	v_mul_f32_e32 v107, v107, v108
	v_mul_f32_e32 v108, v106, v107
	v_pk_mul_f32 v[106:107], v[112:113], v[184:185] op_sel_hi:[1,0]
	s_nop 0
	v_mul_f32_e32 v109, 0xbfb8aa3b, v107
	v_exp_f32_e32 v109, v109
	s_nop 0
	v_add_f32_e32 v109, 1.0, v109
	v_rcp_f32_e32 v109, v109
	s_nop 0
	v_mul_f32_e32 v107, v107, v109
	v_mul_f32_e32 v109, v106, v107
	v_mov_b32_e32 v106, v98
	v_mov_b32_e32 v107, v102
	v_pk_mul_f32 v[106:107], v[106:107], v[184:185] op_sel_hi:[1,0]
	v_mov_b32_e32 v102, v99
	v_mul_f32_e32 v98, 0xbfb8aa3b, v107
	v_exp_f32_e32 v98, v98
	s_nop 0
	v_add_f32_e32 v98, 1.0, v98
	v_rcp_f32_e32 v98, v98
	s_nop 0
	v_mul_f32_e32 v98, v107, v98
	v_mul_f32_e32 v106, v106, v98
	v_pk_mul_f32 v[98:99], v[102:103], v[184:185] op_sel_hi:[1,0]
	s_nop 0
	v_mul_f32_e32 v102, 0xbfb8aa3b, v99
	v_exp_f32_e32 v102, v102
	s_nop 0
	v_add_f32_e32 v102, 1.0, v102
	v_rcp_f32_e32 v102, v102
	s_nop 0
	v_mul_f32_e32 v99, v99, v102
	v_mul_f32_e32 v102, v98, v99
	v_mov_b32_e32 v98, v100
	v_mov_b32_e32 v99, v104
	v_pk_mul_f32 v[98:99], v[98:99], v[184:185] op_sel_hi:[1,0]
	v_mov_b32_e32 v104, v101
	v_mul_f32_e32 v100, 0xbfb8aa3b, v99
	v_exp_f32_e32 v100, v100
	s_nop 0
	v_add_f32_e32 v100, 1.0, v100
	v_rcp_f32_e32 v100, v100
	s_nop 0
	v_mul_f32_e32 v99, v99, v100
	v_mul_f32_e32 v103, v98, v99
	v_pk_mul_f32 v[98:99], v[104:105], v[184:185] op_sel_hi:[1,0]
	s_nop 0
	v_mul_f32_e32 v100, 0xbfb8aa3b, v99
	v_exp_f32_e32 v100, v100
	s_nop 0
	v_add_f32_e32 v100, 1.0, v100
	v_rcp_f32_e32 v100, v100
	s_nop 0
	v_mul_f32_e32 v99, v99, v100
	v_mul_f32_e32 v101, v98, v99
	v_cvt_pk_bf16_f32 v98, v118, v110
	v_cvt_pk_bf16_f32 v99, v108, v109
	v_cvt_pk_bf16_f32 v100, v106, v102
	v_cvt_pk_bf16_f32 v101, v103, v101
	v_mad_i64_i32 v[102:103], s[4:5], v178, s31, v[114:115]
	v_lshl_add_u64 v[102:103], v[102:103], 0, v[116:117]
	global_store_dwordx4 v[102:103], v[98:101], off
	s_nop 1
	v_mov_b32_e32 v98, v88
	v_mov_b32_e32 v99, v92
	v_pk_mul_f32 v[98:99], v[98:99], v[148:149] op_sel_hi:[1,0]
	v_mov_b32_e32 v92, v89
	v_mul_f32_e32 v88, 0xbfb8aa3b, v99
	v_exp_f32_e32 v88, v88
	s_nop 0
	v_add_f32_e32 v88, 1.0, v88
	v_rcp_f32_e32 v88, v88
	s_nop 0
	v_mul_f32_e32 v88, v99, v88
	v_mul_f32_e32 v98, v98, v88
	v_pk_mul_f32 v[88:89], v[92:93], v[148:149] op_sel_hi:[1,0]
	s_nop 0
	v_mul_f32_e32 v92, 0xbfb8aa3b, v89
	v_exp_f32_e32 v92, v92
	s_nop 0
	v_add_f32_e32 v92, 1.0, v92
	v_rcp_f32_e32 v92, v92
	s_nop 0
	v_mul_f32_e32 v89, v89, v92
	v_mul_f32_e32 v92, v88, v89
	v_mov_b32_e32 v88, v90
	v_mov_b32_e32 v89, v94
	v_pk_mul_f32 v[88:89], v[88:89], v[148:149] op_sel_hi:[1,0]
	v_mov_b32_e32 v94, v91
	v_mul_f32_e32 v90, 0xbfb8aa3b, v89
	v_exp_f32_e32 v90, v90
	s_nop 0
	v_add_f32_e32 v90, 1.0, v90
	v_rcp_f32_e32 v90, v90
	s_nop 0
	v_mul_f32_e32 v89, v89, v90
	v_mul_f32_e32 v90, v88, v89
	v_pk_mul_f32 v[88:89], v[94:95], v[148:149] op_sel_hi:[1,0]
	s_nop 0
	v_mul_f32_e32 v91, 0xbfb8aa3b, v89
	v_exp_f32_e32 v91, v91
	s_nop 0
	v_add_f32_e32 v91, 1.0, v91
	v_rcp_f32_e32 v91, v91
	s_nop 0
	v_mul_f32_e32 v89, v89, v91
	v_mul_f32_e32 v91, v88, v89
	v_mov_b32_e32 v88, v80
	v_mov_b32_e32 v89, v84
	v_pk_mul_f32 v[88:89], v[88:89], v[148:149] op_sel_hi:[1,0]
	v_mov_b32_e32 v84, v81
	v_mul_f32_e32 v80, 0xbfb8aa3b, v89
	v_exp_f32_e32 v80, v80
	s_nop 0
	v_add_f32_e32 v80, 1.0, v80
	v_rcp_f32_e32 v80, v80
	s_nop 0
	v_mul_f32_e32 v80, v89, v80
	v_mul_f32_e32 v88, v88, v80
	v_pk_mul_f32 v[80:81], v[84:85], v[148:149] op_sel_hi:[1,0]
	s_nop 0
	v_mul_f32_e32 v84, 0xbfb8aa3b, v81
	v_exp_f32_e32 v84, v84
	s_nop 0
	v_add_f32_e32 v84, 1.0, v84
	v_rcp_f32_e32 v84, v84
	s_nop 0
	v_mul_f32_e32 v81, v81, v84
	v_mul_f32_e32 v84, v80, v81
	v_mov_b32_e32 v80, v82
	v_mov_b32_e32 v81, v86
	v_pk_mul_f32 v[80:81], v[80:81], v[148:149] op_sel_hi:[1,0]
	v_mov_b32_e32 v86, v83
	v_mul_f32_e32 v82, 0xbfb8aa3b, v81
	v_exp_f32_e32 v82, v82
	s_nop 0
	v_add_f32_e32 v82, 1.0, v82
	v_rcp_f32_e32 v82, v82
	s_nop 0
	v_mul_f32_e32 v81, v81, v82
	v_mul_f32_e32 v85, v80, v81
	v_pk_mul_f32 v[80:81], v[86:87], v[148:149] op_sel_hi:[1,0]
	s_nop 0
	v_mul_f32_e32 v82, 0xbfb8aa3b, v81
	v_exp_f32_e32 v82, v82
	s_nop 0
	v_add_f32_e32 v82, 1.0, v82
	v_rcp_f32_e32 v82, v82
	s_nop 0
	v_mul_f32_e32 v81, v81, v82
	v_mul_f32_e32 v83, v80, v81
	v_cvt_pk_bf16_f32 v80, v98, v92
	v_cvt_pk_bf16_f32 v81, v90, v91
	v_cvt_pk_bf16_f32 v82, v88, v84
	v_cvt_pk_bf16_f32 v83, v85, v83
	v_mad_i64_i32 v[84:85], s[4:5], v176, s31, v[114:115]
	v_lshl_add_u64 v[84:85], v[84:85], 0, v[116:117]
	global_store_dwordx4 v[84:85], v[80:83], off
	s_nop 1
	v_mov_b32_e32 v80, v72
	v_mov_b32_e32 v81, v76
	v_pk_mul_f32 v[80:81], v[80:81], v[146:147] op_sel_hi:[1,0]
	v_mov_b32_e32 v76, v73
	v_mul_f32_e32 v72, 0xbfb8aa3b, v81
	v_exp_f32_e32 v72, v72
	s_nop 0
	v_add_f32_e32 v72, 1.0, v72
	v_rcp_f32_e32 v72, v72
	s_nop 0
	v_mul_f32_e32 v72, v81, v72
	v_mul_f32_e32 v80, v80, v72
	v_pk_mul_f32 v[72:73], v[76:77], v[146:147] op_sel_hi:[1,0]
	s_nop 0
	v_mul_f32_e32 v76, 0xbfb8aa3b, v73
	v_exp_f32_e32 v76, v76
	s_nop 0
	v_add_f32_e32 v76, 1.0, v76
	v_rcp_f32_e32 v76, v76
	s_nop 0
	v_mul_f32_e32 v73, v73, v76
	v_mul_f32_e32 v76, v72, v73
	v_mov_b32_e32 v72, v74
	v_mov_b32_e32 v73, v78
	v_pk_mul_f32 v[72:73], v[72:73], v[146:147] op_sel_hi:[1,0]
	v_mov_b32_e32 v78, v75
	v_mul_f32_e32 v74, 0xbfb8aa3b, v73
	v_exp_f32_e32 v74, v74
	s_nop 0
	v_add_f32_e32 v74, 1.0, v74
	v_rcp_f32_e32 v74, v74
	s_nop 0
	v_mul_f32_e32 v73, v73, v74
	v_mul_f32_e32 v74, v72, v73
	v_pk_mul_f32 v[72:73], v[78:79], v[146:147] op_sel_hi:[1,0]
	s_nop 0
	v_mul_f32_e32 v75, 0xbfb8aa3b, v73
	v_exp_f32_e32 v75, v75
	s_nop 0
	v_add_f32_e32 v75, 1.0, v75
	v_rcp_f32_e32 v75, v75
	s_nop 0
	v_mul_f32_e32 v73, v73, v75
	v_mul_f32_e32 v75, v72, v73
	v_mov_b32_e32 v72, v64
	v_mov_b32_e32 v73, v68
	v_pk_mul_f32 v[72:73], v[72:73], v[146:147] op_sel_hi:[1,0]
	v_mov_b32_e32 v68, v65
	v_mul_f32_e32 v64, 0xbfb8aa3b, v73
	v_exp_f32_e32 v64, v64
	s_nop 0
	v_add_f32_e32 v64, 1.0, v64
	v_rcp_f32_e32 v64, v64
	s_nop 0
	v_mul_f32_e32 v64, v73, v64
	v_mul_f32_e32 v72, v72, v64
	v_pk_mul_f32 v[64:65], v[68:69], v[146:147] op_sel_hi:[1,0]
	s_nop 0
	v_mul_f32_e32 v68, 0xbfb8aa3b, v65
	v_exp_f32_e32 v68, v68
	s_nop 0
	v_add_f32_e32 v68, 1.0, v68
	v_rcp_f32_e32 v68, v68
	s_nop 0
	v_mul_f32_e32 v65, v65, v68
	v_mul_f32_e32 v68, v64, v65
	v_mov_b32_e32 v64, v66
	v_mov_b32_e32 v65, v70
	v_pk_mul_f32 v[64:65], v[64:65], v[146:147] op_sel_hi:[1,0]
	v_mov_b32_e32 v70, v67
	v_mul_f32_e32 v66, 0xbfb8aa3b, v65
	v_exp_f32_e32 v66, v66
	s_nop 0
	v_add_f32_e32 v66, 1.0, v66
	v_rcp_f32_e32 v66, v66
	s_nop 0
	v_mul_f32_e32 v65, v65, v66
	v_mul_f32_e32 v69, v64, v65
	v_pk_mul_f32 v[64:65], v[70:71], v[146:147] op_sel_hi:[1,0]
	s_nop 0
	v_mul_f32_e32 v66, 0xbfb8aa3b, v65
	v_exp_f32_e32 v66, v66
	s_nop 0
	v_add_f32_e32 v66, 1.0, v66
	v_rcp_f32_e32 v66, v66
	s_nop 0
	v_mul_f32_e32 v65, v65, v66
	v_mul_f32_e32 v67, v64, v65
	v_cvt_pk_bf16_f32 v64, v80, v76
	v_cvt_pk_bf16_f32 v65, v74, v75
	v_cvt_pk_bf16_f32 v66, v72, v68
	v_cvt_pk_bf16_f32 v67, v69, v67
	v_mad_i64_i32 v[68:69], s[4:5], v174, s31, v[114:115]
	v_lshl_add_u64 v[68:69], v[68:69], 0, v[116:117]
	global_store_dwordx4 v[68:69], v[64:67], off
	s_nop 1
	v_mov_b32_e32 v64, v56
	v_mov_b32_e32 v65, v60
	v_pk_mul_f32 v[64:65], v[64:65], v[140:141] op_sel_hi:[1,0]
	v_mov_b32_e32 v60, v57
	v_mul_f32_e32 v56, 0xbfb8aa3b, v65
	v_exp_f32_e32 v56, v56
	s_nop 0
	v_add_f32_e32 v56, 1.0, v56
	v_rcp_f32_e32 v56, v56
	s_nop 0
	v_mul_f32_e32 v56, v65, v56
	v_mul_f32_e32 v64, v64, v56
	v_pk_mul_f32 v[56:57], v[60:61], v[140:141] op_sel_hi:[1,0]
	s_nop 0
	v_mul_f32_e32 v60, 0xbfb8aa3b, v57
	v_exp_f32_e32 v60, v60
	s_nop 0
	v_add_f32_e32 v60, 1.0, v60
	v_rcp_f32_e32 v60, v60
	s_nop 0
	v_mul_f32_e32 v57, v57, v60
	v_mul_f32_e32 v60, v56, v57
	v_mov_b32_e32 v56, v58
	v_mov_b32_e32 v57, v62
	v_pk_mul_f32 v[56:57], v[56:57], v[140:141] op_sel_hi:[1,0]
	v_mov_b32_e32 v62, v59
	v_mul_f32_e32 v58, 0xbfb8aa3b, v57
	v_exp_f32_e32 v58, v58
	s_nop 0
	v_add_f32_e32 v58, 1.0, v58
	v_rcp_f32_e32 v58, v58
	s_nop 0
	v_mul_f32_e32 v57, v57, v58
	v_mul_f32_e32 v58, v56, v57
	v_pk_mul_f32 v[56:57], v[62:63], v[140:141] op_sel_hi:[1,0]
	s_nop 0
	v_mul_f32_e32 v59, 0xbfb8aa3b, v57
	v_exp_f32_e32 v59, v59
	s_nop 0
	v_add_f32_e32 v59, 1.0, v59
	v_rcp_f32_e32 v59, v59
	s_nop 0
	v_mul_f32_e32 v57, v57, v59
	v_mul_f32_e32 v59, v56, v57
	v_mov_b32_e32 v56, v48
	v_mov_b32_e32 v57, v52
	v_pk_mul_f32 v[56:57], v[56:57], v[140:141] op_sel_hi:[1,0]
	v_mov_b32_e32 v52, v49
	v_mul_f32_e32 v48, 0xbfb8aa3b, v57
	v_exp_f32_e32 v48, v48
	s_nop 0
	v_add_f32_e32 v48, 1.0, v48
	v_rcp_f32_e32 v48, v48
	s_nop 0
	v_mul_f32_e32 v48, v57, v48
	v_mul_f32_e32 v56, v56, v48
	v_pk_mul_f32 v[48:49], v[52:53], v[140:141] op_sel_hi:[1,0]
	s_nop 0
	v_mul_f32_e32 v52, 0xbfb8aa3b, v49
	v_exp_f32_e32 v52, v52
	s_nop 0
	v_add_f32_e32 v52, 1.0, v52
	v_rcp_f32_e32 v52, v52
	s_nop 0
	v_mul_f32_e32 v49, v49, v52
	v_mul_f32_e32 v52, v48, v49
	v_mov_b32_e32 v48, v50
	v_mov_b32_e32 v49, v54
	v_pk_mul_f32 v[48:49], v[48:49], v[140:141] op_sel_hi:[1,0]
	v_mov_b32_e32 v54, v51
	v_mul_f32_e32 v50, 0xbfb8aa3b, v49
	v_exp_f32_e32 v50, v50
	s_nop 0
	v_add_f32_e32 v50, 1.0, v50
	v_rcp_f32_e32 v50, v50
	s_nop 0
	v_mul_f32_e32 v49, v49, v50
	v_mul_f32_e32 v53, v48, v49
	v_pk_mul_f32 v[48:49], v[54:55], v[140:141] op_sel_hi:[1,0]
	s_nop 0
	v_mul_f32_e32 v50, 0xbfb8aa3b, v49
	v_exp_f32_e32 v50, v50
	s_nop 0
	v_add_f32_e32 v50, 1.0, v50
	v_rcp_f32_e32 v50, v50
	s_nop 0
	v_mul_f32_e32 v49, v49, v50
	v_mul_f32_e32 v51, v48, v49
	v_cvt_pk_bf16_f32 v48, v64, v60
	v_cvt_pk_bf16_f32 v49, v58, v59
	v_cvt_pk_bf16_f32 v50, v56, v52
	v_cvt_pk_bf16_f32 v51, v53, v51
	v_mad_i64_i32 v[52:53], s[4:5], v172, s31, v[114:115]
	v_lshl_add_u64 v[52:53], v[52:53], 0, v[116:117]
	global_store_dwordx4 v[52:53], v[48:51], off
	s_nop 1
	v_mov_b32_e32 v48, v40
	v_mov_b32_e32 v49, v44
	v_pk_mul_f32 v[48:49], v[48:49], v[138:139] op_sel_hi:[1,0]
	v_mov_b32_e32 v44, v41
	v_mul_f32_e32 v40, 0xbfb8aa3b, v49
	v_exp_f32_e32 v40, v40
	s_nop 0
	v_add_f32_e32 v40, 1.0, v40
	v_rcp_f32_e32 v40, v40
	s_nop 0
	v_mul_f32_e32 v40, v49, v40
	v_mul_f32_e32 v48, v48, v40
	v_pk_mul_f32 v[40:41], v[44:45], v[138:139] op_sel_hi:[1,0]
	s_nop 0
	v_mul_f32_e32 v44, 0xbfb8aa3b, v41
	v_exp_f32_e32 v44, v44
	s_nop 0
	v_add_f32_e32 v44, 1.0, v44
	v_rcp_f32_e32 v44, v44
	s_nop 0
	v_mul_f32_e32 v41, v41, v44
	v_mul_f32_e32 v44, v40, v41
	v_mov_b32_e32 v40, v42
	v_mov_b32_e32 v41, v46
	v_pk_mul_f32 v[40:41], v[40:41], v[138:139] op_sel_hi:[1,0]
	v_mov_b32_e32 v46, v43
	v_mul_f32_e32 v42, 0xbfb8aa3b, v41
	v_exp_f32_e32 v42, v42
	s_nop 0
	v_add_f32_e32 v42, 1.0, v42
	v_rcp_f32_e32 v42, v42
	s_nop 0
	v_mul_f32_e32 v41, v41, v42
	v_mul_f32_e32 v42, v40, v41
	v_pk_mul_f32 v[40:41], v[46:47], v[138:139] op_sel_hi:[1,0]
	s_nop 0
	v_mul_f32_e32 v43, 0xbfb8aa3b, v41
	v_exp_f32_e32 v43, v43
	s_nop 0
	v_add_f32_e32 v43, 1.0, v43
	v_rcp_f32_e32 v43, v43
	s_nop 0
	v_mul_f32_e32 v41, v41, v43
	v_mul_f32_e32 v43, v40, v41
	v_mov_b32_e32 v40, v32
	v_mov_b32_e32 v41, v36
	v_pk_mul_f32 v[40:41], v[40:41], v[138:139] op_sel_hi:[1,0]
	v_mov_b32_e32 v36, v33
	v_mul_f32_e32 v32, 0xbfb8aa3b, v41
	v_exp_f32_e32 v32, v32
	s_nop 0
	v_add_f32_e32 v32, 1.0, v32
	v_rcp_f32_e32 v32, v32
	s_nop 0
	v_mul_f32_e32 v32, v41, v32
	v_mul_f32_e32 v40, v40, v32
	v_pk_mul_f32 v[32:33], v[36:37], v[138:139] op_sel_hi:[1,0]
	s_nop 0
	v_mul_f32_e32 v36, 0xbfb8aa3b, v33
	v_exp_f32_e32 v36, v36
	s_nop 0
	v_add_f32_e32 v36, 1.0, v36
	v_rcp_f32_e32 v36, v36
	s_nop 0
	v_mul_f32_e32 v33, v33, v36
	v_mul_f32_e32 v36, v32, v33
	v_mov_b32_e32 v32, v34
	v_mov_b32_e32 v33, v38
	v_pk_mul_f32 v[32:33], v[32:33], v[138:139] op_sel_hi:[1,0]
	v_mov_b32_e32 v38, v35
	v_mul_f32_e32 v34, 0xbfb8aa3b, v33
	v_exp_f32_e32 v34, v34
	s_nop 0
	v_add_f32_e32 v34, 1.0, v34
	v_rcp_f32_e32 v34, v34
	s_nop 0
	v_mul_f32_e32 v33, v33, v34
	v_mul_f32_e32 v37, v32, v33
	v_pk_mul_f32 v[32:33], v[38:39], v[138:139] op_sel_hi:[1,0]
	s_nop 0
	v_mul_f32_e32 v34, 0xbfb8aa3b, v33
	v_exp_f32_e32 v34, v34
	s_nop 0
	v_add_f32_e32 v34, 1.0, v34
	v_rcp_f32_e32 v34, v34
	s_nop 0
	v_mul_f32_e32 v33, v33, v34
	v_mul_f32_e32 v35, v32, v33
	v_cvt_pk_bf16_f32 v32, v48, v44
	v_cvt_pk_bf16_f32 v33, v42, v43
	v_cvt_pk_bf16_f32 v34, v40, v36
	v_cvt_pk_bf16_f32 v35, v37, v35
	v_mad_i64_i32 v[36:37], s[4:5], v170, s31, v[114:115]
	v_lshl_add_u64 v[36:37], v[36:37], 0, v[116:117]
	global_store_dwordx4 v[36:37], v[32:35], off
	s_nop 1
	v_mov_b32_e32 v32, v24
	v_mov_b32_e32 v33, v28
	v_pk_mul_f32 v[32:33], v[32:33], v[132:133] op_sel_hi:[1,0]
	v_mov_b32_e32 v28, v25
	v_mul_f32_e32 v24, 0xbfb8aa3b, v33
	v_exp_f32_e32 v24, v24
	s_nop 0
	v_add_f32_e32 v24, 1.0, v24
	v_rcp_f32_e32 v24, v24
	s_nop 0
	v_mul_f32_e32 v24, v33, v24
	v_mul_f32_e32 v32, v32, v24
	v_pk_mul_f32 v[24:25], v[28:29], v[132:133] op_sel_hi:[1,0]
	s_nop 0
	v_mul_f32_e32 v28, 0xbfb8aa3b, v25
	v_exp_f32_e32 v28, v28
	s_nop 0
	v_add_f32_e32 v28, 1.0, v28
	v_rcp_f32_e32 v28, v28
	s_nop 0
	v_mul_f32_e32 v25, v25, v28
	v_mul_f32_e32 v28, v24, v25
	v_mov_b32_e32 v24, v26
	v_mov_b32_e32 v25, v30
	v_pk_mul_f32 v[24:25], v[24:25], v[132:133] op_sel_hi:[1,0]
	v_mov_b32_e32 v30, v27
	v_mul_f32_e32 v26, 0xbfb8aa3b, v25
	v_exp_f32_e32 v26, v26
	s_nop 0
	v_add_f32_e32 v26, 1.0, v26
	v_rcp_f32_e32 v26, v26
	s_nop 0
	v_mul_f32_e32 v25, v25, v26
	v_mul_f32_e32 v26, v24, v25
	v_pk_mul_f32 v[24:25], v[30:31], v[132:133] op_sel_hi:[1,0]
	s_nop 0
	v_mul_f32_e32 v27, 0xbfb8aa3b, v25
	v_exp_f32_e32 v27, v27
	s_nop 0
	v_add_f32_e32 v27, 1.0, v27
	v_rcp_f32_e32 v27, v27
	s_nop 0
	v_mul_f32_e32 v25, v25, v27
	v_mul_f32_e32 v27, v24, v25
	v_mov_b32_e32 v24, v16
	v_mov_b32_e32 v25, v20
	v_pk_mul_f32 v[24:25], v[24:25], v[132:133] op_sel_hi:[1,0]
	v_mov_b32_e32 v20, v17
	v_mul_f32_e32 v16, 0xbfb8aa3b, v25
	v_exp_f32_e32 v16, v16
	s_nop 0
	v_add_f32_e32 v16, 1.0, v16
	v_rcp_f32_e32 v16, v16
	s_nop 0
	v_mul_f32_e32 v16, v25, v16
	v_mul_f32_e32 v24, v24, v16
	v_pk_mul_f32 v[16:17], v[20:21], v[132:133] op_sel_hi:[1,0]
	s_nop 0
	v_mul_f32_e32 v20, 0xbfb8aa3b, v17
	v_exp_f32_e32 v20, v20
	s_nop 0
	v_add_f32_e32 v20, 1.0, v20
	v_rcp_f32_e32 v20, v20
	s_nop 0
	v_mul_f32_e32 v17, v17, v20
	v_mul_f32_e32 v20, v16, v17
	v_mov_b32_e32 v16, v18
	v_mov_b32_e32 v17, v22
	v_pk_mul_f32 v[16:17], v[16:17], v[132:133] op_sel_hi:[1,0]
	v_mov_b32_e32 v22, v19
	v_mul_f32_e32 v18, 0xbfb8aa3b, v17
	v_exp_f32_e32 v18, v18
	s_nop 0
	v_add_f32_e32 v18, 1.0, v18
	v_rcp_f32_e32 v18, v18
	s_nop 0
	v_mul_f32_e32 v17, v17, v18
	v_mul_f32_e32 v21, v16, v17
	v_pk_mul_f32 v[16:17], v[22:23], v[132:133] op_sel_hi:[1,0]
	s_nop 0
	v_mul_f32_e32 v18, 0xbfb8aa3b, v17
	v_exp_f32_e32 v18, v18
	s_nop 0
	v_add_f32_e32 v18, 1.0, v18
	v_rcp_f32_e32 v18, v18
	s_nop 0
	v_mul_f32_e32 v17, v17, v18
	v_mul_f32_e32 v19, v16, v17
	v_cvt_pk_bf16_f32 v16, v32, v28
	v_cvt_pk_bf16_f32 v17, v26, v27
	v_cvt_pk_bf16_f32 v18, v24, v20
	v_cvt_pk_bf16_f32 v19, v21, v19
	v_mad_i64_i32 v[20:21], s[4:5], v168, s31, v[114:115]
	v_lshl_add_u64 v[20:21], v[20:21], 0, v[116:117]
	global_store_dwordx4 v[20:21], v[16:19], off
	s_nop 1
	v_mov_b32_e32 v16, v8
	v_mov_b32_e32 v17, v12
	v_pk_mul_f32 v[16:17], v[16:17], v[130:131] op_sel_hi:[1,0]
	v_mov_b32_e32 v12, v9
	v_mul_f32_e32 v8, 0xbfb8aa3b, v17
	v_exp_f32_e32 v8, v8
	s_nop 0
	v_add_f32_e32 v8, 1.0, v8
	v_rcp_f32_e32 v8, v8
	s_nop 0
	v_mul_f32_e32 v8, v17, v8
	v_mul_f32_e32 v16, v16, v8
	v_pk_mul_f32 v[8:9], v[12:13], v[130:131] op_sel_hi:[1,0]
	s_nop 0
	v_mul_f32_e32 v12, 0xbfb8aa3b, v9
	v_exp_f32_e32 v12, v12
	s_nop 0
	v_add_f32_e32 v12, 1.0, v12
	v_rcp_f32_e32 v12, v12
	s_nop 0
	v_mul_f32_e32 v9, v9, v12
	v_mul_f32_e32 v12, v8, v9
	v_mov_b32_e32 v8, v10
	v_mov_b32_e32 v9, v14
	v_pk_mul_f32 v[8:9], v[8:9], v[130:131] op_sel_hi:[1,0]
	v_mov_b32_e32 v14, v11
	v_mul_f32_e32 v10, 0xbfb8aa3b, v9
	v_exp_f32_e32 v10, v10
	s_nop 0
	v_add_f32_e32 v10, 1.0, v10
	v_rcp_f32_e32 v10, v10
	s_nop 0
	v_mul_f32_e32 v9, v9, v10
	v_mul_f32_e32 v10, v8, v9
	v_pk_mul_f32 v[8:9], v[14:15], v[130:131] op_sel_hi:[1,0]
	s_nop 0
	v_mul_f32_e32 v11, 0xbfb8aa3b, v9
	v_exp_f32_e32 v11, v11
	s_nop 0
	v_add_f32_e32 v11, 1.0, v11
	v_rcp_f32_e32 v11, v11
	s_nop 0
	v_mul_f32_e32 v9, v9, v11
	v_mul_f32_e32 v11, v8, v9
	v_mov_b32_e32 v8, v0
	v_mov_b32_e32 v9, v4
	v_pk_mul_f32 v[8:9], v[8:9], v[130:131] op_sel_hi:[1,0]
	v_mov_b32_e32 v4, v1
	v_mul_f32_e32 v0, 0xbfb8aa3b, v9
	v_exp_f32_e32 v0, v0
	s_nop 0
	v_add_f32_e32 v0, 1.0, v0
	v_rcp_f32_e32 v0, v0
	s_nop 0
	v_mul_f32_e32 v0, v9, v0
	v_mul_f32_e32 v8, v8, v0
	v_pk_mul_f32 v[0:1], v[4:5], v[130:131] op_sel_hi:[1,0]
	s_nop 0
	v_mul_f32_e32 v4, 0xbfb8aa3b, v1
	v_exp_f32_e32 v4, v4
	s_nop 0
	v_add_f32_e32 v4, 1.0, v4
	v_rcp_f32_e32 v4, v4
	s_nop 0
	v_mul_f32_e32 v1, v1, v4
	v_mul_f32_e32 v4, v0, v1
	v_mov_b32_e32 v0, v2
	v_mov_b32_e32 v1, v6
	v_pk_mul_f32 v[0:1], v[0:1], v[130:131] op_sel_hi:[1,0]
	v_mov_b32_e32 v6, v3
	v_mul_f32_e32 v2, 0xbfb8aa3b, v1
	v_exp_f32_e32 v2, v2
	s_nop 0
	v_add_f32_e32 v2, 1.0, v2
	v_rcp_f32_e32 v2, v2
	s_nop 0
	v_mul_f32_e32 v1, v1, v2
	v_mul_f32_e32 v5, v0, v1
	v_pk_mul_f32 v[0:1], v[6:7], v[130:131] op_sel_hi:[1,0]
	s_nop 0
	v_mul_f32_e32 v2, 0xbfb8aa3b, v1
	v_exp_f32_e32 v2, v2
	s_nop 0
	v_add_f32_e32 v2, 1.0, v2
	v_rcp_f32_e32 v2, v2
	s_nop 0
	v_mul_f32_e32 v1, v1, v2
	v_mul_f32_e32 v3, v0, v1
	v_cvt_pk_bf16_f32 v0, v16, v12
	v_cvt_pk_bf16_f32 v1, v10, v11
	v_cvt_pk_bf16_f32 v2, v8, v4
	v_cvt_pk_bf16_f32 v3, v5, v3
	v_mad_i64_i32 v[4:5], s[4:5], v166, s31, v[114:115]
	v_lshl_add_u64 v[4:5], v[4:5], 0, v[116:117]
	s_mov_b64 s[4:5], -1
	global_store_dwordx4 v[4:5], v[0:3], off
	s_cbranch_vccnz .LBB0_940
	s_andn2_b64 vcc, exec, s[6:7]
	s_cbranch_vccnz .LBB0_939
	s_barrier
	s_branch .LBB0_939
